# K-loop back-edge rotation: counter/pointer updates and exit test moved ahead of the closing barrier of the loop body and of the peeled iteration
# baseline (speedup 1.0000x reference)
; #define PG8_STAGE(bufoff, gbase, voff) do { _Pragma("unroll") for (int _i = 0; _i < 2; ++_i) { \
;         const unsigned _m0 = ldsb + (unsigned)((bufoff) + _i * 8192); const char* _gb = (const char*)(gbase); \
;         asm volatile("s_mov_b32 m0, %0\n\ts_nop 0\n\tglobal_load_lds_dwordx4 %1, %2" :: "s"(_m0), "v"((voff)[_i]), "s"(_gb) : "m0", "memory"); } } while (0)
; #define PG8_LDA(dst, b, h) do { _Pragma("unroll") for (int m = 0; m < 4; ++m) _Pragma("unroll") for (int k = 0; k < 2; ++k) dst[m][k] = *(const LAS bf16x8*)(lds + PG8_SA(b, h) + aoff + m * 2048 + k * 1024); } while (0)
; #define PG8_LDB(dst, b, h) do { _Pragma("unroll") for (int n = 0; n < 2; ++n) _Pragma("unroll") for (int k = 0; k < 2; ++k) dst[n][k] = *(const LAS bf16x8*)(lds + PG8_SB(b, h) + boff + n * 2048 + k * 1024); } while (0)
; #define PG8_MMA(ai, bj, At, Bt) do { __builtin_amdgcn_s_setprio(1); _Pragma("unroll") for (int m = 0; m < 4; ++m) _Pragma("unroll") for (int n = 0; n < 2; ++n) _Pragma("unroll") for (int k = 0; k < 2; ++k) \
;         acc[ai][bj][m][n] = __builtin_amdgcn_mfma_f32_16x16x32_bf16(Bt[n][k], At[m][k], acc[ai][bj][m][n], 0, 0, 0); __builtin_amdgcn_s_setprio(0); } while (0)
; #define PG8_WAIT_V(n) asm volatile("s_waitcnt vmcnt(" #n ")" ::: "memory")
; #define PG8_WAIT_L(n) asm volatile("s_waitcnt lgkmcnt(" #n ")" ::: "memory")
; template <class Epi, bool ALIGN_EPI>
; __device__ __forceinline__ void gemm_phase(LAS unsigned char* lds, const Gemm g, const StaticOrder& S, const Epi& E) {
;     ...
;         for (int t = 0; t < nt; t += 2) {
;             const bool last = (t == nt - 2);
;             const char* a1 = cA + (size_t)(t + 1) * kstep;
;             const char* a2 = last ? nA : cA + (size_t)(t + 2) * kstep; const char* b2 = last ? nB : cB + (size_t)(t + 2) * kstep;
;             const char* a3 = a2 + kstep; const char* b3 = b2 + kstep;
;             PG8_LDB(B0, 0, 0); PG8_LDB(B1, 0, 1); PG8_SCHED; PG8_LDA(At, 0, 0); PG8_STAGE(PG8_SA(1, 1), a1 + hstepA, voffA);
;             PG8_WAIT_V(8); PG8_WAIT_L(0); PG8_BAR; PG8_MMA(0, 0, At, B0); PG8_MMA(0, 1, At, B1); PG8_BAR; PG8_SCHED;
;             PG8_LDA(At, 0, 1); PG8_STAGE(PG8_SB(0, 0), b2, voffB); PG8_STAGE(PG8_SB(0, 1), b2 + hstepB, voffB); PG8_STAGE(PG8_SA(0, 0), a2, voffA);
;             PG8_WAIT_V(8); PG8_WAIT_L(0); PG8_BAR; PG8_MMA(1, 0, At, B0); PG8_MMA(1, 1, At, B1); PG8_BAR; PG8_SCHED;
.LBB0_150:
	s_add_u32 s4, s48, 0x100
	s_addc_u32 s5, s49, 0
	s_add_u32 s37, s54, 0x100
	s_addc_u32 s44, s55, 0
	s_mov_b32 s45, 0
	s_waitcnt lgkmcnt(0)
	s_add_i32 s51, s45, 2
	s_cmp_eq_u32 s67, s45
	s_cselect_b32 s56, s0, s37
	s_cselect_b32 s57, s1, s44
	s_cselect_b32 s54, s94, s4
	s_cselect_b32 s55, s95, s5
	s_add_u32 s48, s56, 0x80
	s_addc_u32 s49, s57, 0
	s_add_u32 s45, s37, s15
	s_addc_u32 s59, s44, 0
	s_add_u32 s58, s45, 0xffffff80
	s_addc_u32 s59, s59, -1
	s_mov_b32 m0, s68
	s_nop 0
	global_load_lds_dwordx4 v0, s[58:59]
	s_nop 0
	s_mov_b32 m0, s85
	s_nop 0
	global_load_lds_dwordx4 v240, s[58:59]
	s_waitcnt vmcnt(8)
	s_waitcnt lgkmcnt(0)
	s_barrier
	s_setprio 1
	s_waitcnt lgkmcnt(0)
	v_mfma_f32_16x16x32_bf16 v[172:175], v[108:111], v[156:159], 0
	v_mfma_f32_16x16x32_bf16 v[172:175], v[120:123], v[160:163], v[172:175]
	v_mfma_f32_16x16x32_bf16 v[168:171], v[128:131], v[156:159], 0
	v_mfma_f32_16x16x32_bf16 v[168:171], v[132:135], v[160:163], v[168:171]
	v_mfma_f32_16x16x32_bf16 v[140:143], v[136:139], v[156:159], 0
	v_mfma_f32_16x16x32_bf16 v[140:143], v[144:147], v[160:163], v[140:143]
	v_mfma_f32_16x16x32_bf16 v[124:127], v[148:151], v[156:159], 0
	v_mfma_f32_16x16x32_bf16 v[124:127], v[152:155], v[160:163], v[124:127]
	v_mfma_f32_16x16x32_bf16 v[100:103], v[148:151], v[164:167], 0
	v_mfma_f32_16x16x32_bf16 v[100:103], v[152:155], v[176:179], v[100:103]
	v_mfma_f32_16x16x32_bf16 v[104:107], v[136:139], v[164:167], 0
	v_mfma_f32_16x16x32_bf16 v[104:107], v[144:147], v[176:179], v[104:107]
	v_mfma_f32_16x16x32_bf16 v[112:115], v[128:131], v[164:167], 0
	v_mfma_f32_16x16x32_bf16 v[112:115], v[132:135], v[176:179], v[112:115]
	v_mfma_f32_16x16x32_bf16 v[116:119], v[108:111], v[164:167], 0
	v_mfma_f32_16x16x32_bf16 v[116:119], v[120:123], v[176:179], v[116:119]
	v_mfma_f32_16x16x32_bf16 v[96:99], v[108:111], v[180:183], 0
	v_mfma_f32_16x16x32_bf16 v[96:99], v[120:123], v[184:187], v[96:99]
	v_mfma_f32_16x16x32_bf16 v[92:95], v[128:131], v[180:183], 0
	v_mfma_f32_16x16x32_bf16 v[92:95], v[132:135], v[184:187], v[92:95]
	v_mfma_f32_16x16x32_bf16 v[88:91], v[136:139], v[180:183], 0
	v_mfma_f32_16x16x32_bf16 v[88:91], v[144:147], v[184:187], v[88:91]
	v_mfma_f32_16x16x32_bf16 v[84:87], v[148:151], v[180:183], 0
	v_mfma_f32_16x16x32_bf16 v[84:87], v[152:155], v[184:187], v[84:87]
	v_mfma_f32_16x16x32_bf16 v[68:71], v[148:151], v[188:191], 0
	v_mfma_f32_16x16x32_bf16 v[68:71], v[152:155], v[202:205], v[68:71]
	v_mfma_f32_16x16x32_bf16 v[72:75], v[136:139], v[188:191], 0
	v_mfma_f32_16x16x32_bf16 v[72:75], v[144:147], v[202:205], v[72:75]
	v_mfma_f32_16x16x32_bf16 v[76:79], v[128:131], v[188:191], 0
	v_mfma_f32_16x16x32_bf16 v[76:79], v[132:135], v[202:205], v[76:79]
	v_mfma_f32_16x16x32_bf16 v[80:83], v[108:111], v[188:191], 0
	v_mfma_f32_16x16x32_bf16 v[80:83], v[120:123], v[202:205], v[80:83]
	s_setprio 0
	s_barrier
	ds_read_b128 v[156:159], v245 offset:16384
	ds_read_b128 v[160:163], v245 offset:17408
	ds_read_b128 v[164:167], v245 offset:18432
	ds_read_b128 v[176:179], v245 offset:19456
	ds_read_b128 v[180:183], v245 offset:20480
	ds_read_b128 v[184:187], v245 offset:21504
	ds_read_b128 v[188:191], v245 offset:22528
	ds_read_b128 v[202:205], v245 offset:23552
	s_mov_b32 m0, s27
	s_nop 0
	global_load_lds_dwordx4 v195, s[54:55]
	s_add_u32 s58, s54, s15
	s_mov_b32 m0, s28
	s_nop 0
	global_load_lds_dwordx4 v241, s[54:55]
	s_addc_u32 s59, s55, 0
	s_mov_b32 m0, s29
	s_nop 0
	global_load_lds_dwordx4 v195, s[58:59]
	s_nop 0
	s_mov_b32 m0, s30
	s_nop 0
	global_load_lds_dwordx4 v241, s[58:59]
	s_nop 0
	s_mov_b32 m0, s26
	s_nop 0
	global_load_lds_dwordx4 v0, s[56:57]
	s_nop 0
	s_mov_b32 m0, s31
	s_nop 0
	global_load_lds_dwordx4 v240, s[56:57]
	s_waitcnt vmcnt(8)
	s_waitcnt lgkmcnt(0)
	s_barrier
	s_setprio 1
	s_waitcnt lgkmcnt(0)
	v_mfma_f32_16x16x32_bf16 v[64:67], v[108:111], v[156:159], 0
	v_mfma_f32_16x16x32_bf16 v[64:67], v[120:123], v[160:163], v[64:67]
	v_mfma_f32_16x16x32_bf16 v[60:63], v[128:131], v[156:159], 0
	v_mfma_f32_16x16x32_bf16 v[60:63], v[132:135], v[160:163], v[60:63]
	v_mfma_f32_16x16x32_bf16 v[56:59], v[136:139], v[156:159], 0
	v_mfma_f32_16x16x32_bf16 v[56:59], v[144:147], v[160:163], v[56:59]
	v_mfma_f32_16x16x32_bf16 v[52:55], v[148:151], v[156:159], 0
	v_mfma_f32_16x16x32_bf16 v[52:55], v[152:155], v[160:163], v[52:55]
	v_mfma_f32_16x16x32_bf16 v[36:39], v[148:151], v[164:167], 0
	v_mfma_f32_16x16x32_bf16 v[36:39], v[152:155], v[176:179], v[36:39]
	v_mfma_f32_16x16x32_bf16 v[40:43], v[136:139], v[164:167], 0
	v_mfma_f32_16x16x32_bf16 v[40:43], v[144:147], v[176:179], v[40:43]
	v_mfma_f32_16x16x32_bf16 v[44:47], v[128:131], v[164:167], 0
	v_mfma_f32_16x16x32_bf16 v[44:47], v[132:135], v[176:179], v[44:47]
	v_mfma_f32_16x16x32_bf16 v[48:51], v[108:111], v[164:167], 0
	v_mfma_f32_16x16x32_bf16 v[48:51], v[120:123], v[176:179], v[48:51]
	v_mfma_f32_16x16x32_bf16 v[32:35], v[108:111], v[180:183], 0
	v_mfma_f32_16x16x32_bf16 v[32:35], v[120:123], v[184:187], v[32:35]
	v_mfma_f32_16x16x32_bf16 v[28:31], v[128:131], v[180:183], 0
	v_mfma_f32_16x16x32_bf16 v[28:31], v[132:135], v[184:187], v[28:31]
	v_mfma_f32_16x16x32_bf16 v[24:27], v[136:139], v[180:183], 0
	v_mfma_f32_16x16x32_bf16 v[24:27], v[144:147], v[184:187], v[24:27]
	v_mfma_f32_16x16x32_bf16 v[20:23], v[148:151], v[180:183], 0
	v_mfma_f32_16x16x32_bf16 v[20:23], v[152:155], v[184:187], v[20:23]
	v_mfma_f32_16x16x32_bf16 v[4:7], v[148:151], v[188:191], 0
	v_mfma_f32_16x16x32_bf16 v[4:7], v[152:155], v[202:205], v[4:7]
	v_mfma_f32_16x16x32_bf16 v[8:11], v[136:139], v[188:191], 0
	v_mfma_f32_16x16x32_bf16 v[8:11], v[144:147], v[202:205], v[8:11]
	v_mfma_f32_16x16x32_bf16 v[12:15], v[128:131], v[188:191], 0
	v_mfma_f32_16x16x32_bf16 v[12:15], v[132:135], v[202:205], v[12:15]
	v_mfma_f32_16x16x32_bf16 v[16:19], v[108:111], v[188:191], 0
	v_mfma_f32_16x16x32_bf16 v[16:19], v[120:123], v[202:205], v[16:19]
	s_setprio 0
	s_barrier
; #define PG8_STAGE(bufoff, gbase, voff) do { _Pragma("unroll") for (int _i = 0; _i < 2; ++_i) { \
;         const unsigned _m0 = ldsb + (unsigned)((bufoff) + _i * 8192); const char* _gb = (const char*)(gbase); \
;         asm volatile("s_mov_b32 m0, %0\n\ts_nop 0\n\tglobal_load_lds_dwordx4 %1, %2" :: "s"(_m0), "v"((voff)[_i]), "s"(_gb) : "m0", "memory"); } } while (0)
; #define PG8_LDA(dst, b, h) do { _Pragma("unroll") for (int m = 0; m < 4; ++m) _Pragma("unroll") for (int k = 0; k < 2; ++k) dst[m][k] = *(const LAS bf16x8*)(lds + PG8_SA(b, h) + aoff + m * 2048 + k * 1024); } while (0)
; #define PG8_LDB(dst, b, h) do { _Pragma("unroll") for (int n = 0; n < 2; ++n) _Pragma("unroll") for (int k = 0; k < 2; ++k) dst[n][k] = *(const LAS bf16x8*)(lds + PG8_SB(b, h) + boff + n * 2048 + k * 1024); } while (0)
; #define PG8_MMA(ai, bj, At, Bt) do { __builtin_amdgcn_s_setprio(1); _Pragma("unroll") for (int m = 0; m < 4; ++m) _Pragma("unroll") for (int n = 0; n < 2; ++n) _Pragma("unroll") for (int k = 0; k < 2; ++k) \
;         acc[ai][bj][m][n] = __builtin_amdgcn_mfma_f32_16x16x32_bf16(Bt[n][k], At[m][k], acc[ai][bj][m][n], 0, 0, 0); __builtin_amdgcn_s_setprio(0); } while (0)
; #define PG8_WAIT_V(n) asm volatile("s_waitcnt vmcnt(" #n ")" ::: "memory")
; #define PG8_WAIT_L(n) asm volatile("s_waitcnt lgkmcnt(" #n ")" ::: "memory")
; #define PG8_BAR __builtin_amdgcn_s_barrier()
; #define PG8_SCHED __builtin_amdgcn_sched_barrier(0)
; template <class Epi, bool ALIGN_EPI>
; __device__ __forceinline__ void gemm_phase(LAS unsigned char* lds, const Gemm g, const StaticOrder& S, const Epi& E) {
;     ...
;             PG8_LDB(B0, 1, 0); PG8_LDB(B1, 1, 1); PG8_SCHED; PG8_LDA(At, 1, 0); PG8_STAGE(PG8_SA(0, 1), a2 + hstepA, voffA);
;             PG8_WAIT_V(8); PG8_WAIT_L(0); PG8_BAR; PG8_MMA(0, 0, At, B0); PG8_MMA(0, 1, At, B1); PG8_BAR; PG8_SCHED;
;             PG8_LDA(At, 1, 1); PG8_STAGE(PG8_SB(1, 0), b3, voffB); PG8_STAGE(PG8_SB(1, 1), b3 + hstepB, voffB); PG8_STAGE(PG8_SA(1, 0), a3, voffA);
;             PG8_WAIT_V(8); PG8_WAIT_L(0); PG8_BAR; PG8_MMA(1, 0, At, B0); PG8_MMA(1, 1, At, B1); PG8_BAR; PG8_SCHED;
;         }
	v_add_u32_e32 v132, 0x18000, v244
	v_add_u32_e32 v152, 0x1c000, v244
	ds_read_b128 v[108:111], v132
	ds_read_b128 v[120:123], v132 offset:1024
	ds_read_b128 v[128:131], v132 offset:2048
	ds_read_b128 v[132:135], v132 offset:3072
	ds_read_b128 v[136:139], v152
	ds_read_b128 v[144:147], v152 offset:1024
	ds_read_b128 v[148:151], v152 offset:2048
	ds_read_b128 v[152:155], v152 offset:3072
	ds_read_b128 v[156:159], v245 offset:32768
	ds_read_b128 v[160:163], v245 offset:33792
	ds_read_b128 v[164:167], v245 offset:34816
	ds_read_b128 v[176:179], v245 offset:35840
	ds_read_b128 v[180:183], v245 offset:36864
	ds_read_b128 v[184:187], v245 offset:37888
	ds_read_b128 v[188:191], v245 offset:38912
	ds_read_b128 v[202:205], v245 offset:39936
	s_add_u32 s56, s56, s15
	s_addc_u32 s57, s57, 0
	s_mov_b32 m0, s41
	s_nop 0
	global_load_lds_dwordx4 v0, s[56:57]
	s_nop 0
	s_mov_b32 m0, s42
	s_nop 0
	global_load_lds_dwordx4 v240, s[56:57]
	s_waitcnt vmcnt(8)
	s_waitcnt lgkmcnt(0)
	s_barrier
	s_setprio 1
	s_waitcnt lgkmcnt(0)
	v_mfma_f32_16x16x32_bf16 v[172:175], v[108:111], v[156:159], v[172:175]
	v_mfma_f32_16x16x32_bf16 v[172:175], v[120:123], v[160:163], v[172:175]
	v_mfma_f32_16x16x32_bf16 v[168:171], v[128:131], v[156:159], v[168:171]
	v_mfma_f32_16x16x32_bf16 v[168:171], v[132:135], v[160:163], v[168:171]
	v_mfma_f32_16x16x32_bf16 v[140:143], v[136:139], v[156:159], v[140:143]
	v_mfma_f32_16x16x32_bf16 v[140:143], v[144:147], v[160:163], v[140:143]
	v_mfma_f32_16x16x32_bf16 v[124:127], v[148:151], v[156:159], v[124:127]
	v_mfma_f32_16x16x32_bf16 v[124:127], v[152:155], v[160:163], v[124:127]
	v_mfma_f32_16x16x32_bf16 v[100:103], v[148:151], v[164:167], v[100:103]
	v_mfma_f32_16x16x32_bf16 v[100:103], v[152:155], v[176:179], v[100:103]
	v_mfma_f32_16x16x32_bf16 v[104:107], v[136:139], v[164:167], v[104:107]
	v_mfma_f32_16x16x32_bf16 v[104:107], v[144:147], v[176:179], v[104:107]
	v_mfma_f32_16x16x32_bf16 v[112:115], v[128:131], v[164:167], v[112:115]
	v_mfma_f32_16x16x32_bf16 v[112:115], v[132:135], v[176:179], v[112:115]
	v_mfma_f32_16x16x32_bf16 v[116:119], v[108:111], v[164:167], v[116:119]
	v_mfma_f32_16x16x32_bf16 v[116:119], v[120:123], v[176:179], v[116:119]
	v_mfma_f32_16x16x32_bf16 v[96:99], v[108:111], v[180:183], v[96:99]
	v_mfma_f32_16x16x32_bf16 v[96:99], v[120:123], v[184:187], v[96:99]
	v_mfma_f32_16x16x32_bf16 v[92:95], v[128:131], v[180:183], v[92:95]
	v_mfma_f32_16x16x32_bf16 v[92:95], v[132:135], v[184:187], v[92:95]
	v_mfma_f32_16x16x32_bf16 v[88:91], v[136:139], v[180:183], v[88:91]
	v_mfma_f32_16x16x32_bf16 v[88:91], v[144:147], v[184:187], v[88:91]
	v_mfma_f32_16x16x32_bf16 v[84:87], v[148:151], v[180:183], v[84:87]
	v_mfma_f32_16x16x32_bf16 v[84:87], v[152:155], v[184:187], v[84:87]
	v_mfma_f32_16x16x32_bf16 v[68:71], v[148:151], v[188:191], v[68:71]
	v_mfma_f32_16x16x32_bf16 v[68:71], v[152:155], v[202:205], v[68:71]
	v_mfma_f32_16x16x32_bf16 v[72:75], v[136:139], v[188:191], v[72:75]
	v_mfma_f32_16x16x32_bf16 v[72:75], v[144:147], v[202:205], v[72:75]
	v_mfma_f32_16x16x32_bf16 v[76:79], v[128:131], v[188:191], v[76:79]
	v_mfma_f32_16x16x32_bf16 v[76:79], v[132:135], v[202:205], v[76:79]
	v_mfma_f32_16x16x32_bf16 v[80:83], v[108:111], v[188:191], v[80:83]
	v_mfma_f32_16x16x32_bf16 v[80:83], v[120:123], v[202:205], v[80:83]
	s_setprio 0
	s_barrier
	ds_read_b128 v[156:159], v245 offset:49152
	ds_read_b128 v[160:163], v245 offset:50176
	ds_read_b128 v[164:167], v245 offset:51200
	ds_read_b128 v[176:179], v245 offset:52224
	ds_read_b128 v[180:183], v245 offset:53248
	ds_read_b128 v[184:187], v245 offset:54272
	ds_read_b128 v[188:191], v245 offset:55296
	ds_read_b128 v[202:205], v245 offset:56320
	s_add_u32 s54, s54, 0x80
	s_addc_u32 s55, s55, 0
	s_mov_b32 m0, s46
	s_nop 0
	global_load_lds_dwordx4 v195, s[54:55]
	s_nop 0
	s_mov_b32 m0, s50
	s_nop 0
	global_load_lds_dwordx4 v241, s[54:55]
	s_add_u32 s54, s58, 0x80
	s_addc_u32 s55, s59, 0
	s_mov_b32 m0, s61
	s_nop 0
	global_load_lds_dwordx4 v195, s[54:55]
	s_nop 0
	s_mov_b32 m0, s65
	s_nop 0
	global_load_lds_dwordx4 v241, s[54:55]
	s_nop 0
	s_mov_b32 m0, s53
	s_nop 0
	global_load_lds_dwordx4 v0, s[48:49]
	s_nop 0
	s_mov_b32 m0, s60
	s_nop 0
	global_load_lds_dwordx4 v240, s[48:49]
	s_waitcnt vmcnt(8)
	s_waitcnt lgkmcnt(0)
	s_barrier
	s_setprio 1
	s_waitcnt lgkmcnt(0)
	v_mfma_f32_16x16x32_bf16 v[64:67], v[108:111], v[156:159], v[64:67]
	v_mfma_f32_16x16x32_bf16 v[64:67], v[120:123], v[160:163], v[64:67]
	v_mfma_f32_16x16x32_bf16 v[60:63], v[128:131], v[156:159], v[60:63]
	v_mfma_f32_16x16x32_bf16 v[60:63], v[132:135], v[160:163], v[60:63]
	v_mfma_f32_16x16x32_bf16 v[56:59], v[136:139], v[156:159], v[56:59]
	v_mfma_f32_16x16x32_bf16 v[56:59], v[144:147], v[160:163], v[56:59]
	v_mfma_f32_16x16x32_bf16 v[52:55], v[148:151], v[156:159], v[52:55]
	v_mfma_f32_16x16x32_bf16 v[52:55], v[152:155], v[160:163], v[52:55]
	v_mfma_f32_16x16x32_bf16 v[36:39], v[148:151], v[164:167], v[36:39]
	v_mfma_f32_16x16x32_bf16 v[36:39], v[152:155], v[176:179], v[36:39]
	v_mfma_f32_16x16x32_bf16 v[40:43], v[136:139], v[164:167], v[40:43]
	v_mfma_f32_16x16x32_bf16 v[40:43], v[144:147], v[176:179], v[40:43]
	v_mfma_f32_16x16x32_bf16 v[44:47], v[128:131], v[164:167], v[44:47]
	v_mfma_f32_16x16x32_bf16 v[44:47], v[132:135], v[176:179], v[44:47]
	v_mfma_f32_16x16x32_bf16 v[48:51], v[108:111], v[164:167], v[48:51]
	v_mfma_f32_16x16x32_bf16 v[48:51], v[120:123], v[176:179], v[48:51]
	v_mfma_f32_16x16x32_bf16 v[32:35], v[108:111], v[180:183], v[32:35]
	v_mfma_f32_16x16x32_bf16 v[32:35], v[120:123], v[184:187], v[32:35]
	v_mfma_f32_16x16x32_bf16 v[28:31], v[128:131], v[180:183], v[28:31]
	v_mfma_f32_16x16x32_bf16 v[28:31], v[132:135], v[184:187], v[28:31]
	v_mfma_f32_16x16x32_bf16 v[24:27], v[136:139], v[180:183], v[24:27]
	v_mfma_f32_16x16x32_bf16 v[24:27], v[144:147], v[184:187], v[24:27]
	v_mfma_f32_16x16x32_bf16 v[20:23], v[148:151], v[180:183], v[20:23]
	v_mfma_f32_16x16x32_bf16 v[20:23], v[152:155], v[184:187], v[20:23]
	v_mfma_f32_16x16x32_bf16 v[4:7], v[148:151], v[188:191], v[4:7]
	v_mfma_f32_16x16x32_bf16 v[4:7], v[152:155], v[202:205], v[4:7]
	v_mfma_f32_16x16x32_bf16 v[8:11], v[136:139], v[188:191], v[8:11]
	v_mfma_f32_16x16x32_bf16 v[8:11], v[144:147], v[202:205], v[8:11]
	v_mfma_f32_16x16x32_bf16 v[12:15], v[128:131], v[188:191], v[12:15]
	v_mfma_f32_16x16x32_bf16 v[12:15], v[132:135], v[202:205], v[12:15]
	v_mfma_f32_16x16x32_bf16 v[16:19], v[108:111], v[188:191], v[16:19]
	v_mfma_f32_16x16x32_bf16 v[16:19], v[120:123], v[202:205], v[16:19]
	s_setprio 0
	s_add_u32 s4, s4, 0x100
	s_addc_u32 s5, s5, 0
	s_add_u32 s37, s37, 0x100
	s_addc_u32 s44, s44, 0
	s_cmp_ge_u32 s51, s43
	s_mov_b32 s45, s51
	s_barrier
; #define PG8_STAGE(bufoff, gbase, voff) do { _Pragma("unroll") for (int _i = 0; _i < 2; ++_i) { \
;         const unsigned _m0 = ldsb + (unsigned)((bufoff) + _i * 8192); const char* _gb = (const char*)(gbase); \
;         asm volatile("s_mov_b32 m0, %0\n\ts_nop 0\n\tglobal_load_lds_dwordx4 %1, %2" :: "s"(_m0), "v"((voff)[_i]), "s"(_gb) : "m0", "memory"); } } while (0)
; #define PG8_LDA(dst, b, h) do { _Pragma("unroll") for (int m = 0; m < 4; ++m) _Pragma("unroll") for (int k = 0; k < 2; ++k) dst[m][k] = *(const LAS bf16x8*)(lds + PG8_SA(b, h) + aoff + m * 2048 + k * 1024); } while (0)
; #define PG8_LDB(dst, b, h) do { _Pragma("unroll") for (int n = 0; n < 2; ++n) _Pragma("unroll") for (int k = 0; k < 2; ++k) dst[n][k] = *(const LAS bf16x8*)(lds + PG8_SB(b, h) + boff + n * 2048 + k * 1024); } while (0)
; #define PG8_MMA(ai, bj, At, Bt) do { __builtin_amdgcn_s_setprio(1); _Pragma("unroll") for (int m = 0; m < 4; ++m) _Pragma("unroll") for (int n = 0; n < 2; ++n) _Pragma("unroll") for (int k = 0; k < 2; ++k) \
;         acc[ai][bj][m][n] = __builtin_amdgcn_mfma_f32_16x16x32_bf16(Bt[n][k], At[m][k], acc[ai][bj][m][n], 0, 0, 0); __builtin_amdgcn_s_setprio(0); } while (0)
; #define PG8_WAIT_V(n) asm volatile("s_waitcnt vmcnt(" #n ")" ::: "memory")
; #define PG8_WAIT_L(n) asm volatile("s_waitcnt lgkmcnt(" #n ")" ::: "memory")
; template <class Epi, bool ALIGN_EPI>
; __device__ __forceinline__ void gemm_phase(LAS unsigned char* lds, const Gemm g, const StaticOrder& S, const Epi& E) {
;     ...
;         for (int t = 0; t < nt; t += 2) {
;             const bool last = (t == nt - 2);
;             const char* a1 = cA + (size_t)(t + 1) * kstep;
;             const char* a2 = last ? nA : cA + (size_t)(t + 2) * kstep; const char* b2 = last ? nB : cB + (size_t)(t + 2) * kstep;
;             const char* a3 = a2 + kstep; const char* b3 = b2 + kstep;
;             PG8_LDB(B0, 0, 0); PG8_LDB(B1, 0, 1); PG8_SCHED; PG8_LDA(At, 0, 0); PG8_STAGE(PG8_SA(1, 1), a1 + hstepA, voffA);
;             PG8_WAIT_V(8); PG8_WAIT_L(0); PG8_BAR; PG8_MMA(0, 0, At, B0); PG8_MMA(0, 1, At, B1); PG8_BAR; PG8_SCHED;
;             PG8_LDA(At, 0, 1); PG8_STAGE(PG8_SB(0, 0), b2, voffB); PG8_STAGE(PG8_SB(0, 1), b2 + hstepB, voffB); PG8_STAGE(PG8_SA(0, 0), a2, voffA);
;             PG8_WAIT_V(8); PG8_WAIT_L(0); PG8_BAR; PG8_MMA(1, 0, At, B0); PG8_MMA(1, 1, At, B1); PG8_BAR; PG8_SCHED;
.LBB0_151:
	v_add_u32_e32 v132, 0x10000, v244
	v_add_u32_e32 v152, 0x14000, v244
	ds_read_b128 v[108:111], v132
	ds_read_b128 v[120:123], v132 offset:1024
	ds_read_b128 v[128:131], v132 offset:2048
	ds_read_b128 v[132:135], v132 offset:3072
	ds_read_b128 v[136:139], v152
	ds_read_b128 v[144:147], v152 offset:1024
	ds_read_b128 v[148:151], v152 offset:2048
	ds_read_b128 v[152:155], v152 offset:3072
	s_add_i32 s51, s45, 2
	s_cmp_eq_u32 s67, s45
	s_cselect_b32 s56, s0, s37
	s_cselect_b32 s57, s1, s44
	s_cselect_b32 s54, s94, s4
	s_cselect_b32 s55, s95, s5
	s_add_u32 s48, s56, 0x80
	s_addc_u32 s49, s57, 0
	ds_read_b128 v[156:159], v245
	ds_read_b128 v[160:163], v245 offset:1024
	ds_read_b128 v[164:167], v245 offset:2048
	ds_read_b128 v[176:179], v245 offset:3072
	ds_read_b128 v[180:183], v245 offset:4096
	ds_read_b128 v[184:187], v245 offset:5120
	ds_read_b128 v[188:191], v245 offset:6144
	ds_read_b128 v[202:205], v245 offset:7168
	s_add_u32 s45, s37, s15
	s_addc_u32 s59, s44, 0
	s_add_u32 s58, s45, 0xffffff80
	s_addc_u32 s59, s59, -1
	s_mov_b32 m0, s68
	s_nop 0
	global_load_lds_dwordx4 v0, s[58:59]
	s_nop 0
	s_mov_b32 m0, s85
	s_nop 0
	global_load_lds_dwordx4 v240, s[58:59]
	s_waitcnt vmcnt(8)
	s_waitcnt lgkmcnt(0)
	s_barrier
	s_setprio 1
	s_waitcnt lgkmcnt(0)
	v_mfma_f32_16x16x32_bf16 v[172:175], v[108:111], v[156:159], v[172:175]
	v_mfma_f32_16x16x32_bf16 v[172:175], v[120:123], v[160:163], v[172:175]
	v_mfma_f32_16x16x32_bf16 v[168:171], v[128:131], v[156:159], v[168:171]
	v_mfma_f32_16x16x32_bf16 v[168:171], v[132:135], v[160:163], v[168:171]
	v_mfma_f32_16x16x32_bf16 v[140:143], v[136:139], v[156:159], v[140:143]
	v_mfma_f32_16x16x32_bf16 v[140:143], v[144:147], v[160:163], v[140:143]
	v_mfma_f32_16x16x32_bf16 v[124:127], v[148:151], v[156:159], v[124:127]
	v_mfma_f32_16x16x32_bf16 v[124:127], v[152:155], v[160:163], v[124:127]
	v_mfma_f32_16x16x32_bf16 v[100:103], v[148:151], v[164:167], v[100:103]
	v_mfma_f32_16x16x32_bf16 v[100:103], v[152:155], v[176:179], v[100:103]
	v_mfma_f32_16x16x32_bf16 v[104:107], v[136:139], v[164:167], v[104:107]
	v_mfma_f32_16x16x32_bf16 v[104:107], v[144:147], v[176:179], v[104:107]
	v_mfma_f32_16x16x32_bf16 v[112:115], v[128:131], v[164:167], v[112:115]
	v_mfma_f32_16x16x32_bf16 v[112:115], v[132:135], v[176:179], v[112:115]
	v_mfma_f32_16x16x32_bf16 v[116:119], v[108:111], v[164:167], v[116:119]
	v_mfma_f32_16x16x32_bf16 v[116:119], v[120:123], v[176:179], v[116:119]
	v_mfma_f32_16x16x32_bf16 v[96:99], v[108:111], v[180:183], v[96:99]
	v_mfma_f32_16x16x32_bf16 v[96:99], v[120:123], v[184:187], v[96:99]
	v_mfma_f32_16x16x32_bf16 v[92:95], v[128:131], v[180:183], v[92:95]
	v_mfma_f32_16x16x32_bf16 v[92:95], v[132:135], v[184:187], v[92:95]
	v_mfma_f32_16x16x32_bf16 v[88:91], v[136:139], v[180:183], v[88:91]
	v_mfma_f32_16x16x32_bf16 v[88:91], v[144:147], v[184:187], v[88:91]
	v_mfma_f32_16x16x32_bf16 v[84:87], v[148:151], v[180:183], v[84:87]
	v_mfma_f32_16x16x32_bf16 v[84:87], v[152:155], v[184:187], v[84:87]
	v_mfma_f32_16x16x32_bf16 v[68:71], v[148:151], v[188:191], v[68:71]
	v_mfma_f32_16x16x32_bf16 v[68:71], v[152:155], v[202:205], v[68:71]
	v_mfma_f32_16x16x32_bf16 v[72:75], v[136:139], v[188:191], v[72:75]
	v_mfma_f32_16x16x32_bf16 v[72:75], v[144:147], v[202:205], v[72:75]
	v_mfma_f32_16x16x32_bf16 v[76:79], v[128:131], v[188:191], v[76:79]
	v_mfma_f32_16x16x32_bf16 v[76:79], v[132:135], v[202:205], v[76:79]
	v_mfma_f32_16x16x32_bf16 v[80:83], v[108:111], v[188:191], v[80:83]
	v_mfma_f32_16x16x32_bf16 v[80:83], v[120:123], v[202:205], v[80:83]
	s_setprio 0
	s_barrier
	ds_read_b128 v[156:159], v245 offset:16384
	ds_read_b128 v[160:163], v245 offset:17408
	ds_read_b128 v[164:167], v245 offset:18432
	ds_read_b128 v[176:179], v245 offset:19456
	ds_read_b128 v[180:183], v245 offset:20480
	ds_read_b128 v[184:187], v245 offset:21504
	ds_read_b128 v[188:191], v245 offset:22528
	ds_read_b128 v[202:205], v245 offset:23552
	s_mov_b32 m0, s27
	s_nop 0
	global_load_lds_dwordx4 v195, s[54:55]
	s_add_u32 s58, s54, s15
	s_mov_b32 m0, s28
	s_nop 0
	global_load_lds_dwordx4 v241, s[54:55]
	s_addc_u32 s59, s55, 0
	s_mov_b32 m0, s29
	s_nop 0
	global_load_lds_dwordx4 v195, s[58:59]
	s_nop 0
	s_mov_b32 m0, s30
	s_nop 0
	global_load_lds_dwordx4 v241, s[58:59]
	s_nop 0
	s_mov_b32 m0, s26
	s_nop 0
	global_load_lds_dwordx4 v0, s[56:57]
	s_nop 0
	s_mov_b32 m0, s31
	s_nop 0
	global_load_lds_dwordx4 v240, s[56:57]
	s_waitcnt vmcnt(8)
	s_waitcnt lgkmcnt(0)
	s_barrier
	s_setprio 1
	s_waitcnt lgkmcnt(0)
	v_mfma_f32_16x16x32_bf16 v[64:67], v[108:111], v[156:159], v[64:67]
	v_mfma_f32_16x16x32_bf16 v[64:67], v[120:123], v[160:163], v[64:67]
	v_mfma_f32_16x16x32_bf16 v[60:63], v[128:131], v[156:159], v[60:63]
	v_mfma_f32_16x16x32_bf16 v[60:63], v[132:135], v[160:163], v[60:63]
	v_mfma_f32_16x16x32_bf16 v[56:59], v[136:139], v[156:159], v[56:59]
	v_mfma_f32_16x16x32_bf16 v[56:59], v[144:147], v[160:163], v[56:59]
	v_mfma_f32_16x16x32_bf16 v[52:55], v[148:151], v[156:159], v[52:55]
	v_mfma_f32_16x16x32_bf16 v[52:55], v[152:155], v[160:163], v[52:55]
	v_mfma_f32_16x16x32_bf16 v[36:39], v[148:151], v[164:167], v[36:39]
	v_mfma_f32_16x16x32_bf16 v[36:39], v[152:155], v[176:179], v[36:39]
	v_mfma_f32_16x16x32_bf16 v[40:43], v[136:139], v[164:167], v[40:43]
	v_mfma_f32_16x16x32_bf16 v[40:43], v[144:147], v[176:179], v[40:43]
	v_mfma_f32_16x16x32_bf16 v[44:47], v[128:131], v[164:167], v[44:47]
	v_mfma_f32_16x16x32_bf16 v[44:47], v[132:135], v[176:179], v[44:47]
	v_mfma_f32_16x16x32_bf16 v[48:51], v[108:111], v[164:167], v[48:51]
	v_mfma_f32_16x16x32_bf16 v[48:51], v[120:123], v[176:179], v[48:51]
	v_mfma_f32_16x16x32_bf16 v[32:35], v[108:111], v[180:183], v[32:35]
	v_mfma_f32_16x16x32_bf16 v[32:35], v[120:123], v[184:187], v[32:35]
	v_mfma_f32_16x16x32_bf16 v[28:31], v[128:131], v[180:183], v[28:31]
	v_mfma_f32_16x16x32_bf16 v[28:31], v[132:135], v[184:187], v[28:31]
	v_mfma_f32_16x16x32_bf16 v[24:27], v[136:139], v[180:183], v[24:27]
	v_mfma_f32_16x16x32_bf16 v[24:27], v[144:147], v[184:187], v[24:27]
	v_mfma_f32_16x16x32_bf16 v[20:23], v[148:151], v[180:183], v[20:23]
	v_mfma_f32_16x16x32_bf16 v[20:23], v[152:155], v[184:187], v[20:23]
	v_mfma_f32_16x16x32_bf16 v[4:7], v[148:151], v[188:191], v[4:7]
	v_mfma_f32_16x16x32_bf16 v[4:7], v[152:155], v[202:205], v[4:7]
	v_mfma_f32_16x16x32_bf16 v[8:11], v[136:139], v[188:191], v[8:11]
	v_mfma_f32_16x16x32_bf16 v[8:11], v[144:147], v[202:205], v[8:11]
	v_mfma_f32_16x16x32_bf16 v[12:15], v[128:131], v[188:191], v[12:15]
	v_mfma_f32_16x16x32_bf16 v[12:15], v[132:135], v[202:205], v[12:15]
	v_mfma_f32_16x16x32_bf16 v[16:19], v[108:111], v[188:191], v[16:19]
	v_mfma_f32_16x16x32_bf16 v[16:19], v[120:123], v[202:205], v[16:19]
	s_setprio 0
	s_barrier
; #define PG8_STAGE(bufoff, gbase, voff) do { _Pragma("unroll") for (int _i = 0; _i < 2; ++_i) { \
;         const unsigned _m0 = ldsb + (unsigned)((bufoff) + _i * 8192); const char* _gb = (const char*)(gbase); \
;         asm volatile("s_mov_b32 m0, %0\n\ts_nop 0\n\tglobal_load_lds_dwordx4 %1, %2" :: "s"(_m0), "v"((voff)[_i]), "s"(_gb) : "m0", "memory"); } } while (0)
; #define PG8_LDA(dst, b, h) do { _Pragma("unroll") for (int m = 0; m < 4; ++m) _Pragma("unroll") for (int k = 0; k < 2; ++k) dst[m][k] = *(const LAS bf16x8*)(lds + PG8_SA(b, h) + aoff + m * 2048 + k * 1024); } while (0)
; #define PG8_LDB(dst, b, h) do { _Pragma("unroll") for (int n = 0; n < 2; ++n) _Pragma("unroll") for (int k = 0; k < 2; ++k) dst[n][k] = *(const LAS bf16x8*)(lds + PG8_SB(b, h) + boff + n * 2048 + k * 1024); } while (0)
; #define PG8_MMA(ai, bj, At, Bt) do { __builtin_amdgcn_s_setprio(1); _Pragma("unroll") for (int m = 0; m < 4; ++m) _Pragma("unroll") for (int n = 0; n < 2; ++n) _Pragma("unroll") for (int k = 0; k < 2; ++k) \
;         acc[ai][bj][m][n] = __builtin_amdgcn_mfma_f32_16x16x32_bf16(Bt[n][k], At[m][k], acc[ai][bj][m][n], 0, 0, 0); __builtin_amdgcn_s_setprio(0); } while (0)
; #define PG8_WAIT_V(n) asm volatile("s_waitcnt vmcnt(" #n ")" ::: "memory")
; #define PG8_WAIT_L(n) asm volatile("s_waitcnt lgkmcnt(" #n ")" ::: "memory")
; #define PG8_BAR __builtin_amdgcn_s_barrier()
; #define PG8_SCHED __builtin_amdgcn_sched_barrier(0)
; template <class Epi, bool ALIGN_EPI>
; __device__ __forceinline__ void gemm_phase(LAS unsigned char* lds, const Gemm g, const StaticOrder& S, const Epi& E) {
;     ...
;             PG8_LDB(B0, 1, 0); PG8_LDB(B1, 1, 1); PG8_SCHED; PG8_LDA(At, 1, 0); PG8_STAGE(PG8_SA(0, 1), a2 + hstepA, voffA);
;             PG8_WAIT_V(8); PG8_WAIT_L(0); PG8_BAR; PG8_MMA(0, 0, At, B0); PG8_MMA(0, 1, At, B1); PG8_BAR; PG8_SCHED;
;             PG8_LDA(At, 1, 1); PG8_STAGE(PG8_SB(1, 0), b3, voffB); PG8_STAGE(PG8_SB(1, 1), b3 + hstepB, voffB); PG8_STAGE(PG8_SA(1, 0), a3, voffA);
;             PG8_WAIT_V(8); PG8_WAIT_L(0); PG8_BAR; PG8_MMA(1, 0, At, B0); PG8_MMA(1, 1, At, B1); PG8_BAR; PG8_SCHED;
;         }
;         if constexpr (ALIGN_EPI) { if (wr == 0) PG8_BAR; }
	v_add_u32_e32 v132, 0x18000, v244
	v_add_u32_e32 v152, 0x1c000, v244
	ds_read_b128 v[108:111], v132
	ds_read_b128 v[120:123], v132 offset:1024
	ds_read_b128 v[128:131], v132 offset:2048
	ds_read_b128 v[132:135], v132 offset:3072
	ds_read_b128 v[136:139], v152
	ds_read_b128 v[144:147], v152 offset:1024
	ds_read_b128 v[148:151], v152 offset:2048
	ds_read_b128 v[152:155], v152 offset:3072
	ds_read_b128 v[156:159], v245 offset:32768
	ds_read_b128 v[160:163], v245 offset:33792
	ds_read_b128 v[164:167], v245 offset:34816
	ds_read_b128 v[176:179], v245 offset:35840
	ds_read_b128 v[180:183], v245 offset:36864
	ds_read_b128 v[184:187], v245 offset:37888
	ds_read_b128 v[188:191], v245 offset:38912
	ds_read_b128 v[202:205], v245 offset:39936
	s_add_u32 s56, s56, s15
	s_addc_u32 s57, s57, 0
	s_mov_b32 m0, s41
	s_nop 0
	global_load_lds_dwordx4 v0, s[56:57]
	s_nop 0
	s_mov_b32 m0, s42
	s_nop 0
	global_load_lds_dwordx4 v240, s[56:57]
	s_waitcnt vmcnt(8)
	s_waitcnt lgkmcnt(0)
	s_barrier
	s_setprio 1
	s_waitcnt lgkmcnt(0)
	v_mfma_f32_16x16x32_bf16 v[172:175], v[108:111], v[156:159], v[172:175]
	v_mfma_f32_16x16x32_bf16 v[172:175], v[120:123], v[160:163], v[172:175]
	v_mfma_f32_16x16x32_bf16 v[168:171], v[128:131], v[156:159], v[168:171]
	v_mfma_f32_16x16x32_bf16 v[168:171], v[132:135], v[160:163], v[168:171]
	v_mfma_f32_16x16x32_bf16 v[140:143], v[136:139], v[156:159], v[140:143]
	v_mfma_f32_16x16x32_bf16 v[140:143], v[144:147], v[160:163], v[140:143]
	v_mfma_f32_16x16x32_bf16 v[124:127], v[148:151], v[156:159], v[124:127]
	v_mfma_f32_16x16x32_bf16 v[124:127], v[152:155], v[160:163], v[124:127]
	v_mfma_f32_16x16x32_bf16 v[100:103], v[148:151], v[164:167], v[100:103]
	v_mfma_f32_16x16x32_bf16 v[100:103], v[152:155], v[176:179], v[100:103]
	v_mfma_f32_16x16x32_bf16 v[104:107], v[136:139], v[164:167], v[104:107]
	v_mfma_f32_16x16x32_bf16 v[104:107], v[144:147], v[176:179], v[104:107]
	v_mfma_f32_16x16x32_bf16 v[112:115], v[128:131], v[164:167], v[112:115]
	v_mfma_f32_16x16x32_bf16 v[112:115], v[132:135], v[176:179], v[112:115]
	v_mfma_f32_16x16x32_bf16 v[116:119], v[108:111], v[164:167], v[116:119]
	v_mfma_f32_16x16x32_bf16 v[116:119], v[120:123], v[176:179], v[116:119]
	v_mfma_f32_16x16x32_bf16 v[96:99], v[108:111], v[180:183], v[96:99]
	v_mfma_f32_16x16x32_bf16 v[96:99], v[120:123], v[184:187], v[96:99]
	v_mfma_f32_16x16x32_bf16 v[92:95], v[128:131], v[180:183], v[92:95]
	v_mfma_f32_16x16x32_bf16 v[92:95], v[132:135], v[184:187], v[92:95]
	v_mfma_f32_16x16x32_bf16 v[88:91], v[136:139], v[180:183], v[88:91]
	v_mfma_f32_16x16x32_bf16 v[88:91], v[144:147], v[184:187], v[88:91]
	v_mfma_f32_16x16x32_bf16 v[84:87], v[148:151], v[180:183], v[84:87]
	v_mfma_f32_16x16x32_bf16 v[84:87], v[152:155], v[184:187], v[84:87]
	v_mfma_f32_16x16x32_bf16 v[68:71], v[148:151], v[188:191], v[68:71]
	v_mfma_f32_16x16x32_bf16 v[68:71], v[152:155], v[202:205], v[68:71]
	v_mfma_f32_16x16x32_bf16 v[72:75], v[136:139], v[188:191], v[72:75]
	v_mfma_f32_16x16x32_bf16 v[72:75], v[144:147], v[202:205], v[72:75]
	v_mfma_f32_16x16x32_bf16 v[76:79], v[128:131], v[188:191], v[76:79]
	v_mfma_f32_16x16x32_bf16 v[76:79], v[132:135], v[202:205], v[76:79]
	v_mfma_f32_16x16x32_bf16 v[80:83], v[108:111], v[188:191], v[80:83]
	v_mfma_f32_16x16x32_bf16 v[80:83], v[120:123], v[202:205], v[80:83]
	s_setprio 0
	s_barrier
	ds_read_b128 v[156:159], v245 offset:49152
	ds_read_b128 v[160:163], v245 offset:50176
	ds_read_b128 v[164:167], v245 offset:51200
	ds_read_b128 v[176:179], v245 offset:52224
	ds_read_b128 v[180:183], v245 offset:53248
	ds_read_b128 v[184:187], v245 offset:54272
	ds_read_b128 v[188:191], v245 offset:55296
	ds_read_b128 v[202:205], v245 offset:56320
	s_add_u32 s54, s54, 0x80
	s_addc_u32 s55, s55, 0
	s_mov_b32 m0, s46
	s_nop 0
	global_load_lds_dwordx4 v195, s[54:55]
	s_nop 0
	s_mov_b32 m0, s50
	s_nop 0
	global_load_lds_dwordx4 v241, s[54:55]
	s_add_u32 s54, s58, 0x80
	s_addc_u32 s55, s59, 0
	s_mov_b32 m0, s61
	s_nop 0
	global_load_lds_dwordx4 v195, s[54:55]
	s_nop 0
	s_mov_b32 m0, s65
	s_nop 0
	global_load_lds_dwordx4 v241, s[54:55]
	s_nop 0
	s_mov_b32 m0, s53
	s_nop 0
	global_load_lds_dwordx4 v0, s[48:49]
	s_nop 0
	s_mov_b32 m0, s60
	s_nop 0
	global_load_lds_dwordx4 v240, s[48:49]
	s_waitcnt vmcnt(8)
	s_waitcnt lgkmcnt(0)
	s_barrier
	s_setprio 1
	s_waitcnt lgkmcnt(0)
	v_mfma_f32_16x16x32_bf16 v[64:67], v[108:111], v[156:159], v[64:67]
	v_mfma_f32_16x16x32_bf16 v[64:67], v[120:123], v[160:163], v[64:67]
	v_mfma_f32_16x16x32_bf16 v[60:63], v[128:131], v[156:159], v[60:63]
	v_mfma_f32_16x16x32_bf16 v[60:63], v[132:135], v[160:163], v[60:63]
	v_mfma_f32_16x16x32_bf16 v[56:59], v[136:139], v[156:159], v[56:59]
	v_mfma_f32_16x16x32_bf16 v[56:59], v[144:147], v[160:163], v[56:59]
	v_mfma_f32_16x16x32_bf16 v[52:55], v[148:151], v[156:159], v[52:55]
	v_mfma_f32_16x16x32_bf16 v[52:55], v[152:155], v[160:163], v[52:55]
	v_mfma_f32_16x16x32_bf16 v[36:39], v[148:151], v[164:167], v[36:39]
	v_mfma_f32_16x16x32_bf16 v[36:39], v[152:155], v[176:179], v[36:39]
	v_mfma_f32_16x16x32_bf16 v[40:43], v[136:139], v[164:167], v[40:43]
	v_mfma_f32_16x16x32_bf16 v[40:43], v[144:147], v[176:179], v[40:43]
	v_mfma_f32_16x16x32_bf16 v[44:47], v[128:131], v[164:167], v[44:47]
	v_mfma_f32_16x16x32_bf16 v[44:47], v[132:135], v[176:179], v[44:47]
	v_mfma_f32_16x16x32_bf16 v[48:51], v[108:111], v[164:167], v[48:51]
	v_mfma_f32_16x16x32_bf16 v[48:51], v[120:123], v[176:179], v[48:51]
	v_mfma_f32_16x16x32_bf16 v[32:35], v[108:111], v[180:183], v[32:35]
	v_mfma_f32_16x16x32_bf16 v[32:35], v[120:123], v[184:187], v[32:35]
	v_mfma_f32_16x16x32_bf16 v[28:31], v[128:131], v[180:183], v[28:31]
	v_mfma_f32_16x16x32_bf16 v[28:31], v[132:135], v[184:187], v[28:31]
	v_mfma_f32_16x16x32_bf16 v[24:27], v[136:139], v[180:183], v[24:27]
	v_mfma_f32_16x16x32_bf16 v[24:27], v[144:147], v[184:187], v[24:27]
	v_mfma_f32_16x16x32_bf16 v[20:23], v[148:151], v[180:183], v[20:23]
	v_mfma_f32_16x16x32_bf16 v[20:23], v[152:155], v[184:187], v[20:23]
	v_mfma_f32_16x16x32_bf16 v[4:7], v[148:151], v[188:191], v[4:7]
	v_mfma_f32_16x16x32_bf16 v[4:7], v[152:155], v[202:205], v[4:7]
	v_mfma_f32_16x16x32_bf16 v[8:11], v[136:139], v[188:191], v[8:11]
	v_mfma_f32_16x16x32_bf16 v[8:11], v[144:147], v[202:205], v[8:11]
	v_mfma_f32_16x16x32_bf16 v[12:15], v[128:131], v[188:191], v[12:15]
	v_mfma_f32_16x16x32_bf16 v[12:15], v[132:135], v[202:205], v[12:15]
	v_mfma_f32_16x16x32_bf16 v[16:19], v[108:111], v[188:191], v[16:19]
	v_mfma_f32_16x16x32_bf16 v[16:19], v[120:123], v[202:205], v[16:19]
	s_setprio 0
	s_add_u32 s4, s4, 0x100
	s_addc_u32 s5, s5, 0
	s_add_u32 s37, s37, 0x100
	s_addc_u32 s44, s44, 0
	s_cmp_ge_u32 s51, s43
	s_mov_b32 s45, s51
	s_barrier
	s_cbranch_scc0 .LBB0_151
	s_and_b64 vcc, exec, s[92:93]
	s_cbranch_vccz .LBB0_154
	s_barrier

; #define PG8_STAGE(bufoff, gbase, voff) do { _Pragma("unroll") for (int _i = 0; _i < 2; ++_i) { \
;         const unsigned _m0 = ldsb + (unsigned)((bufoff) + _i * 8192); const char* _gb = (const char*)(gbase); \
;         asm volatile("s_mov_b32 m0, %0\n\ts_nop 0\n\tglobal_load_lds_dwordx4 %1, %2" :: "s"(_m0), "v"((voff)[_i]), "s"(_gb) : "m0", "memory"); } } while (0)
; #define PG8_LDA(dst, b, h) do { _Pragma("unroll") for (int m = 0; m < 4; ++m) _Pragma("unroll") for (int k = 0; k < 2; ++k) dst[m][k] = *(const LAS bf16x8*)(lds + PG8_SA(b, h) + aoff + m * 2048 + k * 1024); } while (0)
; #define PG8_LDB(dst, b, h) do { _Pragma("unroll") for (int n = 0; n < 2; ++n) _Pragma("unroll") for (int k = 0; k < 2; ++k) dst[n][k] = *(const LAS bf16x8*)(lds + PG8_SB(b, h) + boff + n * 2048 + k * 1024); } while (0)
; #define PG8_MMA(ai, bj, At, Bt) do { __builtin_amdgcn_s_setprio(1); _Pragma("unroll") for (int m = 0; m < 4; ++m) _Pragma("unroll") for (int n = 0; n < 2; ++n) _Pragma("unroll") for (int k = 0; k < 2; ++k) \
;         acc[ai][bj][m][n] = __builtin_amdgcn_mfma_f32_16x16x32_bf16(Bt[n][k], At[m][k], acc[ai][bj][m][n], 0, 0, 0); __builtin_amdgcn_s_setprio(0); } while (0)
; #define PG8_WAIT_V(n) asm volatile("s_waitcnt vmcnt(" #n ")" ::: "memory")
; #define PG8_WAIT_L(n) asm volatile("s_waitcnt lgkmcnt(" #n ")" ::: "memory")
; template <class Epi, bool ALIGN_EPI>
; __device__ __forceinline__ void gemm_phase(LAS unsigned char* lds, const Gemm g, const StaticOrder& S, const Epi& E) {
;     ...
;         for (int t = 0; t < nt; t += 2) {
;             const bool last = (t == nt - 2);
;             const char* a1 = cA + (size_t)(t + 1) * kstep;
;             const char* a2 = last ? nA : cA + (size_t)(t + 2) * kstep; const char* b2 = last ? nB : cB + (size_t)(t + 2) * kstep;
;             const char* a3 = a2 + kstep; const char* b3 = b2 + kstep;
;             PG8_LDB(B0, 0, 0); PG8_LDB(B1, 0, 1); PG8_SCHED; PG8_LDA(At, 0, 0); PG8_STAGE(PG8_SA(1, 1), a1 + hstepA, voffA);
;             PG8_WAIT_V(8); PG8_WAIT_L(0); PG8_BAR; PG8_MMA(0, 0, At, B0); PG8_MMA(0, 1, At, B1); PG8_BAR; PG8_SCHED;
;             PG8_LDA(At, 0, 1); PG8_STAGE(PG8_SB(0, 0), b2, voffB); PG8_STAGE(PG8_SB(0, 1), b2 + hstepB, voffB); PG8_STAGE(PG8_SA(0, 0), a2, voffA);
;             PG8_WAIT_V(8); PG8_WAIT_L(0); PG8_BAR; PG8_MMA(1, 0, At, B0); PG8_MMA(1, 1, At, B1); PG8_BAR; PG8_SCHED;
.LBB0_200:
	s_add_u32 s4, s48, 0x100
	s_addc_u32 s5, s49, 0
	s_add_u32 s15, s54, 0x100
	s_addc_u32 s42, s55, 0
	s_mov_b32 s43, 0
	s_add_i32 s44, s43, 2
	s_cmp_eq_u32 s68, s43
	s_cselect_b32 s56, s0, s15
	s_cselect_b32 s57, s1, s42
	s_cselect_b32 s54, s94, s4
	s_cselect_b32 s55, s95, s5
	s_add_u32 s48, s56, 0x80
	s_addc_u32 s49, s57, 0
	s_add_u32 s43, s15, s38
	s_addc_u32 s45, s42, 0
	s_add_u32 s58, s43, 0xffffff80
	s_addc_u32 s59, s45, -1
	s_mov_b32 m0, s37
	s_nop 0
	global_load_lds_dwordx4 v0, s[58:59]
	s_nop 0
	s_mov_b32 m0, s41
	s_nop 0
	global_load_lds_dwordx4 v206, s[58:59]
	s_waitcnt vmcnt(8)
	s_waitcnt lgkmcnt(0)
	s_barrier
	s_setprio 1
	s_waitcnt lgkmcnt(0)
	v_mfma_f32_16x16x32_bf16 v[126:129], v[130:133], v[162:165], 0
	v_mfma_f32_16x16x32_bf16 v[126:129], v[134:137], v[166:169], v[126:129]
	v_mfma_f32_16x16x32_bf16 v[122:125], v[138:141], v[162:165], 0
	v_mfma_f32_16x16x32_bf16 v[122:125], v[142:145], v[166:169], v[122:125]
	v_mfma_f32_16x16x32_bf16 v[118:121], v[146:149], v[162:165], 0
	v_mfma_f32_16x16x32_bf16 v[118:121], v[150:153], v[166:169], v[118:121]
	v_mfma_f32_16x16x32_bf16 v[114:117], v[154:157], v[162:165], 0
	v_mfma_f32_16x16x32_bf16 v[114:117], v[158:161], v[166:169], v[114:117]
	v_mfma_f32_16x16x32_bf16 v[98:101], v[154:157], v[170:173], 0
	v_mfma_f32_16x16x32_bf16 v[98:101], v[158:161], v[174:177], v[98:101]
	v_mfma_f32_16x16x32_bf16 v[102:105], v[146:149], v[170:173], 0
	v_mfma_f32_16x16x32_bf16 v[102:105], v[150:153], v[174:177], v[102:105]
	v_mfma_f32_16x16x32_bf16 v[106:109], v[138:141], v[170:173], 0
	v_mfma_f32_16x16x32_bf16 v[106:109], v[142:145], v[174:177], v[106:109]
	v_mfma_f32_16x16x32_bf16 v[110:113], v[130:133], v[170:173], 0
	v_mfma_f32_16x16x32_bf16 v[110:113], v[134:137], v[174:177], v[110:113]
	v_mfma_f32_16x16x32_bf16 v[94:97], v[130:133], v[178:181], 0
	v_mfma_f32_16x16x32_bf16 v[94:97], v[134:137], v[182:185], v[94:97]
	v_mfma_f32_16x16x32_bf16 v[90:93], v[138:141], v[178:181], 0
	v_mfma_f32_16x16x32_bf16 v[90:93], v[142:145], v[182:185], v[90:93]
	v_mfma_f32_16x16x32_bf16 v[86:89], v[146:149], v[178:181], 0
	v_mfma_f32_16x16x32_bf16 v[86:89], v[150:153], v[182:185], v[86:89]
	v_mfma_f32_16x16x32_bf16 v[82:85], v[154:157], v[178:181], 0
	v_mfma_f32_16x16x32_bf16 v[82:85], v[158:161], v[182:185], v[82:85]
	v_mfma_f32_16x16x32_bf16 v[66:69], v[154:157], v[186:189], 0
	v_mfma_f32_16x16x32_bf16 v[66:69], v[158:161], v[190:193], v[66:69]
	v_mfma_f32_16x16x32_bf16 v[70:73], v[146:149], v[186:189], 0
	v_mfma_f32_16x16x32_bf16 v[70:73], v[150:153], v[190:193], v[70:73]
	v_mfma_f32_16x16x32_bf16 v[74:77], v[138:141], v[186:189], 0
	v_mfma_f32_16x16x32_bf16 v[74:77], v[142:145], v[190:193], v[74:77]
	v_mfma_f32_16x16x32_bf16 v[78:81], v[130:133], v[186:189], 0
	v_mfma_f32_16x16x32_bf16 v[78:81], v[134:137], v[190:193], v[78:81]
	s_setprio 0
	s_barrier
	ds_read_b128 v[162:165], v246 offset:16384
	ds_read_b128 v[166:169], v246 offset:17408
	ds_read_b128 v[170:173], v246 offset:18432
	ds_read_b128 v[174:177], v246 offset:19456
	ds_read_b128 v[178:181], v246 offset:20480
	ds_read_b128 v[182:185], v246 offset:21504
	ds_read_b128 v[186:189], v246 offset:22528
	ds_read_b128 v[190:193], v246 offset:23552
	s_mov_b32 m0, s46
	s_nop 0
	global_load_lds_dwordx4 v195, s[54:55]
	s_add_u32 s58, s54, s38
	s_mov_b32 m0, s26
	s_nop 0
	global_load_lds_dwordx4 v207, s[54:55]
	s_addc_u32 s59, s55, 0
	s_mov_b32 m0, s27
	s_nop 0
	global_load_lds_dwordx4 v195, s[58:59]
	s_nop 0
	s_mov_b32 m0, s30
	s_nop 0
	global_load_lds_dwordx4 v207, s[58:59]
	s_nop 0
	s_mov_b32 m0, s29
	s_nop 0
	global_load_lds_dwordx4 v0, s[56:57]
	s_nop 0
	s_mov_b32 m0, s17
	s_nop 0
	global_load_lds_dwordx4 v206, s[56:57]
	s_waitcnt vmcnt(8)
	s_waitcnt lgkmcnt(0)
	s_barrier
	s_setprio 1
	s_waitcnt lgkmcnt(0)
	v_mfma_f32_16x16x32_bf16 v[62:65], v[130:133], v[162:165], 0
	v_mfma_f32_16x16x32_bf16 v[62:65], v[134:137], v[166:169], v[62:65]
	v_mfma_f32_16x16x32_bf16 v[58:61], v[138:141], v[162:165], 0
	v_mfma_f32_16x16x32_bf16 v[58:61], v[142:145], v[166:169], v[58:61]
	v_mfma_f32_16x16x32_bf16 v[54:57], v[146:149], v[162:165], 0
	v_mfma_f32_16x16x32_bf16 v[54:57], v[150:153], v[166:169], v[54:57]
	v_mfma_f32_16x16x32_bf16 v[50:53], v[154:157], v[162:165], 0
	v_mfma_f32_16x16x32_bf16 v[50:53], v[158:161], v[166:169], v[50:53]
	v_mfma_f32_16x16x32_bf16 v[34:37], v[154:157], v[170:173], 0
	v_mfma_f32_16x16x32_bf16 v[34:37], v[158:161], v[174:177], v[34:37]
	v_mfma_f32_16x16x32_bf16 v[38:41], v[146:149], v[170:173], 0
	v_mfma_f32_16x16x32_bf16 v[38:41], v[150:153], v[174:177], v[38:41]
	v_mfma_f32_16x16x32_bf16 v[42:45], v[138:141], v[170:173], 0
	v_mfma_f32_16x16x32_bf16 v[42:45], v[142:145], v[174:177], v[42:45]
	v_mfma_f32_16x16x32_bf16 v[46:49], v[130:133], v[170:173], 0
	v_mfma_f32_16x16x32_bf16 v[46:49], v[134:137], v[174:177], v[46:49]
	v_mfma_f32_16x16x32_bf16 v[30:33], v[130:133], v[178:181], 0
	v_mfma_f32_16x16x32_bf16 v[30:33], v[134:137], v[182:185], v[30:33]
	v_mfma_f32_16x16x32_bf16 v[26:29], v[138:141], v[178:181], 0
	v_mfma_f32_16x16x32_bf16 v[26:29], v[142:145], v[182:185], v[26:29]
	v_mfma_f32_16x16x32_bf16 v[22:25], v[146:149], v[178:181], 0
	v_mfma_f32_16x16x32_bf16 v[22:25], v[150:153], v[182:185], v[22:25]
	v_mfma_f32_16x16x32_bf16 v[18:21], v[154:157], v[178:181], 0
	v_mfma_f32_16x16x32_bf16 v[18:21], v[158:161], v[182:185], v[18:21]
	v_mfma_f32_16x16x32_bf16 v[2:5], v[154:157], v[186:189], 0
	v_mfma_f32_16x16x32_bf16 v[2:5], v[158:161], v[190:193], v[2:5]
	v_mfma_f32_16x16x32_bf16 v[6:9], v[146:149], v[186:189], 0
	v_mfma_f32_16x16x32_bf16 v[6:9], v[150:153], v[190:193], v[6:9]
	v_mfma_f32_16x16x32_bf16 v[10:13], v[138:141], v[186:189], 0
	v_mfma_f32_16x16x32_bf16 v[10:13], v[142:145], v[190:193], v[10:13]
	v_mfma_f32_16x16x32_bf16 v[14:17], v[130:133], v[186:189], 0
	v_mfma_f32_16x16x32_bf16 v[14:17], v[134:137], v[190:193], v[14:17]
	s_setprio 0
	s_barrier
; #define PG8_STAGE(bufoff, gbase, voff) do { _Pragma("unroll") for (int _i = 0; _i < 2; ++_i) { \
;         const unsigned _m0 = ldsb + (unsigned)((bufoff) + _i * 8192); const char* _gb = (const char*)(gbase); \
;         asm volatile("s_mov_b32 m0, %0\n\ts_nop 0\n\tglobal_load_lds_dwordx4 %1, %2" :: "s"(_m0), "v"((voff)[_i]), "s"(_gb) : "m0", "memory"); } } while (0)
; #define PG8_LDA(dst, b, h) do { _Pragma("unroll") for (int m = 0; m < 4; ++m) _Pragma("unroll") for (int k = 0; k < 2; ++k) dst[m][k] = *(const LAS bf16x8*)(lds + PG8_SA(b, h) + aoff + m * 2048 + k * 1024); } while (0)
; #define PG8_LDB(dst, b, h) do { _Pragma("unroll") for (int n = 0; n < 2; ++n) _Pragma("unroll") for (int k = 0; k < 2; ++k) dst[n][k] = *(const LAS bf16x8*)(lds + PG8_SB(b, h) + boff + n * 2048 + k * 1024); } while (0)
; #define PG8_MMA(ai, bj, At, Bt) do { __builtin_amdgcn_s_setprio(1); _Pragma("unroll") for (int m = 0; m < 4; ++m) _Pragma("unroll") for (int n = 0; n < 2; ++n) _Pragma("unroll") for (int k = 0; k < 2; ++k) \
;         acc[ai][bj][m][n] = __builtin_amdgcn_mfma_f32_16x16x32_bf16(Bt[n][k], At[m][k], acc[ai][bj][m][n], 0, 0, 0); __builtin_amdgcn_s_setprio(0); } while (0)
; #define PG8_WAIT_V(n) asm volatile("s_waitcnt vmcnt(" #n ")" ::: "memory")
; #define PG8_WAIT_L(n) asm volatile("s_waitcnt lgkmcnt(" #n ")" ::: "memory")
; #define PG8_BAR __builtin_amdgcn_s_barrier()
; #define PG8_SCHED __builtin_amdgcn_sched_barrier(0)
; template <class Epi, bool ALIGN_EPI>
; __device__ __forceinline__ void gemm_phase(LAS unsigned char* lds, const Gemm g, const StaticOrder& S, const Epi& E) {
;     ...
;             PG8_LDB(B0, 1, 0); PG8_LDB(B1, 1, 1); PG8_SCHED; PG8_LDA(At, 1, 0); PG8_STAGE(PG8_SA(0, 1), a2 + hstepA, voffA);
;             PG8_WAIT_V(8); PG8_WAIT_L(0); PG8_BAR; PG8_MMA(0, 0, At, B0); PG8_MMA(0, 1, At, B1); PG8_BAR; PG8_SCHED;
;             PG8_LDA(At, 1, 1); PG8_STAGE(PG8_SB(1, 0), b3, voffB); PG8_STAGE(PG8_SB(1, 1), b3 + hstepB, voffB); PG8_STAGE(PG8_SA(1, 0), a3, voffA);
;             PG8_WAIT_V(8); PG8_WAIT_L(0); PG8_BAR; PG8_MMA(1, 0, At, B0); PG8_MMA(1, 1, At, B1); PG8_BAR; PG8_SCHED;
;         }
	v_add_u32_e32 v142, 0x18000, v245
	v_add_u32_e32 v158, 0x1c000, v245
	ds_read_b128 v[130:133], v142
	ds_read_b128 v[134:137], v142 offset:1024
	ds_read_b128 v[138:141], v142 offset:2048
	ds_read_b128 v[142:145], v142 offset:3072
	ds_read_b128 v[146:149], v158
	ds_read_b128 v[150:153], v158 offset:1024
	ds_read_b128 v[154:157], v158 offset:2048
	ds_read_b128 v[158:161], v158 offset:3072
	ds_read_b128 v[162:165], v246 offset:32768
	ds_read_b128 v[166:169], v246 offset:33792
	ds_read_b128 v[170:173], v246 offset:34816
	ds_read_b128 v[174:177], v246 offset:35840
	ds_read_b128 v[178:181], v246 offset:36864
	ds_read_b128 v[182:185], v246 offset:37888
	ds_read_b128 v[186:189], v246 offset:38912
	ds_read_b128 v[190:193], v246 offset:39936
	s_add_u32 s56, s56, s38
	s_addc_u32 s57, s57, 0
	s_mov_b32 m0, s31
	s_nop 0
	global_load_lds_dwordx4 v0, s[56:57]
	s_nop 0
	s_mov_b32 m0, s53
	s_nop 0
	global_load_lds_dwordx4 v206, s[56:57]
	s_waitcnt vmcnt(8)
	s_waitcnt lgkmcnt(0)
	s_barrier
	s_setprio 1
	s_waitcnt lgkmcnt(0)
	v_mfma_f32_16x16x32_bf16 v[126:129], v[130:133], v[162:165], v[126:129]
	v_mfma_f32_16x16x32_bf16 v[126:129], v[134:137], v[166:169], v[126:129]
	v_mfma_f32_16x16x32_bf16 v[122:125], v[138:141], v[162:165], v[122:125]
	v_mfma_f32_16x16x32_bf16 v[122:125], v[142:145], v[166:169], v[122:125]
	v_mfma_f32_16x16x32_bf16 v[118:121], v[146:149], v[162:165], v[118:121]
	v_mfma_f32_16x16x32_bf16 v[118:121], v[150:153], v[166:169], v[118:121]
	v_mfma_f32_16x16x32_bf16 v[114:117], v[154:157], v[162:165], v[114:117]
	v_mfma_f32_16x16x32_bf16 v[114:117], v[158:161], v[166:169], v[114:117]
	v_mfma_f32_16x16x32_bf16 v[98:101], v[154:157], v[170:173], v[98:101]
	v_mfma_f32_16x16x32_bf16 v[98:101], v[158:161], v[174:177], v[98:101]
	v_mfma_f32_16x16x32_bf16 v[102:105], v[146:149], v[170:173], v[102:105]
	v_mfma_f32_16x16x32_bf16 v[102:105], v[150:153], v[174:177], v[102:105]
	v_mfma_f32_16x16x32_bf16 v[106:109], v[138:141], v[170:173], v[106:109]
	v_mfma_f32_16x16x32_bf16 v[106:109], v[142:145], v[174:177], v[106:109]
	v_mfma_f32_16x16x32_bf16 v[110:113], v[130:133], v[170:173], v[110:113]
	v_mfma_f32_16x16x32_bf16 v[110:113], v[134:137], v[174:177], v[110:113]
	v_mfma_f32_16x16x32_bf16 v[94:97], v[130:133], v[178:181], v[94:97]
	v_mfma_f32_16x16x32_bf16 v[94:97], v[134:137], v[182:185], v[94:97]
	v_mfma_f32_16x16x32_bf16 v[90:93], v[138:141], v[178:181], v[90:93]
	v_mfma_f32_16x16x32_bf16 v[90:93], v[142:145], v[182:185], v[90:93]
	v_mfma_f32_16x16x32_bf16 v[86:89], v[146:149], v[178:181], v[86:89]
	v_mfma_f32_16x16x32_bf16 v[86:89], v[150:153], v[182:185], v[86:89]
	v_mfma_f32_16x16x32_bf16 v[82:85], v[154:157], v[178:181], v[82:85]
	v_mfma_f32_16x16x32_bf16 v[82:85], v[158:161], v[182:185], v[82:85]
	v_mfma_f32_16x16x32_bf16 v[66:69], v[154:157], v[186:189], v[66:69]
	v_mfma_f32_16x16x32_bf16 v[66:69], v[158:161], v[190:193], v[66:69]
	v_mfma_f32_16x16x32_bf16 v[70:73], v[146:149], v[186:189], v[70:73]
	v_mfma_f32_16x16x32_bf16 v[70:73], v[150:153], v[190:193], v[70:73]
	v_mfma_f32_16x16x32_bf16 v[74:77], v[138:141], v[186:189], v[74:77]
	v_mfma_f32_16x16x32_bf16 v[74:77], v[142:145], v[190:193], v[74:77]
	v_mfma_f32_16x16x32_bf16 v[78:81], v[130:133], v[186:189], v[78:81]
	v_mfma_f32_16x16x32_bf16 v[78:81], v[134:137], v[190:193], v[78:81]
	s_setprio 0
	s_barrier
	ds_read_b128 v[162:165], v246 offset:49152
	ds_read_b128 v[166:169], v246 offset:50176
	ds_read_b128 v[170:173], v246 offset:51200
	ds_read_b128 v[174:177], v246 offset:52224
	ds_read_b128 v[178:181], v246 offset:53248
	ds_read_b128 v[182:185], v246 offset:54272
	ds_read_b128 v[186:189], v246 offset:55296
	ds_read_b128 v[190:193], v246 offset:56320
	s_add_u32 s54, s54, 0x80
	s_addc_u32 s55, s55, 0
	s_mov_b32 m0, s85
	s_nop 0
	global_load_lds_dwordx4 v195, s[54:55]
	s_nop 0
	s_mov_b32 m0, s65
	s_nop 0
	global_load_lds_dwordx4 v207, s[54:55]
	s_add_u32 s54, s58, 0x80
	s_addc_u32 s55, s59, 0
	s_mov_b32 m0, s93
	s_nop 0
	global_load_lds_dwordx4 v195, s[54:55]
	s_nop 0
	s_mov_b32 m0, s28
	s_nop 0
	global_load_lds_dwordx4 v207, s[54:55]
	s_nop 0
	s_mov_b32 m0, s67
	s_nop 0
	global_load_lds_dwordx4 v0, s[48:49]
	s_nop 0
	s_mov_b32 m0, s92
	s_nop 0
	global_load_lds_dwordx4 v206, s[48:49]
	s_waitcnt vmcnt(8)
	s_waitcnt lgkmcnt(0)
	s_barrier
	s_setprio 1
	s_waitcnt lgkmcnt(0)
	v_mfma_f32_16x16x32_bf16 v[62:65], v[130:133], v[162:165], v[62:65]
	v_mfma_f32_16x16x32_bf16 v[62:65], v[134:137], v[166:169], v[62:65]
	v_mfma_f32_16x16x32_bf16 v[58:61], v[138:141], v[162:165], v[58:61]
	v_mfma_f32_16x16x32_bf16 v[58:61], v[142:145], v[166:169], v[58:61]
	v_mfma_f32_16x16x32_bf16 v[54:57], v[146:149], v[162:165], v[54:57]
	v_mfma_f32_16x16x32_bf16 v[54:57], v[150:153], v[166:169], v[54:57]
	v_mfma_f32_16x16x32_bf16 v[50:53], v[154:157], v[162:165], v[50:53]
	v_mfma_f32_16x16x32_bf16 v[50:53], v[158:161], v[166:169], v[50:53]
	v_mfma_f32_16x16x32_bf16 v[34:37], v[154:157], v[170:173], v[34:37]
	v_mfma_f32_16x16x32_bf16 v[34:37], v[158:161], v[174:177], v[34:37]
	v_mfma_f32_16x16x32_bf16 v[38:41], v[146:149], v[170:173], v[38:41]
	v_mfma_f32_16x16x32_bf16 v[38:41], v[150:153], v[174:177], v[38:41]
	v_mfma_f32_16x16x32_bf16 v[42:45], v[138:141], v[170:173], v[42:45]
	v_mfma_f32_16x16x32_bf16 v[42:45], v[142:145], v[174:177], v[42:45]
	v_mfma_f32_16x16x32_bf16 v[46:49], v[130:133], v[170:173], v[46:49]
	v_mfma_f32_16x16x32_bf16 v[46:49], v[134:137], v[174:177], v[46:49]
	v_mfma_f32_16x16x32_bf16 v[30:33], v[130:133], v[178:181], v[30:33]
	v_mfma_f32_16x16x32_bf16 v[30:33], v[134:137], v[182:185], v[30:33]
	v_mfma_f32_16x16x32_bf16 v[26:29], v[138:141], v[178:181], v[26:29]
	v_mfma_f32_16x16x32_bf16 v[26:29], v[142:145], v[182:185], v[26:29]
	v_mfma_f32_16x16x32_bf16 v[22:25], v[146:149], v[178:181], v[22:25]
	v_mfma_f32_16x16x32_bf16 v[22:25], v[150:153], v[182:185], v[22:25]
	v_mfma_f32_16x16x32_bf16 v[18:21], v[154:157], v[178:181], v[18:21]
	v_mfma_f32_16x16x32_bf16 v[18:21], v[158:161], v[182:185], v[18:21]
	v_mfma_f32_16x16x32_bf16 v[2:5], v[154:157], v[186:189], v[2:5]
	v_mfma_f32_16x16x32_bf16 v[2:5], v[158:161], v[190:193], v[2:5]
	v_mfma_f32_16x16x32_bf16 v[6:9], v[146:149], v[186:189], v[6:9]
	v_mfma_f32_16x16x32_bf16 v[6:9], v[150:153], v[190:193], v[6:9]
	v_mfma_f32_16x16x32_bf16 v[10:13], v[138:141], v[186:189], v[10:13]
	v_mfma_f32_16x16x32_bf16 v[10:13], v[142:145], v[190:193], v[10:13]
	v_mfma_f32_16x16x32_bf16 v[14:17], v[130:133], v[186:189], v[14:17]
	v_mfma_f32_16x16x32_bf16 v[14:17], v[134:137], v[190:193], v[14:17]
	s_setprio 0
	s_add_u32 s4, s4, 0x100
	s_addc_u32 s5, s5, 0
	s_add_u32 s15, s15, 0x100
	s_addc_u32 s42, s42, 0
	s_cmp_ge_u32 s44, s36
	s_mov_b32 s43, s44
	s_barrier
; #define PG8_STAGE(bufoff, gbase, voff) do { _Pragma("unroll") for (int _i = 0; _i < 2; ++_i) { \
;         const unsigned _m0 = ldsb + (unsigned)((bufoff) + _i * 8192); const char* _gb = (const char*)(gbase); \
;         asm volatile("s_mov_b32 m0, %0\n\ts_nop 0\n\tglobal_load_lds_dwordx4 %1, %2" :: "s"(_m0), "v"((voff)[_i]), "s"(_gb) : "m0", "memory"); } } while (0)
; #define PG8_LDA(dst, b, h) do { _Pragma("unroll") for (int m = 0; m < 4; ++m) _Pragma("unroll") for (int k = 0; k < 2; ++k) dst[m][k] = *(const LAS bf16x8*)(lds + PG8_SA(b, h) + aoff + m * 2048 + k * 1024); } while (0)
; #define PG8_LDB(dst, b, h) do { _Pragma("unroll") for (int n = 0; n < 2; ++n) _Pragma("unroll") for (int k = 0; k < 2; ++k) dst[n][k] = *(const LAS bf16x8*)(lds + PG8_SB(b, h) + boff + n * 2048 + k * 1024); } while (0)
; #define PG8_MMA(ai, bj, At, Bt) do { __builtin_amdgcn_s_setprio(1); _Pragma("unroll") for (int m = 0; m < 4; ++m) _Pragma("unroll") for (int n = 0; n < 2; ++n) _Pragma("unroll") for (int k = 0; k < 2; ++k) \
;         acc[ai][bj][m][n] = __builtin_amdgcn_mfma_f32_16x16x32_bf16(Bt[n][k], At[m][k], acc[ai][bj][m][n], 0, 0, 0); __builtin_amdgcn_s_setprio(0); } while (0)
; #define PG8_WAIT_V(n) asm volatile("s_waitcnt vmcnt(" #n ")" ::: "memory")
; #define PG8_WAIT_L(n) asm volatile("s_waitcnt lgkmcnt(" #n ")" ::: "memory")
; template <class Epi, bool ALIGN_EPI>
; __device__ __forceinline__ void gemm_phase(LAS unsigned char* lds, const Gemm g, const StaticOrder& S, const Epi& E) {
;     ...
;         for (int t = 0; t < nt; t += 2) {
;             const bool last = (t == nt - 2);
;             const char* a1 = cA + (size_t)(t + 1) * kstep;
;             const char* a2 = last ? nA : cA + (size_t)(t + 2) * kstep; const char* b2 = last ? nB : cB + (size_t)(t + 2) * kstep;
;             const char* a3 = a2 + kstep; const char* b3 = b2 + kstep;
;             PG8_LDB(B0, 0, 0); PG8_LDB(B1, 0, 1); PG8_SCHED; PG8_LDA(At, 0, 0); PG8_STAGE(PG8_SA(1, 1), a1 + hstepA, voffA);
;             PG8_WAIT_V(8); PG8_WAIT_L(0); PG8_BAR; PG8_MMA(0, 0, At, B0); PG8_MMA(0, 1, At, B1); PG8_BAR; PG8_SCHED;
;             PG8_LDA(At, 0, 1); PG8_STAGE(PG8_SB(0, 0), b2, voffB); PG8_STAGE(PG8_SB(0, 1), b2 + hstepB, voffB); PG8_STAGE(PG8_SA(0, 0), a2, voffA);
;             PG8_WAIT_V(8); PG8_WAIT_L(0); PG8_BAR; PG8_MMA(1, 0, At, B0); PG8_MMA(1, 1, At, B1); PG8_BAR; PG8_SCHED;
.LBB0_201:
	v_add_u32_e32 v142, 0x10000, v245
	v_add_u32_e32 v158, 0x14000, v245
	ds_read_b128 v[130:133], v142
	ds_read_b128 v[134:137], v142 offset:1024
	ds_read_b128 v[138:141], v142 offset:2048
	ds_read_b128 v[142:145], v142 offset:3072
	ds_read_b128 v[146:149], v158
	ds_read_b128 v[150:153], v158 offset:1024
	ds_read_b128 v[154:157], v158 offset:2048
	ds_read_b128 v[158:161], v158 offset:3072
	s_add_i32 s44, s43, 2
	s_cmp_eq_u32 s68, s43
	s_cselect_b32 s56, s0, s15
	s_cselect_b32 s57, s1, s42
	s_cselect_b32 s54, s94, s4
	s_cselect_b32 s55, s95, s5
	s_add_u32 s48, s56, 0x80
	s_addc_u32 s49, s57, 0
	ds_read_b128 v[162:165], v246
	ds_read_b128 v[166:169], v246 offset:1024
	ds_read_b128 v[170:173], v246 offset:2048
	ds_read_b128 v[174:177], v246 offset:3072
	ds_read_b128 v[178:181], v246 offset:4096
	ds_read_b128 v[182:185], v246 offset:5120
	ds_read_b128 v[186:189], v246 offset:6144
	ds_read_b128 v[190:193], v246 offset:7168
	s_add_u32 s43, s15, s38
	s_addc_u32 s45, s42, 0
	s_add_u32 s58, s43, 0xffffff80
	s_addc_u32 s59, s45, -1
	s_mov_b32 m0, s37
	s_nop 0
	global_load_lds_dwordx4 v0, s[58:59]
	s_nop 0
	s_mov_b32 m0, s41
	s_nop 0
	global_load_lds_dwordx4 v206, s[58:59]
	s_waitcnt vmcnt(8)
	s_waitcnt lgkmcnt(0)
	s_barrier
	s_setprio 1
	s_waitcnt lgkmcnt(0)
	v_mfma_f32_16x16x32_bf16 v[126:129], v[130:133], v[162:165], v[126:129]
	v_mfma_f32_16x16x32_bf16 v[126:129], v[134:137], v[166:169], v[126:129]
	v_mfma_f32_16x16x32_bf16 v[122:125], v[138:141], v[162:165], v[122:125]
	v_mfma_f32_16x16x32_bf16 v[122:125], v[142:145], v[166:169], v[122:125]
	v_mfma_f32_16x16x32_bf16 v[118:121], v[146:149], v[162:165], v[118:121]
	v_mfma_f32_16x16x32_bf16 v[118:121], v[150:153], v[166:169], v[118:121]
	v_mfma_f32_16x16x32_bf16 v[114:117], v[154:157], v[162:165], v[114:117]
	v_mfma_f32_16x16x32_bf16 v[114:117], v[158:161], v[166:169], v[114:117]
	v_mfma_f32_16x16x32_bf16 v[98:101], v[154:157], v[170:173], v[98:101]
	v_mfma_f32_16x16x32_bf16 v[98:101], v[158:161], v[174:177], v[98:101]
	v_mfma_f32_16x16x32_bf16 v[102:105], v[146:149], v[170:173], v[102:105]
	v_mfma_f32_16x16x32_bf16 v[102:105], v[150:153], v[174:177], v[102:105]
	v_mfma_f32_16x16x32_bf16 v[106:109], v[138:141], v[170:173], v[106:109]
	v_mfma_f32_16x16x32_bf16 v[106:109], v[142:145], v[174:177], v[106:109]
	v_mfma_f32_16x16x32_bf16 v[110:113], v[130:133], v[170:173], v[110:113]
	v_mfma_f32_16x16x32_bf16 v[110:113], v[134:137], v[174:177], v[110:113]
	v_mfma_f32_16x16x32_bf16 v[94:97], v[130:133], v[178:181], v[94:97]
	v_mfma_f32_16x16x32_bf16 v[94:97], v[134:137], v[182:185], v[94:97]
	v_mfma_f32_16x16x32_bf16 v[90:93], v[138:141], v[178:181], v[90:93]
	v_mfma_f32_16x16x32_bf16 v[90:93], v[142:145], v[182:185], v[90:93]
	v_mfma_f32_16x16x32_bf16 v[86:89], v[146:149], v[178:181], v[86:89]
	v_mfma_f32_16x16x32_bf16 v[86:89], v[150:153], v[182:185], v[86:89]
	v_mfma_f32_16x16x32_bf16 v[82:85], v[154:157], v[178:181], v[82:85]
	v_mfma_f32_16x16x32_bf16 v[82:85], v[158:161], v[182:185], v[82:85]
	v_mfma_f32_16x16x32_bf16 v[66:69], v[154:157], v[186:189], v[66:69]
	v_mfma_f32_16x16x32_bf16 v[66:69], v[158:161], v[190:193], v[66:69]
	v_mfma_f32_16x16x32_bf16 v[70:73], v[146:149], v[186:189], v[70:73]
	v_mfma_f32_16x16x32_bf16 v[70:73], v[150:153], v[190:193], v[70:73]
	v_mfma_f32_16x16x32_bf16 v[74:77], v[138:141], v[186:189], v[74:77]
	v_mfma_f32_16x16x32_bf16 v[74:77], v[142:145], v[190:193], v[74:77]
	v_mfma_f32_16x16x32_bf16 v[78:81], v[130:133], v[186:189], v[78:81]
	v_mfma_f32_16x16x32_bf16 v[78:81], v[134:137], v[190:193], v[78:81]
	s_setprio 0
	s_barrier
	ds_read_b128 v[162:165], v246 offset:16384
	ds_read_b128 v[166:169], v246 offset:17408
	ds_read_b128 v[170:173], v246 offset:18432
	ds_read_b128 v[174:177], v246 offset:19456
	ds_read_b128 v[178:181], v246 offset:20480
	ds_read_b128 v[182:185], v246 offset:21504
	ds_read_b128 v[186:189], v246 offset:22528
	ds_read_b128 v[190:193], v246 offset:23552
	s_mov_b32 m0, s46
	s_nop 0
	global_load_lds_dwordx4 v195, s[54:55]
	s_add_u32 s58, s54, s38
	s_mov_b32 m0, s26
	s_nop 0
	global_load_lds_dwordx4 v207, s[54:55]
	s_addc_u32 s59, s55, 0
	s_mov_b32 m0, s27
	s_nop 0
	global_load_lds_dwordx4 v195, s[58:59]
	s_nop 0
	s_mov_b32 m0, s30
	s_nop 0
	global_load_lds_dwordx4 v207, s[58:59]
	s_nop 0
	s_mov_b32 m0, s29
	s_nop 0
	global_load_lds_dwordx4 v0, s[56:57]
	s_nop 0
	s_mov_b32 m0, s17
	s_nop 0
	global_load_lds_dwordx4 v206, s[56:57]
	s_waitcnt vmcnt(8)
	s_waitcnt lgkmcnt(0)
	s_barrier
	s_setprio 1
	s_waitcnt lgkmcnt(0)
	v_mfma_f32_16x16x32_bf16 v[62:65], v[130:133], v[162:165], v[62:65]
	v_mfma_f32_16x16x32_bf16 v[62:65], v[134:137], v[166:169], v[62:65]
	v_mfma_f32_16x16x32_bf16 v[58:61], v[138:141], v[162:165], v[58:61]
	v_mfma_f32_16x16x32_bf16 v[58:61], v[142:145], v[166:169], v[58:61]
	v_mfma_f32_16x16x32_bf16 v[54:57], v[146:149], v[162:165], v[54:57]
	v_mfma_f32_16x16x32_bf16 v[54:57], v[150:153], v[166:169], v[54:57]
	v_mfma_f32_16x16x32_bf16 v[50:53], v[154:157], v[162:165], v[50:53]
	v_mfma_f32_16x16x32_bf16 v[50:53], v[158:161], v[166:169], v[50:53]
	v_mfma_f32_16x16x32_bf16 v[34:37], v[154:157], v[170:173], v[34:37]
	v_mfma_f32_16x16x32_bf16 v[34:37], v[158:161], v[174:177], v[34:37]
	v_mfma_f32_16x16x32_bf16 v[38:41], v[146:149], v[170:173], v[38:41]
	v_mfma_f32_16x16x32_bf16 v[38:41], v[150:153], v[174:177], v[38:41]
	v_mfma_f32_16x16x32_bf16 v[42:45], v[138:141], v[170:173], v[42:45]
	v_mfma_f32_16x16x32_bf16 v[42:45], v[142:145], v[174:177], v[42:45]
	v_mfma_f32_16x16x32_bf16 v[46:49], v[130:133], v[170:173], v[46:49]
	v_mfma_f32_16x16x32_bf16 v[46:49], v[134:137], v[174:177], v[46:49]
	v_mfma_f32_16x16x32_bf16 v[30:33], v[130:133], v[178:181], v[30:33]
	v_mfma_f32_16x16x32_bf16 v[30:33], v[134:137], v[182:185], v[30:33]
	v_mfma_f32_16x16x32_bf16 v[26:29], v[138:141], v[178:181], v[26:29]
	v_mfma_f32_16x16x32_bf16 v[26:29], v[142:145], v[182:185], v[26:29]
	v_mfma_f32_16x16x32_bf16 v[22:25], v[146:149], v[178:181], v[22:25]
	v_mfma_f32_16x16x32_bf16 v[22:25], v[150:153], v[182:185], v[22:25]
	v_mfma_f32_16x16x32_bf16 v[18:21], v[154:157], v[178:181], v[18:21]
	v_mfma_f32_16x16x32_bf16 v[18:21], v[158:161], v[182:185], v[18:21]
	v_mfma_f32_16x16x32_bf16 v[2:5], v[154:157], v[186:189], v[2:5]
	v_mfma_f32_16x16x32_bf16 v[2:5], v[158:161], v[190:193], v[2:5]
	v_mfma_f32_16x16x32_bf16 v[6:9], v[146:149], v[186:189], v[6:9]
	v_mfma_f32_16x16x32_bf16 v[6:9], v[150:153], v[190:193], v[6:9]
	v_mfma_f32_16x16x32_bf16 v[10:13], v[138:141], v[186:189], v[10:13]
	v_mfma_f32_16x16x32_bf16 v[10:13], v[142:145], v[190:193], v[10:13]
	v_mfma_f32_16x16x32_bf16 v[14:17], v[130:133], v[186:189], v[14:17]
	v_mfma_f32_16x16x32_bf16 v[14:17], v[134:137], v[190:193], v[14:17]
	s_setprio 0
	s_barrier
; #define PG8_STAGE(bufoff, gbase, voff) do { _Pragma("unroll") for (int _i = 0; _i < 2; ++_i) { \
;         const unsigned _m0 = ldsb + (unsigned)((bufoff) + _i * 8192); const char* _gb = (const char*)(gbase); \
;         asm volatile("s_mov_b32 m0, %0\n\ts_nop 0\n\tglobal_load_lds_dwordx4 %1, %2" :: "s"(_m0), "v"((voff)[_i]), "s"(_gb) : "m0", "memory"); } } while (0)
; #define PG8_LDA(dst, b, h) do { _Pragma("unroll") for (int m = 0; m < 4; ++m) _Pragma("unroll") for (int k = 0; k < 2; ++k) dst[m][k] = *(const LAS bf16x8*)(lds + PG8_SA(b, h) + aoff + m * 2048 + k * 1024); } while (0)
; #define PG8_LDB(dst, b, h) do { _Pragma("unroll") for (int n = 0; n < 2; ++n) _Pragma("unroll") for (int k = 0; k < 2; ++k) dst[n][k] = *(const LAS bf16x8*)(lds + PG8_SB(b, h) + boff + n * 2048 + k * 1024); } while (0)
; #define PG8_MMA(ai, bj, At, Bt) do { __builtin_amdgcn_s_setprio(1); _Pragma("unroll") for (int m = 0; m < 4; ++m) _Pragma("unroll") for (int n = 0; n < 2; ++n) _Pragma("unroll") for (int k = 0; k < 2; ++k) \
;         acc[ai][bj][m][n] = __builtin_amdgcn_mfma_f32_16x16x32_bf16(Bt[n][k], At[m][k], acc[ai][bj][m][n], 0, 0, 0); __builtin_amdgcn_s_setprio(0); } while (0)
; #define PG8_WAIT_V(n) asm volatile("s_waitcnt vmcnt(" #n ")" ::: "memory")
; #define PG8_WAIT_L(n) asm volatile("s_waitcnt lgkmcnt(" #n ")" ::: "memory")
; #define PG8_BAR __builtin_amdgcn_s_barrier()
; #define PG8_SCHED __builtin_amdgcn_sched_barrier(0)
; template <class Epi, bool ALIGN_EPI>
; __device__ __forceinline__ void gemm_phase(LAS unsigned char* lds, const Gemm g, const StaticOrder& S, const Epi& E) {
;     ...
;             PG8_LDB(B0, 1, 0); PG8_LDB(B1, 1, 1); PG8_SCHED; PG8_LDA(At, 1, 0); PG8_STAGE(PG8_SA(0, 1), a2 + hstepA, voffA);
;             PG8_WAIT_V(8); PG8_WAIT_L(0); PG8_BAR; PG8_MMA(0, 0, At, B0); PG8_MMA(0, 1, At, B1); PG8_BAR; PG8_SCHED;
;             PG8_LDA(At, 1, 1); PG8_STAGE(PG8_SB(1, 0), b3, voffB); PG8_STAGE(PG8_SB(1, 1), b3 + hstepB, voffB); PG8_STAGE(PG8_SA(1, 0), a3, voffA);
;             PG8_WAIT_V(8); PG8_WAIT_L(0); PG8_BAR; PG8_MMA(1, 0, At, B0); PG8_MMA(1, 1, At, B1); PG8_BAR; PG8_SCHED;
;         }
;         if constexpr (ALIGN_EPI) { if (wr == 0) PG8_BAR; }
	v_add_u32_e32 v142, 0x18000, v245
	v_add_u32_e32 v158, 0x1c000, v245
	ds_read_b128 v[130:133], v142
	ds_read_b128 v[134:137], v142 offset:1024
	ds_read_b128 v[138:141], v142 offset:2048
	ds_read_b128 v[142:145], v142 offset:3072
	ds_read_b128 v[146:149], v158
	ds_read_b128 v[150:153], v158 offset:1024
	ds_read_b128 v[154:157], v158 offset:2048
	ds_read_b128 v[158:161], v158 offset:3072
	ds_read_b128 v[162:165], v246 offset:32768
	ds_read_b128 v[166:169], v246 offset:33792
	ds_read_b128 v[170:173], v246 offset:34816
	ds_read_b128 v[174:177], v246 offset:35840
	ds_read_b128 v[178:181], v246 offset:36864
	ds_read_b128 v[182:185], v246 offset:37888
	ds_read_b128 v[186:189], v246 offset:38912
	ds_read_b128 v[190:193], v246 offset:39936
	s_add_u32 s56, s56, s38
	s_addc_u32 s57, s57, 0
	s_mov_b32 m0, s31
	s_nop 0
	global_load_lds_dwordx4 v0, s[56:57]
	s_nop 0
	s_mov_b32 m0, s53
	s_nop 0
	global_load_lds_dwordx4 v206, s[56:57]
	s_waitcnt vmcnt(8)
	s_waitcnt lgkmcnt(0)
	s_barrier
	s_setprio 1
	s_waitcnt lgkmcnt(0)
	v_mfma_f32_16x16x32_bf16 v[126:129], v[130:133], v[162:165], v[126:129]
	v_mfma_f32_16x16x32_bf16 v[126:129], v[134:137], v[166:169], v[126:129]
	v_mfma_f32_16x16x32_bf16 v[122:125], v[138:141], v[162:165], v[122:125]
	v_mfma_f32_16x16x32_bf16 v[122:125], v[142:145], v[166:169], v[122:125]
	v_mfma_f32_16x16x32_bf16 v[118:121], v[146:149], v[162:165], v[118:121]
	v_mfma_f32_16x16x32_bf16 v[118:121], v[150:153], v[166:169], v[118:121]
	v_mfma_f32_16x16x32_bf16 v[114:117], v[154:157], v[162:165], v[114:117]
	v_mfma_f32_16x16x32_bf16 v[114:117], v[158:161], v[166:169], v[114:117]
	v_mfma_f32_16x16x32_bf16 v[98:101], v[154:157], v[170:173], v[98:101]
	v_mfma_f32_16x16x32_bf16 v[98:101], v[158:161], v[174:177], v[98:101]
	v_mfma_f32_16x16x32_bf16 v[102:105], v[146:149], v[170:173], v[102:105]
	v_mfma_f32_16x16x32_bf16 v[102:105], v[150:153], v[174:177], v[102:105]
	v_mfma_f32_16x16x32_bf16 v[106:109], v[138:141], v[170:173], v[106:109]
	v_mfma_f32_16x16x32_bf16 v[106:109], v[142:145], v[174:177], v[106:109]
	v_mfma_f32_16x16x32_bf16 v[110:113], v[130:133], v[170:173], v[110:113]
	v_mfma_f32_16x16x32_bf16 v[110:113], v[134:137], v[174:177], v[110:113]
	v_mfma_f32_16x16x32_bf16 v[94:97], v[130:133], v[178:181], v[94:97]
	v_mfma_f32_16x16x32_bf16 v[94:97], v[134:137], v[182:185], v[94:97]
	v_mfma_f32_16x16x32_bf16 v[90:93], v[138:141], v[178:181], v[90:93]
	v_mfma_f32_16x16x32_bf16 v[90:93], v[142:145], v[182:185], v[90:93]
	v_mfma_f32_16x16x32_bf16 v[86:89], v[146:149], v[178:181], v[86:89]
	v_mfma_f32_16x16x32_bf16 v[86:89], v[150:153], v[182:185], v[86:89]
	v_mfma_f32_16x16x32_bf16 v[82:85], v[154:157], v[178:181], v[82:85]
	v_mfma_f32_16x16x32_bf16 v[82:85], v[158:161], v[182:185], v[82:85]
	v_mfma_f32_16x16x32_bf16 v[66:69], v[154:157], v[186:189], v[66:69]
	v_mfma_f32_16x16x32_bf16 v[66:69], v[158:161], v[190:193], v[66:69]
	v_mfma_f32_16x16x32_bf16 v[70:73], v[146:149], v[186:189], v[70:73]
	v_mfma_f32_16x16x32_bf16 v[70:73], v[150:153], v[190:193], v[70:73]
	v_mfma_f32_16x16x32_bf16 v[74:77], v[138:141], v[186:189], v[74:77]
	v_mfma_f32_16x16x32_bf16 v[74:77], v[142:145], v[190:193], v[74:77]
	v_mfma_f32_16x16x32_bf16 v[78:81], v[130:133], v[186:189], v[78:81]
	v_mfma_f32_16x16x32_bf16 v[78:81], v[134:137], v[190:193], v[78:81]
	s_setprio 0
	s_barrier
	ds_read_b128 v[162:165], v246 offset:49152
	ds_read_b128 v[166:169], v246 offset:50176
	ds_read_b128 v[170:173], v246 offset:51200
	ds_read_b128 v[174:177], v246 offset:52224
	ds_read_b128 v[178:181], v246 offset:53248
	ds_read_b128 v[182:185], v246 offset:54272
	ds_read_b128 v[186:189], v246 offset:55296
	ds_read_b128 v[190:193], v246 offset:56320
	s_add_u32 s54, s54, 0x80
	s_addc_u32 s55, s55, 0
	s_mov_b32 m0, s85
	s_nop 0
	global_load_lds_dwordx4 v195, s[54:55]
	s_nop 0
	s_mov_b32 m0, s65
	s_nop 0
	global_load_lds_dwordx4 v207, s[54:55]
	s_add_u32 s54, s58, 0x80
	s_addc_u32 s55, s59, 0
	s_mov_b32 m0, s93
	s_nop 0
	global_load_lds_dwordx4 v195, s[54:55]
	s_nop 0
	s_mov_b32 m0, s28
	s_nop 0
	global_load_lds_dwordx4 v207, s[54:55]
	s_nop 0
	s_mov_b32 m0, s67
	s_nop 0
	global_load_lds_dwordx4 v0, s[48:49]
	s_nop 0
	s_mov_b32 m0, s92
	s_nop 0
	global_load_lds_dwordx4 v206, s[48:49]
	s_waitcnt vmcnt(8)
	s_waitcnt lgkmcnt(0)
	s_barrier
	s_setprio 1
	s_waitcnt lgkmcnt(0)
	v_mfma_f32_16x16x32_bf16 v[62:65], v[130:133], v[162:165], v[62:65]
	v_mfma_f32_16x16x32_bf16 v[62:65], v[134:137], v[166:169], v[62:65]
	v_mfma_f32_16x16x32_bf16 v[58:61], v[138:141], v[162:165], v[58:61]
	v_mfma_f32_16x16x32_bf16 v[58:61], v[142:145], v[166:169], v[58:61]
	v_mfma_f32_16x16x32_bf16 v[54:57], v[146:149], v[162:165], v[54:57]
	v_mfma_f32_16x16x32_bf16 v[54:57], v[150:153], v[166:169], v[54:57]
	v_mfma_f32_16x16x32_bf16 v[50:53], v[154:157], v[162:165], v[50:53]
	v_mfma_f32_16x16x32_bf16 v[50:53], v[158:161], v[166:169], v[50:53]
	v_mfma_f32_16x16x32_bf16 v[34:37], v[154:157], v[170:173], v[34:37]
	v_mfma_f32_16x16x32_bf16 v[34:37], v[158:161], v[174:177], v[34:37]
	v_mfma_f32_16x16x32_bf16 v[38:41], v[146:149], v[170:173], v[38:41]
	v_mfma_f32_16x16x32_bf16 v[38:41], v[150:153], v[174:177], v[38:41]
	v_mfma_f32_16x16x32_bf16 v[42:45], v[138:141], v[170:173], v[42:45]
	v_mfma_f32_16x16x32_bf16 v[42:45], v[142:145], v[174:177], v[42:45]
	v_mfma_f32_16x16x32_bf16 v[46:49], v[130:133], v[170:173], v[46:49]
	v_mfma_f32_16x16x32_bf16 v[46:49], v[134:137], v[174:177], v[46:49]
	v_mfma_f32_16x16x32_bf16 v[30:33], v[130:133], v[178:181], v[30:33]
	v_mfma_f32_16x16x32_bf16 v[30:33], v[134:137], v[182:185], v[30:33]
	v_mfma_f32_16x16x32_bf16 v[26:29], v[138:141], v[178:181], v[26:29]
	v_mfma_f32_16x16x32_bf16 v[26:29], v[142:145], v[182:185], v[26:29]
	v_mfma_f32_16x16x32_bf16 v[22:25], v[146:149], v[178:181], v[22:25]
	v_mfma_f32_16x16x32_bf16 v[22:25], v[150:153], v[182:185], v[22:25]
	v_mfma_f32_16x16x32_bf16 v[18:21], v[154:157], v[178:181], v[18:21]
	v_mfma_f32_16x16x32_bf16 v[18:21], v[158:161], v[182:185], v[18:21]
	v_mfma_f32_16x16x32_bf16 v[2:5], v[154:157], v[186:189], v[2:5]
	v_mfma_f32_16x16x32_bf16 v[2:5], v[158:161], v[190:193], v[2:5]
	v_mfma_f32_16x16x32_bf16 v[6:9], v[146:149], v[186:189], v[6:9]
	v_mfma_f32_16x16x32_bf16 v[6:9], v[150:153], v[190:193], v[6:9]
	v_mfma_f32_16x16x32_bf16 v[10:13], v[138:141], v[186:189], v[10:13]
	v_mfma_f32_16x16x32_bf16 v[10:13], v[142:145], v[190:193], v[10:13]
	v_mfma_f32_16x16x32_bf16 v[14:17], v[130:133], v[186:189], v[14:17]
	v_mfma_f32_16x16x32_bf16 v[14:17], v[134:137], v[190:193], v[14:17]
	s_setprio 0
	s_add_u32 s4, s4, 0x100
	s_addc_u32 s5, s5, 0
	s_add_u32 s15, s15, 0x100
	s_addc_u32 s42, s42, 0
	s_cmp_ge_u32 s44, s36
	s_mov_b32 s43, s44
	s_barrier
	s_cbranch_scc0 .LBB0_201
	v_readlane_b32 s4, v255, 6
	v_readlane_b32 s5, v255, 7
	s_and_b64 vcc, exec, s[4:5]
	s_cbranch_vccz .LBB0_204
	s_barrier

; #define PG8_STAGE(bufoff, gbase, voff) do { _Pragma("unroll") for (int _i = 0; _i < 2; ++_i) { \
;         const unsigned _m0 = ldsb + (unsigned)((bufoff) + _i * 8192); const char* _gb = (const char*)(gbase); \
;         asm volatile("s_mov_b32 m0, %0\n\ts_nop 0\n\tglobal_load_lds_dwordx4 %1, %2" :: "s"(_m0), "v"((voff)[_i]), "s"(_gb) : "m0", "memory"); } } while (0)
; #define PG8_LDA(dst, b, h) do { _Pragma("unroll") for (int m = 0; m < 4; ++m) _Pragma("unroll") for (int k = 0; k < 2; ++k) dst[m][k] = *(const LAS bf16x8*)(lds + PG8_SA(b, h) + aoff + m * 2048 + k * 1024); } while (0)
; #define PG8_LDB(dst, b, h) do { _Pragma("unroll") for (int n = 0; n < 2; ++n) _Pragma("unroll") for (int k = 0; k < 2; ++k) dst[n][k] = *(const LAS bf16x8*)(lds + PG8_SB(b, h) + boff + n * 2048 + k * 1024); } while (0)
; #define PG8_MMA(ai, bj, At, Bt) do { __builtin_amdgcn_s_setprio(1); _Pragma("unroll") for (int m = 0; m < 4; ++m) _Pragma("unroll") for (int n = 0; n < 2; ++n) _Pragma("unroll") for (int k = 0; k < 2; ++k) \
;         acc[ai][bj][m][n] = __builtin_amdgcn_mfma_f32_16x16x32_bf16(Bt[n][k], At[m][k], acc[ai][bj][m][n], 0, 0, 0); __builtin_amdgcn_s_setprio(0); } while (0)
; #define PG8_WAIT_V(n) asm volatile("s_waitcnt vmcnt(" #n ")" ::: "memory")
; #define PG8_WAIT_L(n) asm volatile("s_waitcnt lgkmcnt(" #n ")" ::: "memory")
; template <class Epi, bool ALIGN_EPI>
; __device__ __forceinline__ void gemm_phase(LAS unsigned char* lds, const Gemm g, const StaticOrder& S, const Epi& E) {
;     ...
;         for (int t = 0; t < nt; t += 2) {
;             const bool last = (t == nt - 2);
;             const char* a1 = cA + (size_t)(t + 1) * kstep;
;             const char* a2 = last ? nA : cA + (size_t)(t + 2) * kstep; const char* b2 = last ? nB : cB + (size_t)(t + 2) * kstep;
;             const char* a3 = a2 + kstep; const char* b3 = b2 + kstep;
;             PG8_LDB(B0, 0, 0); PG8_LDB(B1, 0, 1); PG8_SCHED; PG8_LDA(At, 0, 0); PG8_STAGE(PG8_SA(1, 1), a1 + hstepA, voffA);
;             PG8_WAIT_V(8); PG8_WAIT_L(0); PG8_BAR; PG8_MMA(0, 0, At, B0); PG8_MMA(0, 1, At, B1); PG8_BAR; PG8_SCHED;
;             PG8_LDA(At, 0, 1); PG8_STAGE(PG8_SB(0, 0), b2, voffB); PG8_STAGE(PG8_SB(0, 1), b2 + hstepB, voffB); PG8_STAGE(PG8_SA(0, 0), a2, voffA);
;             PG8_WAIT_V(8); PG8_WAIT_L(0); PG8_BAR; PG8_MMA(1, 0, At, B0); PG8_MMA(1, 1, At, B1); PG8_BAR; PG8_SCHED;
.LBB0_270:
	s_add_u32 s4, s56, 0x100
	s_addc_u32 s5, s57, 0
	s_add_u32 s0, s58, 0x40080
	s_addc_u32 s1, s59, 0
	s_mov_b32 s44, 0
	s_add_i32 s55, s44, 2
	s_add_u32 s45, s0, 0xfffc0080
	s_addc_u32 s56, s1, -1
	s_cmp_eq_u32 s68, s44
	s_cselect_b32 s60, s96, s45
	s_cselect_b32 s61, s97, s56
	s_cselect_b32 s58, s48, s4
	s_cselect_b32 s59, s49, s5
	s_add_u32 s56, s60, 0x80
	s_addc_u32 s57, s61, 0
	s_mov_b32 m0, s41
	s_nop 0
	global_load_lds_dwordx4 v165, s[0:1]
	s_nop 0
	s_mov_b32 m0, s30
	s_nop 0
	global_load_lds_dwordx4 v171, s[0:1]
	s_waitcnt vmcnt(8)
	s_waitcnt lgkmcnt(0)
	s_barrier
	s_setprio 1
	s_waitcnt lgkmcnt(0)
	v_mfma_f32_16x16x32_bf16 v[126:129], v[130:133], v[182:185], 0
	v_mfma_f32_16x16x32_bf16 v[126:129], v[134:137], v[186:189], v[126:129]
	v_mfma_f32_16x16x32_bf16 v[122:125], v[138:141], v[182:185], 0
	v_mfma_f32_16x16x32_bf16 v[122:125], v[142:145], v[186:189], v[122:125]
	v_mfma_f32_16x16x32_bf16 v[118:121], v[146:149], v[182:185], 0
	v_mfma_f32_16x16x32_bf16 v[118:121], v[150:153], v[186:189], v[118:121]
	v_mfma_f32_16x16x32_bf16 v[110:113], v[154:157], v[182:185], 0
	v_mfma_f32_16x16x32_bf16 v[110:113], v[158:161], v[186:189], v[110:113]
	v_mfma_f32_16x16x32_bf16 v[94:97], v[154:157], v[190:193], 0
	v_mfma_f32_16x16x32_bf16 v[94:97], v[158:161], v[202:205], v[94:97]
	v_mfma_f32_16x16x32_bf16 v[102:105], v[146:149], v[190:193], 0
	v_mfma_f32_16x16x32_bf16 v[102:105], v[150:153], v[202:205], v[102:105]
	v_mfma_f32_16x16x32_bf16 v[106:109], v[138:141], v[190:193], 0
	v_mfma_f32_16x16x32_bf16 v[106:109], v[142:145], v[202:205], v[106:109]
	v_mfma_f32_16x16x32_bf16 v[114:117], v[130:133], v[190:193], 0
	v_mfma_f32_16x16x32_bf16 v[114:117], v[134:137], v[202:205], v[114:117]
	v_mfma_f32_16x16x32_bf16 v[98:101], v[130:133], v[206:209], 0
	v_mfma_f32_16x16x32_bf16 v[98:101], v[134:137], v[210:213], v[98:101]
	v_mfma_f32_16x16x32_bf16 v[90:93], v[138:141], v[206:209], 0
	v_mfma_f32_16x16x32_bf16 v[90:93], v[142:145], v[210:213], v[90:93]
	v_mfma_f32_16x16x32_bf16 v[86:89], v[146:149], v[206:209], 0
	v_mfma_f32_16x16x32_bf16 v[86:89], v[150:153], v[210:213], v[86:89]
	v_mfma_f32_16x16x32_bf16 v[78:81], v[154:157], v[206:209], 0
	v_mfma_f32_16x16x32_bf16 v[78:81], v[158:161], v[210:213], v[78:81]
	v_mfma_f32_16x16x32_bf16 v[66:69], v[154:157], v[214:217], 0
	v_mfma_f32_16x16x32_bf16 v[66:69], v[158:161], v[240:243], v[66:69]
	v_mfma_f32_16x16x32_bf16 v[70:73], v[146:149], v[214:217], 0
	v_mfma_f32_16x16x32_bf16 v[70:73], v[150:153], v[240:243], v[70:73]
	v_mfma_f32_16x16x32_bf16 v[74:77], v[138:141], v[214:217], 0
	v_mfma_f32_16x16x32_bf16 v[74:77], v[142:145], v[240:243], v[74:77]
	v_mfma_f32_16x16x32_bf16 v[82:85], v[130:133], v[214:217], 0
	v_mfma_f32_16x16x32_bf16 v[82:85], v[134:137], v[240:243], v[82:85]
	s_setprio 0
	s_barrier
	ds_read_b128 v[182:185], v180 offset:16384
	ds_read_b128 v[186:189], v180 offset:17408
	ds_read_b128 v[190:193], v180 offset:18432
	ds_read_b128 v[202:205], v180 offset:19456
	ds_read_b128 v[206:209], v180 offset:20480
	ds_read_b128 v[210:213], v180 offset:21504
	ds_read_b128 v[214:217], v180 offset:22528
	ds_read_b128 v[240:243], v180 offset:23552
	s_mov_b32 m0, s42
	s_nop 0
	global_load_lds_dwordx4 v167, s[58:59]
	s_add_u32 s44, s58, s14
	s_mov_b32 m0, s43
	s_nop 0
	global_load_lds_dwordx4 v175, s[58:59]
	s_addc_u32 s45, s59, 0
	s_mov_b32 m0, s46
	s_nop 0
	global_load_lds_dwordx4 v167, s[44:45]
	s_nop 0
	s_mov_b32 m0, s50
	s_nop 0
	global_load_lds_dwordx4 v175, s[44:45]
	s_nop 0
	s_mov_b32 m0, s17
	s_nop 0
	global_load_lds_dwordx4 v165, s[60:61]
	s_nop 0
	s_mov_b32 m0, s53
	s_nop 0
	global_load_lds_dwordx4 v171, s[60:61]
	s_waitcnt vmcnt(8)
	s_waitcnt lgkmcnt(0)
	s_barrier
	s_setprio 1
	s_waitcnt lgkmcnt(0)
	v_mfma_f32_16x16x32_bf16 v[62:65], v[130:133], v[182:185], 0
	v_mfma_f32_16x16x32_bf16 v[62:65], v[134:137], v[186:189], v[62:65]
	v_mfma_f32_16x16x32_bf16 v[58:61], v[138:141], v[182:185], 0
	v_mfma_f32_16x16x32_bf16 v[58:61], v[142:145], v[186:189], v[58:61]
	v_mfma_f32_16x16x32_bf16 v[54:57], v[146:149], v[182:185], 0
	v_mfma_f32_16x16x32_bf16 v[54:57], v[150:153], v[186:189], v[54:57]
	v_mfma_f32_16x16x32_bf16 v[50:53], v[154:157], v[182:185], 0
	v_mfma_f32_16x16x32_bf16 v[50:53], v[158:161], v[186:189], v[50:53]
	v_mfma_f32_16x16x32_bf16 v[30:33], v[154:157], v[190:193], 0
	v_mfma_f32_16x16x32_bf16 v[30:33], v[158:161], v[202:205], v[30:33]
	v_mfma_f32_16x16x32_bf16 v[38:41], v[146:149], v[190:193], 0
	v_mfma_f32_16x16x32_bf16 v[38:41], v[150:153], v[202:205], v[38:41]
	v_mfma_f32_16x16x32_bf16 v[42:45], v[138:141], v[190:193], 0
	v_mfma_f32_16x16x32_bf16 v[42:45], v[142:145], v[202:205], v[42:45]
	v_mfma_f32_16x16x32_bf16 v[46:49], v[130:133], v[190:193], 0
	v_mfma_f32_16x16x32_bf16 v[46:49], v[134:137], v[202:205], v[46:49]
	v_mfma_f32_16x16x32_bf16 v[34:37], v[130:133], v[206:209], 0
	v_mfma_f32_16x16x32_bf16 v[34:37], v[134:137], v[210:213], v[34:37]
	v_mfma_f32_16x16x32_bf16 v[26:29], v[138:141], v[206:209], 0
	v_mfma_f32_16x16x32_bf16 v[26:29], v[142:145], v[210:213], v[26:29]
	v_mfma_f32_16x16x32_bf16 v[22:25], v[146:149], v[206:209], 0
	v_mfma_f32_16x16x32_bf16 v[22:25], v[150:153], v[210:213], v[22:25]
	v_mfma_f32_16x16x32_bf16 v[14:17], v[154:157], v[206:209], 0
	v_mfma_f32_16x16x32_bf16 v[14:17], v[158:161], v[210:213], v[14:17]
	v_mfma_f32_16x16x32_bf16 v[2:5], v[154:157], v[214:217], 0
	v_mfma_f32_16x16x32_bf16 v[2:5], v[158:161], v[240:243], v[2:5]
	v_mfma_f32_16x16x32_bf16 v[6:9], v[146:149], v[214:217], 0
	v_mfma_f32_16x16x32_bf16 v[6:9], v[150:153], v[240:243], v[6:9]
	v_mfma_f32_16x16x32_bf16 v[10:13], v[138:141], v[214:217], 0
	v_mfma_f32_16x16x32_bf16 v[10:13], v[142:145], v[240:243], v[10:13]
	v_mfma_f32_16x16x32_bf16 v[18:21], v[130:133], v[214:217], 0
	v_mfma_f32_16x16x32_bf16 v[18:21], v[134:137], v[240:243], v[18:21]
	s_setprio 0
	s_barrier
; #define PG8_STAGE(bufoff, gbase, voff) do { _Pragma("unroll") for (int _i = 0; _i < 2; ++_i) { \
;         const unsigned _m0 = ldsb + (unsigned)((bufoff) + _i * 8192); const char* _gb = (const char*)(gbase); \
;         asm volatile("s_mov_b32 m0, %0\n\ts_nop 0\n\tglobal_load_lds_dwordx4 %1, %2" :: "s"(_m0), "v"((voff)[_i]), "s"(_gb) : "m0", "memory"); } } while (0)
; #define PG8_LDA(dst, b, h) do { _Pragma("unroll") for (int m = 0; m < 4; ++m) _Pragma("unroll") for (int k = 0; k < 2; ++k) dst[m][k] = *(const LAS bf16x8*)(lds + PG8_SA(b, h) + aoff + m * 2048 + k * 1024); } while (0)
; #define PG8_LDB(dst, b, h) do { _Pragma("unroll") for (int n = 0; n < 2; ++n) _Pragma("unroll") for (int k = 0; k < 2; ++k) dst[n][k] = *(const LAS bf16x8*)(lds + PG8_SB(b, h) + boff + n * 2048 + k * 1024); } while (0)
; #define PG8_MMA(ai, bj, At, Bt) do { __builtin_amdgcn_s_setprio(1); _Pragma("unroll") for (int m = 0; m < 4; ++m) _Pragma("unroll") for (int n = 0; n < 2; ++n) _Pragma("unroll") for (int k = 0; k < 2; ++k) \
;         acc[ai][bj][m][n] = __builtin_amdgcn_mfma_f32_16x16x32_bf16(Bt[n][k], At[m][k], acc[ai][bj][m][n], 0, 0, 0); __builtin_amdgcn_s_setprio(0); } while (0)
; #define PG8_WAIT_V(n) asm volatile("s_waitcnt vmcnt(" #n ")" ::: "memory")
; #define PG8_WAIT_L(n) asm volatile("s_waitcnt lgkmcnt(" #n ")" ::: "memory")
; #define PG8_BAR __builtin_amdgcn_s_barrier()
; #define PG8_SCHED __builtin_amdgcn_sched_barrier(0)
; template <class Epi, bool ALIGN_EPI>
; __device__ __forceinline__ void gemm_phase(LAS unsigned char* lds, const Gemm g, const StaticOrder& S, const Epi& E) {
;     ...
;             PG8_LDB(B0, 1, 0); PG8_LDB(B1, 1, 1); PG8_SCHED; PG8_LDA(At, 1, 0); PG8_STAGE(PG8_SA(0, 1), a2 + hstepA, voffA);
;             PG8_WAIT_V(8); PG8_WAIT_L(0); PG8_BAR; PG8_MMA(0, 0, At, B0); PG8_MMA(0, 1, At, B1); PG8_BAR; PG8_SCHED;
;             PG8_LDA(At, 1, 1); PG8_STAGE(PG8_SB(1, 0), b3, voffB); PG8_STAGE(PG8_SB(1, 1), b3 + hstepB, voffB); PG8_STAGE(PG8_SA(1, 0), a3, voffA);
;             PG8_WAIT_V(8); PG8_WAIT_L(0); PG8_BAR; PG8_MMA(1, 0, At, B0); PG8_MMA(1, 1, At, B1); PG8_BAR; PG8_SCHED;
;         }
	v_add_u32_e32 v0, 0x18000, v179
	ds_read_b128 v[130:133], v0
	ds_read_b128 v[134:137], v0 offset:1024
	ds_read_b128 v[138:141], v0 offset:2048
	ds_read_b128 v[142:145], v0 offset:3072
	v_add_u32_e32 v0, 0x1c000, v179
	ds_read_b128 v[146:149], v0
	ds_read_b128 v[150:153], v0 offset:1024
	ds_read_b128 v[154:157], v0 offset:2048
	ds_read_b128 v[158:161], v0 offset:3072
	ds_read_b128 v[182:185], v180 offset:32768
	ds_read_b128 v[186:189], v180 offset:33792
	ds_read_b128 v[190:193], v180 offset:34816
	ds_read_b128 v[202:205], v180 offset:35840
	ds_read_b128 v[206:209], v180 offset:36864
	ds_read_b128 v[210:213], v180 offset:37888
	ds_read_b128 v[214:217], v180 offset:38912
	ds_read_b128 v[240:243], v180 offset:39936
	s_add_u32 s60, s60, 0x40000
	s_addc_u32 s61, s61, 0
	s_mov_b32 m0, s65
	s_nop 0
	global_load_lds_dwordx4 v165, s[60:61]
	s_nop 0
	s_mov_b32 m0, s67
	s_nop 0
	global_load_lds_dwordx4 v171, s[60:61]
	s_waitcnt vmcnt(8)
	s_waitcnt lgkmcnt(0)
	s_barrier
	s_setprio 1
	s_waitcnt lgkmcnt(0)
	v_mfma_f32_16x16x32_bf16 v[126:129], v[130:133], v[182:185], v[126:129]
	v_mfma_f32_16x16x32_bf16 v[126:129], v[134:137], v[186:189], v[126:129]
	v_mfma_f32_16x16x32_bf16 v[122:125], v[138:141], v[182:185], v[122:125]
	v_mfma_f32_16x16x32_bf16 v[122:125], v[142:145], v[186:189], v[122:125]
	v_mfma_f32_16x16x32_bf16 v[118:121], v[146:149], v[182:185], v[118:121]
	v_mfma_f32_16x16x32_bf16 v[118:121], v[150:153], v[186:189], v[118:121]
	v_mfma_f32_16x16x32_bf16 v[110:113], v[154:157], v[182:185], v[110:113]
	v_mfma_f32_16x16x32_bf16 v[110:113], v[158:161], v[186:189], v[110:113]
	v_mfma_f32_16x16x32_bf16 v[94:97], v[154:157], v[190:193], v[94:97]
	v_mfma_f32_16x16x32_bf16 v[94:97], v[158:161], v[202:205], v[94:97]
	v_mfma_f32_16x16x32_bf16 v[102:105], v[146:149], v[190:193], v[102:105]
	v_mfma_f32_16x16x32_bf16 v[102:105], v[150:153], v[202:205], v[102:105]
	v_mfma_f32_16x16x32_bf16 v[106:109], v[138:141], v[190:193], v[106:109]
	v_mfma_f32_16x16x32_bf16 v[106:109], v[142:145], v[202:205], v[106:109]
	v_mfma_f32_16x16x32_bf16 v[114:117], v[130:133], v[190:193], v[114:117]
	v_mfma_f32_16x16x32_bf16 v[114:117], v[134:137], v[202:205], v[114:117]
	v_mfma_f32_16x16x32_bf16 v[98:101], v[130:133], v[206:209], v[98:101]
	v_mfma_f32_16x16x32_bf16 v[98:101], v[134:137], v[210:213], v[98:101]
	v_mfma_f32_16x16x32_bf16 v[90:93], v[138:141], v[206:209], v[90:93]
	v_mfma_f32_16x16x32_bf16 v[90:93], v[142:145], v[210:213], v[90:93]
	v_mfma_f32_16x16x32_bf16 v[86:89], v[146:149], v[206:209], v[86:89]
	v_mfma_f32_16x16x32_bf16 v[86:89], v[150:153], v[210:213], v[86:89]
	v_mfma_f32_16x16x32_bf16 v[78:81], v[154:157], v[206:209], v[78:81]
	v_mfma_f32_16x16x32_bf16 v[78:81], v[158:161], v[210:213], v[78:81]
	v_mfma_f32_16x16x32_bf16 v[66:69], v[154:157], v[214:217], v[66:69]
	v_mfma_f32_16x16x32_bf16 v[66:69], v[158:161], v[240:243], v[66:69]
	v_mfma_f32_16x16x32_bf16 v[70:73], v[146:149], v[214:217], v[70:73]
	v_mfma_f32_16x16x32_bf16 v[70:73], v[150:153], v[240:243], v[70:73]
	v_mfma_f32_16x16x32_bf16 v[74:77], v[138:141], v[214:217], v[74:77]
	v_mfma_f32_16x16x32_bf16 v[74:77], v[142:145], v[240:243], v[74:77]
	v_mfma_f32_16x16x32_bf16 v[82:85], v[130:133], v[214:217], v[82:85]
	v_mfma_f32_16x16x32_bf16 v[82:85], v[134:137], v[240:243], v[82:85]
	s_setprio 0
	s_barrier
	ds_read_b128 v[182:185], v180 offset:49152
	ds_read_b128 v[186:189], v180 offset:50176
	ds_read_b128 v[190:193], v180 offset:51200
	ds_read_b128 v[202:205], v180 offset:52224
	ds_read_b128 v[206:209], v180 offset:53248
	ds_read_b128 v[210:213], v180 offset:54272
	ds_read_b128 v[214:217], v180 offset:55296
	ds_read_b128 v[240:243], v180 offset:56320
	s_add_u32 s58, s58, 0x80
	s_addc_u32 s59, s59, 0
	s_mov_b32 m0, s89
	s_nop 0
	global_load_lds_dwordx4 v167, s[58:59]
	s_add_u32 s44, s44, 0x80
	s_mov_b32 m0, s95
	s_nop 0
	global_load_lds_dwordx4 v175, s[58:59]
	s_addc_u32 s45, s45, 0
	s_mov_b32 m0, s26
	s_nop 0
	global_load_lds_dwordx4 v167, s[44:45]
	s_nop 0
	s_mov_b32 m0, s27
	s_nop 0
	global_load_lds_dwordx4 v175, s[44:45]
	s_nop 0
	s_mov_b32 m0, s36
	s_nop 0
	global_load_lds_dwordx4 v165, s[56:57]
	s_nop 0
	s_mov_b32 m0, s37
	s_nop 0
	global_load_lds_dwordx4 v171, s[56:57]
	s_waitcnt vmcnt(8)
	s_waitcnt lgkmcnt(0)
	s_barrier
	s_setprio 1
	s_waitcnt lgkmcnt(0)
	v_mfma_f32_16x16x32_bf16 v[62:65], v[130:133], v[182:185], v[62:65]
	v_mfma_f32_16x16x32_bf16 v[62:65], v[134:137], v[186:189], v[62:65]
	v_mfma_f32_16x16x32_bf16 v[58:61], v[138:141], v[182:185], v[58:61]
	v_mfma_f32_16x16x32_bf16 v[58:61], v[142:145], v[186:189], v[58:61]
	v_mfma_f32_16x16x32_bf16 v[54:57], v[146:149], v[182:185], v[54:57]
	v_mfma_f32_16x16x32_bf16 v[54:57], v[150:153], v[186:189], v[54:57]
	v_mfma_f32_16x16x32_bf16 v[50:53], v[154:157], v[182:185], v[50:53]
	v_mfma_f32_16x16x32_bf16 v[50:53], v[158:161], v[186:189], v[50:53]
	v_mfma_f32_16x16x32_bf16 v[30:33], v[154:157], v[190:193], v[30:33]
	v_mfma_f32_16x16x32_bf16 v[30:33], v[158:161], v[202:205], v[30:33]
	v_mfma_f32_16x16x32_bf16 v[38:41], v[146:149], v[190:193], v[38:41]
	v_mfma_f32_16x16x32_bf16 v[38:41], v[150:153], v[202:205], v[38:41]
	v_mfma_f32_16x16x32_bf16 v[42:45], v[138:141], v[190:193], v[42:45]
	v_mfma_f32_16x16x32_bf16 v[42:45], v[142:145], v[202:205], v[42:45]
	v_mfma_f32_16x16x32_bf16 v[46:49], v[130:133], v[190:193], v[46:49]
	v_mfma_f32_16x16x32_bf16 v[46:49], v[134:137], v[202:205], v[46:49]
	v_mfma_f32_16x16x32_bf16 v[34:37], v[130:133], v[206:209], v[34:37]
	v_mfma_f32_16x16x32_bf16 v[34:37], v[134:137], v[210:213], v[34:37]
	v_mfma_f32_16x16x32_bf16 v[26:29], v[138:141], v[206:209], v[26:29]
	v_mfma_f32_16x16x32_bf16 v[26:29], v[142:145], v[210:213], v[26:29]
	v_mfma_f32_16x16x32_bf16 v[22:25], v[146:149], v[206:209], v[22:25]
	v_mfma_f32_16x16x32_bf16 v[22:25], v[150:153], v[210:213], v[22:25]
	v_mfma_f32_16x16x32_bf16 v[14:17], v[154:157], v[206:209], v[14:17]
	v_mfma_f32_16x16x32_bf16 v[14:17], v[158:161], v[210:213], v[14:17]
	v_mfma_f32_16x16x32_bf16 v[2:5], v[154:157], v[214:217], v[2:5]
	v_mfma_f32_16x16x32_bf16 v[2:5], v[158:161], v[240:243], v[2:5]
	v_mfma_f32_16x16x32_bf16 v[6:9], v[146:149], v[214:217], v[6:9]
	v_mfma_f32_16x16x32_bf16 v[6:9], v[150:153], v[240:243], v[6:9]
	v_mfma_f32_16x16x32_bf16 v[10:13], v[138:141], v[214:217], v[10:13]
	v_mfma_f32_16x16x32_bf16 v[10:13], v[142:145], v[240:243], v[10:13]
	v_mfma_f32_16x16x32_bf16 v[18:21], v[130:133], v[214:217], v[18:21]
	v_mfma_f32_16x16x32_bf16 v[18:21], v[134:137], v[240:243], v[18:21]
	s_setprio 0
	s_add_u32 s4, s4, 0x100
	s_addc_u32 s5, s5, 0
	s_add_u32 s0, s0, 0x100
	s_addc_u32 s1, s1, 0
	s_cmp_ge_u32 s55, s31
	s_mov_b32 s44, s55
	s_barrier
; #define PG8_STAGE(bufoff, gbase, voff) do { _Pragma("unroll") for (int _i = 0; _i < 2; ++_i) { \
;         const unsigned _m0 = ldsb + (unsigned)((bufoff) + _i * 8192); const char* _gb = (const char*)(gbase); \
;         asm volatile("s_mov_b32 m0, %0\n\ts_nop 0\n\tglobal_load_lds_dwordx4 %1, %2" :: "s"(_m0), "v"((voff)[_i]), "s"(_gb) : "m0", "memory"); } } while (0)
; #define PG8_LDA(dst, b, h) do { _Pragma("unroll") for (int m = 0; m < 4; ++m) _Pragma("unroll") for (int k = 0; k < 2; ++k) dst[m][k] = *(const LAS bf16x8*)(lds + PG8_SA(b, h) + aoff + m * 2048 + k * 1024); } while (0)
; #define PG8_LDB(dst, b, h) do { _Pragma("unroll") for (int n = 0; n < 2; ++n) _Pragma("unroll") for (int k = 0; k < 2; ++k) dst[n][k] = *(const LAS bf16x8*)(lds + PG8_SB(b, h) + boff + n * 2048 + k * 1024); } while (0)
; #define PG8_MMA(ai, bj, At, Bt) do { __builtin_amdgcn_s_setprio(1); _Pragma("unroll") for (int m = 0; m < 4; ++m) _Pragma("unroll") for (int n = 0; n < 2; ++n) _Pragma("unroll") for (int k = 0; k < 2; ++k) \
;         acc[ai][bj][m][n] = __builtin_amdgcn_mfma_f32_16x16x32_bf16(Bt[n][k], At[m][k], acc[ai][bj][m][n], 0, 0, 0); __builtin_amdgcn_s_setprio(0); } while (0)
; #define PG8_WAIT_V(n) asm volatile("s_waitcnt vmcnt(" #n ")" ::: "memory")
; #define PG8_WAIT_L(n) asm volatile("s_waitcnt lgkmcnt(" #n ")" ::: "memory")
; template <class Epi, bool ALIGN_EPI>
; __device__ __forceinline__ void gemm_phase(LAS unsigned char* lds, const Gemm g, const StaticOrder& S, const Epi& E) {
;     ...
;         for (int t = 0; t < nt; t += 2) {
;             const bool last = (t == nt - 2);
;             const char* a1 = cA + (size_t)(t + 1) * kstep;
;             const char* a2 = last ? nA : cA + (size_t)(t + 2) * kstep; const char* b2 = last ? nB : cB + (size_t)(t + 2) * kstep;
;             const char* a3 = a2 + kstep; const char* b3 = b2 + kstep;
;             PG8_LDB(B0, 0, 0); PG8_LDB(B1, 0, 1); PG8_SCHED; PG8_LDA(At, 0, 0); PG8_STAGE(PG8_SA(1, 1), a1 + hstepA, voffA);
;             PG8_WAIT_V(8); PG8_WAIT_L(0); PG8_BAR; PG8_MMA(0, 0, At, B0); PG8_MMA(0, 1, At, B1); PG8_BAR; PG8_SCHED;
;             PG8_LDA(At, 0, 1); PG8_STAGE(PG8_SB(0, 0), b2, voffB); PG8_STAGE(PG8_SB(0, 1), b2 + hstepB, voffB); PG8_STAGE(PG8_SA(0, 0), a2, voffA);
;             PG8_WAIT_V(8); PG8_WAIT_L(0); PG8_BAR; PG8_MMA(1, 0, At, B0); PG8_MMA(1, 1, At, B1); PG8_BAR; PG8_SCHED;
.LBB0_271:
	v_add_u32_e32 v0, 0x10000, v179
	ds_read_b128 v[130:133], v0
	ds_read_b128 v[134:137], v0 offset:1024
	ds_read_b128 v[138:141], v0 offset:2048
	ds_read_b128 v[142:145], v0 offset:3072
	v_add_u32_e32 v0, 0x14000, v179
	ds_read_b128 v[146:149], v0
	ds_read_b128 v[150:153], v0 offset:1024
	ds_read_b128 v[154:157], v0 offset:2048
	ds_read_b128 v[158:161], v0 offset:3072
	s_add_i32 s55, s44, 2
	s_add_u32 s45, s0, 0xfffc0080
	s_addc_u32 s56, s1, -1
	s_cmp_eq_u32 s68, s44
	s_cselect_b32 s60, s96, s45
	s_cselect_b32 s61, s97, s56
	s_cselect_b32 s58, s48, s4
	s_cselect_b32 s59, s49, s5
	s_add_u32 s56, s60, 0x80
	s_addc_u32 s57, s61, 0
	ds_read_b128 v[182:185], v180
	ds_read_b128 v[186:189], v180 offset:1024
	ds_read_b128 v[190:193], v180 offset:2048
	ds_read_b128 v[202:205], v180 offset:3072
	ds_read_b128 v[206:209], v180 offset:4096
	ds_read_b128 v[210:213], v180 offset:5120
	ds_read_b128 v[214:217], v180 offset:6144
	ds_read_b128 v[240:243], v180 offset:7168
	s_mov_b32 m0, s41
	s_nop 0
	global_load_lds_dwordx4 v165, s[0:1]
	s_nop 0
	s_mov_b32 m0, s30
	s_nop 0
	global_load_lds_dwordx4 v171, s[0:1]
	s_waitcnt vmcnt(8)
	s_waitcnt lgkmcnt(0)
	s_barrier
	s_setprio 1
	s_waitcnt lgkmcnt(0)
	v_mfma_f32_16x16x32_bf16 v[126:129], v[130:133], v[182:185], v[126:129]
	v_mfma_f32_16x16x32_bf16 v[126:129], v[134:137], v[186:189], v[126:129]
	v_mfma_f32_16x16x32_bf16 v[122:125], v[138:141], v[182:185], v[122:125]
	v_mfma_f32_16x16x32_bf16 v[122:125], v[142:145], v[186:189], v[122:125]
	v_mfma_f32_16x16x32_bf16 v[118:121], v[146:149], v[182:185], v[118:121]
	v_mfma_f32_16x16x32_bf16 v[118:121], v[150:153], v[186:189], v[118:121]
	v_mfma_f32_16x16x32_bf16 v[110:113], v[154:157], v[182:185], v[110:113]
	v_mfma_f32_16x16x32_bf16 v[110:113], v[158:161], v[186:189], v[110:113]
	v_mfma_f32_16x16x32_bf16 v[94:97], v[154:157], v[190:193], v[94:97]
	v_mfma_f32_16x16x32_bf16 v[94:97], v[158:161], v[202:205], v[94:97]
	v_mfma_f32_16x16x32_bf16 v[102:105], v[146:149], v[190:193], v[102:105]
	v_mfma_f32_16x16x32_bf16 v[102:105], v[150:153], v[202:205], v[102:105]
	v_mfma_f32_16x16x32_bf16 v[106:109], v[138:141], v[190:193], v[106:109]
	v_mfma_f32_16x16x32_bf16 v[106:109], v[142:145], v[202:205], v[106:109]
	v_mfma_f32_16x16x32_bf16 v[114:117], v[130:133], v[190:193], v[114:117]
	v_mfma_f32_16x16x32_bf16 v[114:117], v[134:137], v[202:205], v[114:117]
	v_mfma_f32_16x16x32_bf16 v[98:101], v[130:133], v[206:209], v[98:101]
	v_mfma_f32_16x16x32_bf16 v[98:101], v[134:137], v[210:213], v[98:101]
	v_mfma_f32_16x16x32_bf16 v[90:93], v[138:141], v[206:209], v[90:93]
	v_mfma_f32_16x16x32_bf16 v[90:93], v[142:145], v[210:213], v[90:93]
	v_mfma_f32_16x16x32_bf16 v[86:89], v[146:149], v[206:209], v[86:89]
	v_mfma_f32_16x16x32_bf16 v[86:89], v[150:153], v[210:213], v[86:89]
	v_mfma_f32_16x16x32_bf16 v[78:81], v[154:157], v[206:209], v[78:81]
	v_mfma_f32_16x16x32_bf16 v[78:81], v[158:161], v[210:213], v[78:81]
	v_mfma_f32_16x16x32_bf16 v[66:69], v[154:157], v[214:217], v[66:69]
	v_mfma_f32_16x16x32_bf16 v[66:69], v[158:161], v[240:243], v[66:69]
	v_mfma_f32_16x16x32_bf16 v[70:73], v[146:149], v[214:217], v[70:73]
	v_mfma_f32_16x16x32_bf16 v[70:73], v[150:153], v[240:243], v[70:73]
	v_mfma_f32_16x16x32_bf16 v[74:77], v[138:141], v[214:217], v[74:77]
	v_mfma_f32_16x16x32_bf16 v[74:77], v[142:145], v[240:243], v[74:77]
	v_mfma_f32_16x16x32_bf16 v[82:85], v[130:133], v[214:217], v[82:85]
	v_mfma_f32_16x16x32_bf16 v[82:85], v[134:137], v[240:243], v[82:85]
	s_setprio 0
	s_barrier
	ds_read_b128 v[182:185], v180 offset:16384
	ds_read_b128 v[186:189], v180 offset:17408
	ds_read_b128 v[190:193], v180 offset:18432
	ds_read_b128 v[202:205], v180 offset:19456
	ds_read_b128 v[206:209], v180 offset:20480
	ds_read_b128 v[210:213], v180 offset:21504
	ds_read_b128 v[214:217], v180 offset:22528
	ds_read_b128 v[240:243], v180 offset:23552
	s_mov_b32 m0, s42
	s_nop 0
	global_load_lds_dwordx4 v167, s[58:59]
	s_add_u32 s44, s58, s14
	s_mov_b32 m0, s43
	s_nop 0
	global_load_lds_dwordx4 v175, s[58:59]
	s_addc_u32 s45, s59, 0
	s_mov_b32 m0, s46
	s_nop 0
	global_load_lds_dwordx4 v167, s[44:45]
	s_nop 0
	s_mov_b32 m0, s50
	s_nop 0
	global_load_lds_dwordx4 v175, s[44:45]
	s_nop 0
	s_mov_b32 m0, s17
	s_nop 0
	global_load_lds_dwordx4 v165, s[60:61]
	s_nop 0
	s_mov_b32 m0, s53
	s_nop 0
	global_load_lds_dwordx4 v171, s[60:61]
	s_waitcnt vmcnt(8)
	s_waitcnt lgkmcnt(0)
	s_barrier
	s_setprio 1
	s_waitcnt lgkmcnt(0)
	v_mfma_f32_16x16x32_bf16 v[62:65], v[130:133], v[182:185], v[62:65]
	v_mfma_f32_16x16x32_bf16 v[62:65], v[134:137], v[186:189], v[62:65]
	v_mfma_f32_16x16x32_bf16 v[58:61], v[138:141], v[182:185], v[58:61]
	v_mfma_f32_16x16x32_bf16 v[58:61], v[142:145], v[186:189], v[58:61]
	v_mfma_f32_16x16x32_bf16 v[54:57], v[146:149], v[182:185], v[54:57]
	v_mfma_f32_16x16x32_bf16 v[54:57], v[150:153], v[186:189], v[54:57]
	v_mfma_f32_16x16x32_bf16 v[50:53], v[154:157], v[182:185], v[50:53]
	v_mfma_f32_16x16x32_bf16 v[50:53], v[158:161], v[186:189], v[50:53]
	v_mfma_f32_16x16x32_bf16 v[30:33], v[154:157], v[190:193], v[30:33]
	v_mfma_f32_16x16x32_bf16 v[30:33], v[158:161], v[202:205], v[30:33]
	v_mfma_f32_16x16x32_bf16 v[38:41], v[146:149], v[190:193], v[38:41]
	v_mfma_f32_16x16x32_bf16 v[38:41], v[150:153], v[202:205], v[38:41]
	v_mfma_f32_16x16x32_bf16 v[42:45], v[138:141], v[190:193], v[42:45]
	v_mfma_f32_16x16x32_bf16 v[42:45], v[142:145], v[202:205], v[42:45]
	v_mfma_f32_16x16x32_bf16 v[46:49], v[130:133], v[190:193], v[46:49]
	v_mfma_f32_16x16x32_bf16 v[46:49], v[134:137], v[202:205], v[46:49]
	v_mfma_f32_16x16x32_bf16 v[34:37], v[130:133], v[206:209], v[34:37]
	v_mfma_f32_16x16x32_bf16 v[34:37], v[134:137], v[210:213], v[34:37]
	v_mfma_f32_16x16x32_bf16 v[26:29], v[138:141], v[206:209], v[26:29]
	v_mfma_f32_16x16x32_bf16 v[26:29], v[142:145], v[210:213], v[26:29]
	v_mfma_f32_16x16x32_bf16 v[22:25], v[146:149], v[206:209], v[22:25]
	v_mfma_f32_16x16x32_bf16 v[22:25], v[150:153], v[210:213], v[22:25]
	v_mfma_f32_16x16x32_bf16 v[14:17], v[154:157], v[206:209], v[14:17]
	v_mfma_f32_16x16x32_bf16 v[14:17], v[158:161], v[210:213], v[14:17]
	v_mfma_f32_16x16x32_bf16 v[2:5], v[154:157], v[214:217], v[2:5]
	v_mfma_f32_16x16x32_bf16 v[2:5], v[158:161], v[240:243], v[2:5]
	v_mfma_f32_16x16x32_bf16 v[6:9], v[146:149], v[214:217], v[6:9]
	v_mfma_f32_16x16x32_bf16 v[6:9], v[150:153], v[240:243], v[6:9]
	v_mfma_f32_16x16x32_bf16 v[10:13], v[138:141], v[214:217], v[10:13]
	v_mfma_f32_16x16x32_bf16 v[10:13], v[142:145], v[240:243], v[10:13]
	v_mfma_f32_16x16x32_bf16 v[18:21], v[130:133], v[214:217], v[18:21]
	v_mfma_f32_16x16x32_bf16 v[18:21], v[134:137], v[240:243], v[18:21]
	s_setprio 0
	s_barrier
; #define PG8_STAGE(bufoff, gbase, voff) do { _Pragma("unroll") for (int _i = 0; _i < 2; ++_i) { \
;         const unsigned _m0 = ldsb + (unsigned)((bufoff) + _i * 8192); const char* _gb = (const char*)(gbase); \
;         asm volatile("s_mov_b32 m0, %0\n\ts_nop 0\n\tglobal_load_lds_dwordx4 %1, %2" :: "s"(_m0), "v"((voff)[_i]), "s"(_gb) : "m0", "memory"); } } while (0)
; #define PG8_LDA(dst, b, h) do { _Pragma("unroll") for (int m = 0; m < 4; ++m) _Pragma("unroll") for (int k = 0; k < 2; ++k) dst[m][k] = *(const LAS bf16x8*)(lds + PG8_SA(b, h) + aoff + m * 2048 + k * 1024); } while (0)
; #define PG8_LDB(dst, b, h) do { _Pragma("unroll") for (int n = 0; n < 2; ++n) _Pragma("unroll") for (int k = 0; k < 2; ++k) dst[n][k] = *(const LAS bf16x8*)(lds + PG8_SB(b, h) + boff + n * 2048 + k * 1024); } while (0)
; #define PG8_MMA(ai, bj, At, Bt) do { __builtin_amdgcn_s_setprio(1); _Pragma("unroll") for (int m = 0; m < 4; ++m) _Pragma("unroll") for (int n = 0; n < 2; ++n) _Pragma("unroll") for (int k = 0; k < 2; ++k) \
;         acc[ai][bj][m][n] = __builtin_amdgcn_mfma_f32_16x16x32_bf16(Bt[n][k], At[m][k], acc[ai][bj][m][n], 0, 0, 0); __builtin_amdgcn_s_setprio(0); } while (0)
; #define PG8_WAIT_V(n) asm volatile("s_waitcnt vmcnt(" #n ")" ::: "memory")
; #define PG8_WAIT_L(n) asm volatile("s_waitcnt lgkmcnt(" #n ")" ::: "memory")
; #define PG8_BAR __builtin_amdgcn_s_barrier()
; #define PG8_SCHED __builtin_amdgcn_sched_barrier(0)
; template <class Epi, bool ALIGN_EPI>
; __device__ __forceinline__ void gemm_phase(LAS unsigned char* lds, const Gemm g, const StaticOrder& S, const Epi& E) {
;     ...
;             PG8_LDB(B0, 1, 0); PG8_LDB(B1, 1, 1); PG8_SCHED; PG8_LDA(At, 1, 0); PG8_STAGE(PG8_SA(0, 1), a2 + hstepA, voffA);
;             PG8_WAIT_V(8); PG8_WAIT_L(0); PG8_BAR; PG8_MMA(0, 0, At, B0); PG8_MMA(0, 1, At, B1); PG8_BAR; PG8_SCHED;
;             PG8_LDA(At, 1, 1); PG8_STAGE(PG8_SB(1, 0), b3, voffB); PG8_STAGE(PG8_SB(1, 1), b3 + hstepB, voffB); PG8_STAGE(PG8_SA(1, 0), a3, voffA);
;             PG8_WAIT_V(8); PG8_WAIT_L(0); PG8_BAR; PG8_MMA(1, 0, At, B0); PG8_MMA(1, 1, At, B1); PG8_BAR; PG8_SCHED;
;         }
;         if constexpr (ALIGN_EPI) { if (wr == 0) PG8_BAR; }
	v_add_u32_e32 v0, 0x18000, v179
	ds_read_b128 v[130:133], v0
	ds_read_b128 v[134:137], v0 offset:1024
	ds_read_b128 v[138:141], v0 offset:2048
	ds_read_b128 v[142:145], v0 offset:3072
	v_add_u32_e32 v0, 0x1c000, v179
	ds_read_b128 v[146:149], v0
	ds_read_b128 v[150:153], v0 offset:1024
	ds_read_b128 v[154:157], v0 offset:2048
	ds_read_b128 v[158:161], v0 offset:3072
	ds_read_b128 v[182:185], v180 offset:32768
	ds_read_b128 v[186:189], v180 offset:33792
	ds_read_b128 v[190:193], v180 offset:34816
	ds_read_b128 v[202:205], v180 offset:35840
	ds_read_b128 v[206:209], v180 offset:36864
	ds_read_b128 v[210:213], v180 offset:37888
	ds_read_b128 v[214:217], v180 offset:38912
	ds_read_b128 v[240:243], v180 offset:39936
	s_add_u32 s60, s60, 0x40000
	s_addc_u32 s61, s61, 0
	s_mov_b32 m0, s65
	s_nop 0
	global_load_lds_dwordx4 v165, s[60:61]
	s_nop 0
	s_mov_b32 m0, s67
	s_nop 0
	global_load_lds_dwordx4 v171, s[60:61]
	s_waitcnt vmcnt(8)
	s_waitcnt lgkmcnt(0)
	s_barrier
	s_setprio 1
	s_waitcnt lgkmcnt(0)
	v_mfma_f32_16x16x32_bf16 v[126:129], v[130:133], v[182:185], v[126:129]
	v_mfma_f32_16x16x32_bf16 v[126:129], v[134:137], v[186:189], v[126:129]
	v_mfma_f32_16x16x32_bf16 v[122:125], v[138:141], v[182:185], v[122:125]
	v_mfma_f32_16x16x32_bf16 v[122:125], v[142:145], v[186:189], v[122:125]
	v_mfma_f32_16x16x32_bf16 v[118:121], v[146:149], v[182:185], v[118:121]
	v_mfma_f32_16x16x32_bf16 v[118:121], v[150:153], v[186:189], v[118:121]
	v_mfma_f32_16x16x32_bf16 v[110:113], v[154:157], v[182:185], v[110:113]
	v_mfma_f32_16x16x32_bf16 v[110:113], v[158:161], v[186:189], v[110:113]
	v_mfma_f32_16x16x32_bf16 v[94:97], v[154:157], v[190:193], v[94:97]
	v_mfma_f32_16x16x32_bf16 v[94:97], v[158:161], v[202:205], v[94:97]
	v_mfma_f32_16x16x32_bf16 v[102:105], v[146:149], v[190:193], v[102:105]
	v_mfma_f32_16x16x32_bf16 v[102:105], v[150:153], v[202:205], v[102:105]
	v_mfma_f32_16x16x32_bf16 v[106:109], v[138:141], v[190:193], v[106:109]
	v_mfma_f32_16x16x32_bf16 v[106:109], v[142:145], v[202:205], v[106:109]
	v_mfma_f32_16x16x32_bf16 v[114:117], v[130:133], v[190:193], v[114:117]
	v_mfma_f32_16x16x32_bf16 v[114:117], v[134:137], v[202:205], v[114:117]
	v_mfma_f32_16x16x32_bf16 v[98:101], v[130:133], v[206:209], v[98:101]
	v_mfma_f32_16x16x32_bf16 v[98:101], v[134:137], v[210:213], v[98:101]
	v_mfma_f32_16x16x32_bf16 v[90:93], v[138:141], v[206:209], v[90:93]
	v_mfma_f32_16x16x32_bf16 v[90:93], v[142:145], v[210:213], v[90:93]
	v_mfma_f32_16x16x32_bf16 v[86:89], v[146:149], v[206:209], v[86:89]
	v_mfma_f32_16x16x32_bf16 v[86:89], v[150:153], v[210:213], v[86:89]
	v_mfma_f32_16x16x32_bf16 v[78:81], v[154:157], v[206:209], v[78:81]
	v_mfma_f32_16x16x32_bf16 v[78:81], v[158:161], v[210:213], v[78:81]
	v_mfma_f32_16x16x32_bf16 v[66:69], v[154:157], v[214:217], v[66:69]
	v_mfma_f32_16x16x32_bf16 v[66:69], v[158:161], v[240:243], v[66:69]
	v_mfma_f32_16x16x32_bf16 v[70:73], v[146:149], v[214:217], v[70:73]
	v_mfma_f32_16x16x32_bf16 v[70:73], v[150:153], v[240:243], v[70:73]
	v_mfma_f32_16x16x32_bf16 v[74:77], v[138:141], v[214:217], v[74:77]
	v_mfma_f32_16x16x32_bf16 v[74:77], v[142:145], v[240:243], v[74:77]
	v_mfma_f32_16x16x32_bf16 v[82:85], v[130:133], v[214:217], v[82:85]
	v_mfma_f32_16x16x32_bf16 v[82:85], v[134:137], v[240:243], v[82:85]
	s_setprio 0
	s_barrier
	ds_read_b128 v[182:185], v180 offset:49152
	ds_read_b128 v[186:189], v180 offset:50176
	ds_read_b128 v[190:193], v180 offset:51200
	ds_read_b128 v[202:205], v180 offset:52224
	ds_read_b128 v[206:209], v180 offset:53248
	ds_read_b128 v[210:213], v180 offset:54272
	ds_read_b128 v[214:217], v180 offset:55296
	ds_read_b128 v[240:243], v180 offset:56320
	s_add_u32 s58, s58, 0x80
	s_addc_u32 s59, s59, 0
	s_mov_b32 m0, s89
	s_nop 0
	global_load_lds_dwordx4 v167, s[58:59]
	s_add_u32 s44, s44, 0x80
	s_mov_b32 m0, s95
	s_nop 0
	global_load_lds_dwordx4 v175, s[58:59]
	s_addc_u32 s45, s45, 0
	s_mov_b32 m0, s26
	s_nop 0
	global_load_lds_dwordx4 v167, s[44:45]
	s_nop 0
	s_mov_b32 m0, s27
	s_nop 0
	global_load_lds_dwordx4 v175, s[44:45]
	s_nop 0
	s_mov_b32 m0, s36
	s_nop 0
	global_load_lds_dwordx4 v165, s[56:57]
	s_nop 0
	s_mov_b32 m0, s37
	s_nop 0
	global_load_lds_dwordx4 v171, s[56:57]
	s_waitcnt vmcnt(8)
	s_waitcnt lgkmcnt(0)
	s_barrier
	s_setprio 1
	s_waitcnt lgkmcnt(0)
	v_mfma_f32_16x16x32_bf16 v[62:65], v[130:133], v[182:185], v[62:65]
	v_mfma_f32_16x16x32_bf16 v[62:65], v[134:137], v[186:189], v[62:65]
	v_mfma_f32_16x16x32_bf16 v[58:61], v[138:141], v[182:185], v[58:61]
	v_mfma_f32_16x16x32_bf16 v[58:61], v[142:145], v[186:189], v[58:61]
	v_mfma_f32_16x16x32_bf16 v[54:57], v[146:149], v[182:185], v[54:57]
	v_mfma_f32_16x16x32_bf16 v[54:57], v[150:153], v[186:189], v[54:57]
	v_mfma_f32_16x16x32_bf16 v[50:53], v[154:157], v[182:185], v[50:53]
	v_mfma_f32_16x16x32_bf16 v[50:53], v[158:161], v[186:189], v[50:53]
	v_mfma_f32_16x16x32_bf16 v[30:33], v[154:157], v[190:193], v[30:33]
	v_mfma_f32_16x16x32_bf16 v[30:33], v[158:161], v[202:205], v[30:33]
	v_mfma_f32_16x16x32_bf16 v[38:41], v[146:149], v[190:193], v[38:41]
	v_mfma_f32_16x16x32_bf16 v[38:41], v[150:153], v[202:205], v[38:41]
	v_mfma_f32_16x16x32_bf16 v[42:45], v[138:141], v[190:193], v[42:45]
	v_mfma_f32_16x16x32_bf16 v[42:45], v[142:145], v[202:205], v[42:45]
	v_mfma_f32_16x16x32_bf16 v[46:49], v[130:133], v[190:193], v[46:49]
	v_mfma_f32_16x16x32_bf16 v[46:49], v[134:137], v[202:205], v[46:49]
	v_mfma_f32_16x16x32_bf16 v[34:37], v[130:133], v[206:209], v[34:37]
	v_mfma_f32_16x16x32_bf16 v[34:37], v[134:137], v[210:213], v[34:37]
	v_mfma_f32_16x16x32_bf16 v[26:29], v[138:141], v[206:209], v[26:29]
	v_mfma_f32_16x16x32_bf16 v[26:29], v[142:145], v[210:213], v[26:29]
	v_mfma_f32_16x16x32_bf16 v[22:25], v[146:149], v[206:209], v[22:25]
	v_mfma_f32_16x16x32_bf16 v[22:25], v[150:153], v[210:213], v[22:25]
	v_mfma_f32_16x16x32_bf16 v[14:17], v[154:157], v[206:209], v[14:17]
	v_mfma_f32_16x16x32_bf16 v[14:17], v[158:161], v[210:213], v[14:17]
	v_mfma_f32_16x16x32_bf16 v[2:5], v[154:157], v[214:217], v[2:5]
	v_mfma_f32_16x16x32_bf16 v[2:5], v[158:161], v[240:243], v[2:5]
	v_mfma_f32_16x16x32_bf16 v[6:9], v[146:149], v[214:217], v[6:9]
	v_mfma_f32_16x16x32_bf16 v[6:9], v[150:153], v[240:243], v[6:9]
	v_mfma_f32_16x16x32_bf16 v[10:13], v[138:141], v[214:217], v[10:13]
	v_mfma_f32_16x16x32_bf16 v[10:13], v[142:145], v[240:243], v[10:13]
	v_mfma_f32_16x16x32_bf16 v[18:21], v[130:133], v[214:217], v[18:21]
	v_mfma_f32_16x16x32_bf16 v[18:21], v[134:137], v[240:243], v[18:21]
	s_setprio 0
	s_add_u32 s4, s4, 0x100
	s_addc_u32 s5, s5, 0
	s_add_u32 s0, s0, 0x100
	s_addc_u32 s1, s1, 0
	s_cmp_ge_u32 s55, s31
	s_mov_b32 s44, s55
	s_barrier
	s_cbranch_scc0 .LBB0_271
	v_readlane_b32 s0, v254, 44
	v_readlane_b32 s1, v254, 45
	s_and_b64 vcc, exec, s[0:1]
	s_cbranch_vccz .LBB0_274
	s_barrier

; #define PG8_STAGE(bufoff, gbase, voff) do { _Pragma("unroll") for (int _i = 0; _i < 2; ++_i) { \
;         const unsigned _m0 = ldsb + (unsigned)((bufoff) + _i * 8192); const char* _gb = (const char*)(gbase); \
;         asm volatile("s_mov_b32 m0, %0\n\ts_nop 0\n\tglobal_load_lds_dwordx4 %1, %2" :: "s"(_m0), "v"((voff)[_i]), "s"(_gb) : "m0", "memory"); } } while (0)
; #define PG8_LDA(dst, b, h) do { _Pragma("unroll") for (int m = 0; m < 4; ++m) _Pragma("unroll") for (int k = 0; k < 2; ++k) dst[m][k] = *(const LAS bf16x8*)(lds + PG8_SA(b, h) + aoff + m * 2048 + k * 1024); } while (0)
; #define PG8_LDB(dst, b, h) do { _Pragma("unroll") for (int n = 0; n < 2; ++n) _Pragma("unroll") for (int k = 0; k < 2; ++k) dst[n][k] = *(const LAS bf16x8*)(lds + PG8_SB(b, h) + boff + n * 2048 + k * 1024); } while (0)
; #define PG8_WAIT_V(n) asm volatile("s_waitcnt vmcnt(" #n ")" ::: "memory")
; #define PG8_WAIT_L(n) asm volatile("s_waitcnt lgkmcnt(" #n ")" ::: "memory")
; #define PG8_BAR __builtin_amdgcn_s_barrier()
; #define PG8_SCHED __builtin_amdgcn_sched_barrier(0)
; template <class Epi, bool ALIGN_EPI>
; __device__ __forceinline__ void gemm_phase(LAS unsigned char* lds, const Gemm g, const StaticOrder& S, const Epi& E) {
;     ...
;         const char* nA = has_next ? (const char*)g.A + (size_t)nxt.pm * tstepA + (size_t)nxt.pn * g.a_pn_off * 2 + (size_t)(nxt.pm >> 4) * g.a_adj : cA; const char* nB = has_next ? (const char*)g.Bt + (size_t)nxt.pn * tstepB : cB;
;         for (int t = 0; t < nt; t += 2) {
;             const bool last = (t == nt - 2);
;             const char* a1 = cA + (size_t)(t + 1) * kstep;
;             const char* a2 = last ? nA : cA + (size_t)(t + 2) * kstep; const char* b2 = last ? nB : cB + (size_t)(t + 2) * kstep;
;             const char* a3 = a2 + kstep; const char* b3 = b2 + kstep;
;             PG8_LDB(B0, 0, 0); PG8_LDB(B1, 0, 1); PG8_SCHED; PG8_LDA(At, 0, 0); PG8_STAGE(PG8_SA(1, 1), a1 + hstepA, voffA);
;             PG8_WAIT_V(8); PG8_WAIT_L(0); PG8_BAR; PG8_MMA(0, 0, At, B0); PG8_MMA(0, 1, At, B1); PG8_BAR; PG8_SCHED;
;             PG8_LDA(At, 0, 1); PG8_STAGE(PG8_SB(0, 0), b2, voffB); PG8_STAGE(PG8_SB(0, 1), b2 + hstepB, voffB); PG8_STAGE(PG8_SA(0, 0), a2, voffA);
;             PG8_WAIT_V(8); PG8_WAIT_L(0); PG8_BAR; PG8_MMA(1, 0, At, B0); PG8_MMA(1, 1, At, B1); PG8_BAR; PG8_SCHED;
.LBB0_305:
	s_ashr_i32 s37, s36, 31
	s_lshl_b64 s[4:5], s[36:37], 19
	s_add_u32 s38, s18, s4
	s_addc_u32 s39, s19, s5
	s_and_b64 s[4:5], s[8:9], exec
	s_cselect_b32 s4, s39, s59
	s_cselect_b32 s5, s38, s58
	s_ashr_i32 s35, s34, 31
	s_lshl_b64 s[50:51], s[34:35], 19
	s_add_u32 s90, s1, s50
	s_addc_u32 s91, s14, s51
	s_and_b64 s[50:51], s[8:9], exec
	s_cselect_b32 s35, s91, s57
	s_cselect_b32 s37, s90, s56
	s_add_u32 s41, s56, 0x100
	s_addc_u32 s49, s57, 0
	s_add_u32 s92, s58, 0x40080
	s_addc_u32 s93, s59, 0
	s_mov_b32 s50, -2
	s_add_u32 s30, s92, 0xfffc0080
	s_addc_u32 s31, s93, -1
	s_cmp_eq_u32 s50, 12
	s_cselect_b32 s60, s5, s30
	s_cselect_b32 s61, s4, s31
	s_cselect_b32 s58, s37, s41
	s_cselect_b32 s59, s35, s49
	s_add_u32 s56, s60, 0x80
	s_addc_u32 s57, s61, 0
	s_mov_b32 m0, s67
	s_nop 0
	global_load_lds_dwordx4 v0, s[92:93]
	s_nop 0
	s_mov_b32 m0, s65
	s_nop 0
	global_load_lds_dwordx4 v181, s[92:93]
	s_waitcnt vmcnt(8)
	s_waitcnt lgkmcnt(0)
	s_barrier
	s_setprio 1
	s_waitcnt lgkmcnt(0)
	v_mfma_f32_16x16x32_bf16 v[142:145], v[74:77], v[162:165], 0
	v_mfma_f32_16x16x32_bf16 v[142:145], v[94:97], v[166:169], v[142:145]
	v_mfma_f32_16x16x32_bf16 v[138:141], v[114:117], v[162:165], 0
	v_mfma_f32_16x16x32_bf16 v[138:141], v[134:137], v[166:169], v[138:141]
	v_mfma_f32_16x16x32_bf16 v[130:133], v[146:149], v[162:165], 0
	v_mfma_f32_16x16x32_bf16 v[130:133], v[150:153], v[166:169], v[130:133]
	v_mfma_f32_16x16x32_bf16 v[126:129], v[154:157], v[162:165], 0
	v_mfma_f32_16x16x32_bf16 v[126:129], v[158:161], v[166:169], v[126:129]
	v_mfma_f32_16x16x32_bf16 v[106:109], v[154:157], v[170:173], 0
	v_mfma_f32_16x16x32_bf16 v[106:109], v[158:161], v[174:177], v[106:109]
	v_mfma_f32_16x16x32_bf16 v[110:113], v[146:149], v[170:173], 0
	v_mfma_f32_16x16x32_bf16 v[110:113], v[150:153], v[174:177], v[110:113]
	v_mfma_f32_16x16x32_bf16 v[118:121], v[114:117], v[170:173], 0
	v_mfma_f32_16x16x32_bf16 v[118:121], v[134:137], v[174:177], v[118:121]
	v_mfma_f32_16x16x32_bf16 v[122:125], v[74:77], v[170:173], 0
	v_mfma_f32_16x16x32_bf16 v[122:125], v[94:97], v[174:177], v[122:125]
	v_mfma_f32_16x16x32_bf16 v[102:105], v[74:77], v[188:191], 0
	v_mfma_f32_16x16x32_bf16 v[102:105], v[94:97], v[202:205], v[102:105]
	v_mfma_f32_16x16x32_bf16 v[98:101], v[114:117], v[188:191], 0
	v_mfma_f32_16x16x32_bf16 v[98:101], v[134:137], v[202:205], v[98:101]
	v_mfma_f32_16x16x32_bf16 v[90:93], v[146:149], v[188:191], 0
	v_mfma_f32_16x16x32_bf16 v[90:93], v[150:153], v[202:205], v[90:93]
	v_mfma_f32_16x16x32_bf16 v[86:89], v[154:157], v[188:191], 0
	v_mfma_f32_16x16x32_bf16 v[86:89], v[158:161], v[202:205], v[86:89]
	v_mfma_f32_16x16x32_bf16 v[66:69], v[154:157], v[206:209], 0
	v_mfma_f32_16x16x32_bf16 v[66:69], v[158:161], v[210:213], v[66:69]
	v_mfma_f32_16x16x32_bf16 v[70:73], v[146:149], v[206:209], 0
	v_mfma_f32_16x16x32_bf16 v[70:73], v[150:153], v[210:213], v[70:73]
	v_mfma_f32_16x16x32_bf16 v[78:81], v[114:117], v[206:209], 0
	v_mfma_f32_16x16x32_bf16 v[78:81], v[134:137], v[210:213], v[78:81]
	v_mfma_f32_16x16x32_bf16 v[82:85], v[74:77], v[206:209], 0
	v_mfma_f32_16x16x32_bf16 v[82:85], v[94:97], v[210:213], v[82:85]
	s_setprio 0
	s_barrier
	ds_read_b128 v[162:165], v186 offset:16384
	ds_read_b128 v[166:169], v186 offset:17408
	ds_read_b128 v[170:173], v186 offset:18432
	ds_read_b128 v[174:177], v186 offset:19456
	ds_read_b128 v[188:191], v186 offset:20480
	ds_read_b128 v[202:205], v186 offset:21504
	ds_read_b128 v[206:209], v186 offset:22528
	ds_read_b128 v[210:213], v186 offset:23552
	s_mov_b32 m0, s29
	s_nop 0
	global_load_lds_dwordx4 v180, s[58:59]
	s_add_u32 s30, s58, 0x40000
	s_mov_b32 m0, s42
	s_nop 0
	global_load_lds_dwordx4 v182, s[58:59]
	s_addc_u32 s31, s59, 0
	s_mov_b32 m0, s43
	s_nop 0
	global_load_lds_dwordx4 v180, s[30:31]
	s_nop 0
	s_mov_b32 m0, s44
	s_nop 0
	global_load_lds_dwordx4 v182, s[30:31]
	s_nop 0
	s_mov_b32 m0, s15
	s_nop 0
	global_load_lds_dwordx4 v0, s[60:61]
	s_nop 0
	s_mov_b32 m0, s45
	s_nop 0
	global_load_lds_dwordx4 v181, s[60:61]
	s_waitcnt vmcnt(8)
	s_waitcnt lgkmcnt(0)
	s_barrier
	s_setprio 1
	s_waitcnt lgkmcnt(0)
	v_mfma_f32_16x16x32_bf16 v[62:65], v[74:77], v[162:165], 0
	v_mfma_f32_16x16x32_bf16 v[62:65], v[94:97], v[166:169], v[62:65]
	v_mfma_f32_16x16x32_bf16 v[58:61], v[114:117], v[162:165], 0
	v_mfma_f32_16x16x32_bf16 v[58:61], v[134:137], v[166:169], v[58:61]
	v_mfma_f32_16x16x32_bf16 v[54:57], v[146:149], v[162:165], 0
	v_mfma_f32_16x16x32_bf16 v[54:57], v[150:153], v[166:169], v[54:57]
	v_mfma_f32_16x16x32_bf16 v[50:53], v[154:157], v[162:165], 0
	v_mfma_f32_16x16x32_bf16 v[50:53], v[158:161], v[166:169], v[50:53]
	v_mfma_f32_16x16x32_bf16 v[34:37], v[154:157], v[170:173], 0
	v_mfma_f32_16x16x32_bf16 v[34:37], v[158:161], v[174:177], v[34:37]
	v_mfma_f32_16x16x32_bf16 v[38:41], v[146:149], v[170:173], 0
	v_mfma_f32_16x16x32_bf16 v[38:41], v[150:153], v[174:177], v[38:41]
	v_mfma_f32_16x16x32_bf16 v[42:45], v[114:117], v[170:173], 0
	v_mfma_f32_16x16x32_bf16 v[42:45], v[134:137], v[174:177], v[42:45]
	v_mfma_f32_16x16x32_bf16 v[46:49], v[74:77], v[170:173], 0
	v_mfma_f32_16x16x32_bf16 v[46:49], v[94:97], v[174:177], v[46:49]
	v_mfma_f32_16x16x32_bf16 v[30:33], v[74:77], v[188:191], 0
	v_mfma_f32_16x16x32_bf16 v[30:33], v[94:97], v[202:205], v[30:33]
	v_mfma_f32_16x16x32_bf16 v[26:29], v[114:117], v[188:191], 0
	v_mfma_f32_16x16x32_bf16 v[26:29], v[134:137], v[202:205], v[26:29]
	v_mfma_f32_16x16x32_bf16 v[22:25], v[146:149], v[188:191], 0
	v_mfma_f32_16x16x32_bf16 v[22:25], v[150:153], v[202:205], v[22:25]
	v_mfma_f32_16x16x32_bf16 v[18:21], v[154:157], v[188:191], 0
	v_mfma_f32_16x16x32_bf16 v[18:21], v[158:161], v[202:205], v[18:21]
	v_mfma_f32_16x16x32_bf16 v[2:5], v[154:157], v[206:209], 0
	v_mfma_f32_16x16x32_bf16 v[2:5], v[158:161], v[210:213], v[2:5]
	v_mfma_f32_16x16x32_bf16 v[6:9], v[146:149], v[206:209], 0
	v_mfma_f32_16x16x32_bf16 v[6:9], v[150:153], v[210:213], v[6:9]
	v_mfma_f32_16x16x32_bf16 v[10:13], v[114:117], v[206:209], 0
	v_mfma_f32_16x16x32_bf16 v[10:13], v[134:137], v[210:213], v[10:13]
	v_mfma_f32_16x16x32_bf16 v[14:17], v[74:77], v[206:209], 0
	v_mfma_f32_16x16x32_bf16 v[14:17], v[94:97], v[210:213], v[14:17]
	s_setprio 0
	s_barrier
; #define PG8_STAGE(bufoff, gbase, voff) do { _Pragma("unroll") for (int _i = 0; _i < 2; ++_i) { \
;         const unsigned _m0 = ldsb + (unsigned)((bufoff) + _i * 8192); const char* _gb = (const char*)(gbase); \
;         asm volatile("s_mov_b32 m0, %0\n\ts_nop 0\n\tglobal_load_lds_dwordx4 %1, %2" :: "s"(_m0), "v"((voff)[_i]), "s"(_gb) : "m0", "memory"); } } while (0)
; #define PG8_LDA(dst, b, h) do { _Pragma("unroll") for (int m = 0; m < 4; ++m) _Pragma("unroll") for (int k = 0; k < 2; ++k) dst[m][k] = *(const LAS bf16x8*)(lds + PG8_SA(b, h) + aoff + m * 2048 + k * 1024); } while (0)
; #define PG8_LDB(dst, b, h) do { _Pragma("unroll") for (int n = 0; n < 2; ++n) _Pragma("unroll") for (int k = 0; k < 2; ++k) dst[n][k] = *(const LAS bf16x8*)(lds + PG8_SB(b, h) + boff + n * 2048 + k * 1024); } while (0)
; template <class Epi, bool ALIGN_EPI>
; __device__ __forceinline__ void gemm_phase(LAS unsigned char* lds, const Gemm g, const StaticOrder& S, const Epi& E) {
;     ...
;         for (int t = 0; t < nt; t += 2) {
;             const bool last = (t == nt - 2);
;             const char* a1 = cA + (size_t)(t + 1) * kstep;
;             const char* a2 = last ? nA : cA + (size_t)(t + 2) * kstep; const char* b2 = last ? nB : cB + (size_t)(t + 2) * kstep;
;             const char* a3 = a2 + kstep; const char* b3 = b2 + kstep;
;             PG8_LDB(B0, 0, 0); PG8_LDB(B1, 0, 1); PG8_SCHED; PG8_LDA(At, 0, 0); PG8_STAGE(PG8_SA(1, 1), a1 + hstepA, voffA);
;             PG8_WAIT_V(8); PG8_WAIT_L(0); PG8_BAR; PG8_MMA(0, 0, At, B0); PG8_MMA(0, 1, At, B1); PG8_BAR; PG8_SCHED;
;             PG8_LDA(At, 0, 1); PG8_STAGE(PG8_SB(0, 0), b2, voffB); PG8_STAGE(PG8_SB(0, 1), b2 + hstepB, voffB); PG8_STAGE(PG8_SA(0, 0), a2, voffA);
;             PG8_WAIT_V(8); PG8_WAIT_L(0); PG8_BAR; PG8_MMA(1, 0, At, B0); PG8_MMA(1, 1, At, B1); PG8_BAR; PG8_SCHED;
;             PG8_LDB(B0, 1, 0); PG8_LDB(B1, 1, 1); PG8_SCHED; PG8_LDA(At, 1, 0); PG8_STAGE(PG8_SA(0, 1), a2 + hstepA, voffA);
;             PG8_WAIT_V(8); PG8_WAIT_L(0); PG8_BAR; PG8_MMA(0, 0, At, B0); PG8_MMA(0, 1, At, B1); PG8_BAR; PG8_SCHED;
;             PG8_LDA(At, 1, 1); PG8_STAGE(PG8_SB(1, 0), b3, voffB); PG8_STAGE(PG8_SB(1, 1), b3 + hstepB, voffB); PG8_STAGE(PG8_SA(1, 0), a3, voffA);
;             PG8_WAIT_V(8); PG8_WAIT_L(0); PG8_BAR; PG8_MMA(1, 0, At, B0); PG8_MMA(1, 1, At, B1); PG8_BAR; PG8_SCHED;
	v_add_u32_e32 v134, 0x18000, v185
	v_add_u32_e32 v158, 0x1c000, v185
	ds_read_b128 v[74:77], v134
	ds_read_b128 v[94:97], v134 offset:1024
	ds_read_b128 v[114:117], v134 offset:2048
	ds_read_b128 v[134:137], v134 offset:3072
	ds_read_b128 v[146:149], v158
	ds_read_b128 v[150:153], v158 offset:1024
	ds_read_b128 v[154:157], v158 offset:2048
	ds_read_b128 v[158:161], v158 offset:3072
	ds_read_b128 v[162:165], v186 offset:32768
	ds_read_b128 v[166:169], v186 offset:33792
	ds_read_b128 v[170:173], v186 offset:34816
	ds_read_b128 v[174:177], v186 offset:35840
	ds_read_b128 v[188:191], v186 offset:36864
	ds_read_b128 v[202:205], v186 offset:37888
	ds_read_b128 v[206:209], v186 offset:38912
	ds_read_b128 v[210:213], v186 offset:39936
	s_add_u32 s30, s60, 0x40000
	s_addc_u32 s31, s61, 0
	s_mov_b32 m0, s55
	s_nop 0
	global_load_lds_dwordx4 v0, s[30:31]
	s_nop 0
	s_mov_b32 m0, s88
	s_nop 0
	global_load_lds_dwordx4 v181, s[30:31]
	s_waitcnt vmcnt(8)
	s_waitcnt lgkmcnt(0)
	s_barrier
	s_setprio 1
	s_waitcnt lgkmcnt(0)
	v_mfma_f32_16x16x32_bf16 v[142:145], v[74:77], v[162:165], v[142:145]
	v_mfma_f32_16x16x32_bf16 v[142:145], v[94:97], v[166:169], v[142:145]
	v_mfma_f32_16x16x32_bf16 v[138:141], v[114:117], v[162:165], v[138:141]
	v_mfma_f32_16x16x32_bf16 v[138:141], v[134:137], v[166:169], v[138:141]
	v_mfma_f32_16x16x32_bf16 v[130:133], v[146:149], v[162:165], v[130:133]
	v_mfma_f32_16x16x32_bf16 v[130:133], v[150:153], v[166:169], v[130:133]
	v_mfma_f32_16x16x32_bf16 v[126:129], v[154:157], v[162:165], v[126:129]
	v_mfma_f32_16x16x32_bf16 v[126:129], v[158:161], v[166:169], v[126:129]
	v_mfma_f32_16x16x32_bf16 v[106:109], v[154:157], v[170:173], v[106:109]
	v_mfma_f32_16x16x32_bf16 v[106:109], v[158:161], v[174:177], v[106:109]
	v_mfma_f32_16x16x32_bf16 v[110:113], v[146:149], v[170:173], v[110:113]
	v_mfma_f32_16x16x32_bf16 v[110:113], v[150:153], v[174:177], v[110:113]
	v_mfma_f32_16x16x32_bf16 v[118:121], v[114:117], v[170:173], v[118:121]
	v_mfma_f32_16x16x32_bf16 v[118:121], v[134:137], v[174:177], v[118:121]
	v_mfma_f32_16x16x32_bf16 v[122:125], v[74:77], v[170:173], v[122:125]
	v_mfma_f32_16x16x32_bf16 v[122:125], v[94:97], v[174:177], v[122:125]
	v_mfma_f32_16x16x32_bf16 v[102:105], v[74:77], v[188:191], v[102:105]
	v_mfma_f32_16x16x32_bf16 v[102:105], v[94:97], v[202:205], v[102:105]
	v_mfma_f32_16x16x32_bf16 v[98:101], v[114:117], v[188:191], v[98:101]
	v_mfma_f32_16x16x32_bf16 v[98:101], v[134:137], v[202:205], v[98:101]
	v_mfma_f32_16x16x32_bf16 v[90:93], v[146:149], v[188:191], v[90:93]
	v_mfma_f32_16x16x32_bf16 v[90:93], v[150:153], v[202:205], v[90:93]
	v_mfma_f32_16x16x32_bf16 v[86:89], v[154:157], v[188:191], v[86:89]
	v_mfma_f32_16x16x32_bf16 v[86:89], v[158:161], v[202:205], v[86:89]
	v_mfma_f32_16x16x32_bf16 v[66:69], v[154:157], v[206:209], v[66:69]
	v_mfma_f32_16x16x32_bf16 v[66:69], v[158:161], v[210:213], v[66:69]
	v_mfma_f32_16x16x32_bf16 v[70:73], v[146:149], v[206:209], v[70:73]
	v_mfma_f32_16x16x32_bf16 v[70:73], v[150:153], v[210:213], v[70:73]
	v_mfma_f32_16x16x32_bf16 v[78:81], v[114:117], v[206:209], v[78:81]
	v_mfma_f32_16x16x32_bf16 v[78:81], v[134:137], v[210:213], v[78:81]
	v_mfma_f32_16x16x32_bf16 v[82:85], v[74:77], v[206:209], v[82:85]
	v_mfma_f32_16x16x32_bf16 v[82:85], v[94:97], v[210:213], v[82:85]
	s_setprio 0
	s_barrier
	ds_read_b128 v[162:165], v186 offset:49152
	ds_read_b128 v[166:169], v186 offset:50176
	ds_read_b128 v[170:173], v186 offset:51200
	ds_read_b128 v[174:177], v186 offset:52224
	ds_read_b128 v[188:191], v186 offset:53248
	ds_read_b128 v[202:205], v186 offset:54272
	ds_read_b128 v[206:209], v186 offset:55296
	ds_read_b128 v[210:213], v186 offset:56320
	s_add_u32 s30, s58, 0x80
	s_addc_u32 s31, s59, 0
	s_mov_b32 m0, s94
	s_nop 0
	global_load_lds_dwordx4 v180, s[30:31]
	s_nop 0
	s_mov_b32 m0, s95
	s_nop 0
	global_load_lds_dwordx4 v182, s[30:31]
	s_add_u32 s30, s58, 0x40080
	s_addc_u32 s31, s59, 0
	s_mov_b32 m0, s17
	s_nop 0
	global_load_lds_dwordx4 v180, s[30:31]
	s_nop 0
	s_mov_b32 m0, s53
	s_nop 0
	global_load_lds_dwordx4 v182, s[30:31]
	s_nop 0
	s_mov_b32 m0, s96
	s_nop 0
	global_load_lds_dwordx4 v0, s[56:57]
	s_nop 0
	s_mov_b32 m0, s97
	s_nop 0
	global_load_lds_dwordx4 v181, s[56:57]
	s_waitcnt vmcnt(8)
	s_waitcnt lgkmcnt(0)
	s_barrier
	s_setprio 1
	s_waitcnt lgkmcnt(0)
	v_mfma_f32_16x16x32_bf16 v[62:65], v[74:77], v[162:165], v[62:65]
	v_mfma_f32_16x16x32_bf16 v[62:65], v[94:97], v[166:169], v[62:65]
	v_mfma_f32_16x16x32_bf16 v[58:61], v[114:117], v[162:165], v[58:61]
	v_mfma_f32_16x16x32_bf16 v[58:61], v[134:137], v[166:169], v[58:61]
	v_mfma_f32_16x16x32_bf16 v[54:57], v[146:149], v[162:165], v[54:57]
	v_mfma_f32_16x16x32_bf16 v[54:57], v[150:153], v[166:169], v[54:57]
	v_mfma_f32_16x16x32_bf16 v[50:53], v[154:157], v[162:165], v[50:53]
	v_mfma_f32_16x16x32_bf16 v[50:53], v[158:161], v[166:169], v[50:53]
	v_mfma_f32_16x16x32_bf16 v[34:37], v[154:157], v[170:173], v[34:37]
	v_mfma_f32_16x16x32_bf16 v[34:37], v[158:161], v[174:177], v[34:37]
	v_mfma_f32_16x16x32_bf16 v[38:41], v[146:149], v[170:173], v[38:41]
	v_mfma_f32_16x16x32_bf16 v[38:41], v[150:153], v[174:177], v[38:41]
	v_mfma_f32_16x16x32_bf16 v[42:45], v[114:117], v[170:173], v[42:45]
	v_mfma_f32_16x16x32_bf16 v[42:45], v[134:137], v[174:177], v[42:45]
	v_mfma_f32_16x16x32_bf16 v[46:49], v[74:77], v[170:173], v[46:49]
	v_mfma_f32_16x16x32_bf16 v[46:49], v[94:97], v[174:177], v[46:49]
	v_mfma_f32_16x16x32_bf16 v[30:33], v[74:77], v[188:191], v[30:33]
	v_mfma_f32_16x16x32_bf16 v[30:33], v[94:97], v[202:205], v[30:33]
	v_mfma_f32_16x16x32_bf16 v[26:29], v[114:117], v[188:191], v[26:29]
	v_mfma_f32_16x16x32_bf16 v[26:29], v[134:137], v[202:205], v[26:29]
	v_mfma_f32_16x16x32_bf16 v[22:25], v[146:149], v[188:191], v[22:25]
	v_mfma_f32_16x16x32_bf16 v[22:25], v[150:153], v[202:205], v[22:25]
	v_mfma_f32_16x16x32_bf16 v[18:21], v[154:157], v[188:191], v[18:21]
	v_mfma_f32_16x16x32_bf16 v[18:21], v[158:161], v[202:205], v[18:21]
	v_mfma_f32_16x16x32_bf16 v[2:5], v[154:157], v[206:209], v[2:5]
	v_mfma_f32_16x16x32_bf16 v[2:5], v[158:161], v[210:213], v[2:5]
	v_mfma_f32_16x16x32_bf16 v[6:9], v[146:149], v[206:209], v[6:9]
	v_mfma_f32_16x16x32_bf16 v[6:9], v[150:153], v[210:213], v[6:9]
	v_mfma_f32_16x16x32_bf16 v[10:13], v[114:117], v[206:209], v[10:13]
	v_mfma_f32_16x16x32_bf16 v[10:13], v[134:137], v[210:213], v[10:13]
	v_mfma_f32_16x16x32_bf16 v[14:17], v[74:77], v[206:209], v[14:17]
	v_mfma_f32_16x16x32_bf16 v[14:17], v[94:97], v[210:213], v[14:17]
	s_setprio 0
	s_add_i32 s50, s50, 2
	s_add_u32 s41, s41, 0x100
	s_addc_u32 s49, s49, 0
	s_add_u32 s92, s92, 0x100
	s_addc_u32 s93, s93, 0
	s_cmp_gt_u32 s50, 13
	s_barrier
; #define PG8_STAGE(bufoff, gbase, voff) do { _Pragma("unroll") for (int _i = 0; _i < 2; ++_i) { \
;         const unsigned _m0 = ldsb + (unsigned)((bufoff) + _i * 8192); const char* _gb = (const char*)(gbase); \
;         asm volatile("s_mov_b32 m0, %0\n\ts_nop 0\n\tglobal_load_lds_dwordx4 %1, %2" :: "s"(_m0), "v"((voff)[_i]), "s"(_gb) : "m0", "memory"); } } while (0)
; #define PG8_LDA(dst, b, h) do { _Pragma("unroll") for (int m = 0; m < 4; ++m) _Pragma("unroll") for (int k = 0; k < 2; ++k) dst[m][k] = *(const LAS bf16x8*)(lds + PG8_SA(b, h) + aoff + m * 2048 + k * 1024); } while (0)
; #define PG8_LDB(dst, b, h) do { _Pragma("unroll") for (int n = 0; n < 2; ++n) _Pragma("unroll") for (int k = 0; k < 2; ++k) dst[n][k] = *(const LAS bf16x8*)(lds + PG8_SB(b, h) + boff + n * 2048 + k * 1024); } while (0)
; #define PG8_MMA(ai, bj, At, Bt) do { __builtin_amdgcn_s_setprio(1); _Pragma("unroll") for (int m = 0; m < 4; ++m) _Pragma("unroll") for (int n = 0; n < 2; ++n) _Pragma("unroll") for (int k = 0; k < 2; ++k) \
;         acc[ai][bj][m][n] = __builtin_amdgcn_mfma_f32_16x16x32_bf16(Bt[n][k], At[m][k], acc[ai][bj][m][n], 0, 0, 0); __builtin_amdgcn_s_setprio(0); } while (0)
; #define PG8_WAIT_V(n) asm volatile("s_waitcnt vmcnt(" #n ")" ::: "memory")
; #define PG8_WAIT_L(n) asm volatile("s_waitcnt lgkmcnt(" #n ")" ::: "memory")
; template <class Epi, bool ALIGN_EPI>
; __device__ __forceinline__ void gemm_phase(LAS unsigned char* lds, const Gemm g, const StaticOrder& S, const Epi& E) {
;     ...
;         for (int t = 0; t < nt; t += 2) {
;             const bool last = (t == nt - 2);
;             const char* a1 = cA + (size_t)(t + 1) * kstep;
;             const char* a2 = last ? nA : cA + (size_t)(t + 2) * kstep; const char* b2 = last ? nB : cB + (size_t)(t + 2) * kstep;
;             const char* a3 = a2 + kstep; const char* b3 = b2 + kstep;
;             PG8_LDB(B0, 0, 0); PG8_LDB(B1, 0, 1); PG8_SCHED; PG8_LDA(At, 0, 0); PG8_STAGE(PG8_SA(1, 1), a1 + hstepA, voffA);
;             PG8_WAIT_V(8); PG8_WAIT_L(0); PG8_BAR; PG8_MMA(0, 0, At, B0); PG8_MMA(0, 1, At, B1); PG8_BAR; PG8_SCHED;
;             PG8_LDA(At, 0, 1); PG8_STAGE(PG8_SB(0, 0), b2, voffB); PG8_STAGE(PG8_SB(0, 1), b2 + hstepB, voffB); PG8_STAGE(PG8_SA(0, 0), a2, voffA);
;             PG8_WAIT_V(8); PG8_WAIT_L(0); PG8_BAR; PG8_MMA(1, 0, At, B0); PG8_MMA(1, 1, At, B1); PG8_BAR; PG8_SCHED;
.LBB0_306:
	v_add_u32_e32 v134, 0x10000, v185
	v_add_u32_e32 v158, 0x14000, v185
	ds_read_b128 v[74:77], v134
	ds_read_b128 v[94:97], v134 offset:1024
	ds_read_b128 v[114:117], v134 offset:2048
	ds_read_b128 v[134:137], v134 offset:3072
	ds_read_b128 v[146:149], v158
	ds_read_b128 v[150:153], v158 offset:1024
	ds_read_b128 v[154:157], v158 offset:2048
	ds_read_b128 v[158:161], v158 offset:3072
	s_add_u32 s30, s92, 0xfffc0080
	s_addc_u32 s31, s93, -1
	s_cmp_eq_u32 s50, 12
	s_cselect_b32 s60, s5, s30
	s_cselect_b32 s61, s4, s31
	s_cselect_b32 s58, s37, s41
	s_cselect_b32 s59, s35, s49
	s_add_u32 s56, s60, 0x80
	s_addc_u32 s57, s61, 0
	ds_read_b128 v[162:165], v186
	ds_read_b128 v[166:169], v186 offset:1024
	ds_read_b128 v[170:173], v186 offset:2048
	ds_read_b128 v[174:177], v186 offset:3072
	ds_read_b128 v[188:191], v186 offset:4096
	ds_read_b128 v[202:205], v186 offset:5120
	ds_read_b128 v[206:209], v186 offset:6144
	ds_read_b128 v[210:213], v186 offset:7168
	s_mov_b32 m0, s67
	s_nop 0
	global_load_lds_dwordx4 v0, s[92:93]
	s_nop 0
	s_mov_b32 m0, s65
	s_nop 0
	global_load_lds_dwordx4 v181, s[92:93]
	s_waitcnt vmcnt(8)
	s_waitcnt lgkmcnt(0)
	s_barrier
	s_setprio 1
	s_waitcnt lgkmcnt(0)
	v_mfma_f32_16x16x32_bf16 v[142:145], v[74:77], v[162:165], v[142:145]
	v_mfma_f32_16x16x32_bf16 v[142:145], v[94:97], v[166:169], v[142:145]
	v_mfma_f32_16x16x32_bf16 v[138:141], v[114:117], v[162:165], v[138:141]
	v_mfma_f32_16x16x32_bf16 v[138:141], v[134:137], v[166:169], v[138:141]
	v_mfma_f32_16x16x32_bf16 v[130:133], v[146:149], v[162:165], v[130:133]
	v_mfma_f32_16x16x32_bf16 v[130:133], v[150:153], v[166:169], v[130:133]
	v_mfma_f32_16x16x32_bf16 v[126:129], v[154:157], v[162:165], v[126:129]
	v_mfma_f32_16x16x32_bf16 v[126:129], v[158:161], v[166:169], v[126:129]
	v_mfma_f32_16x16x32_bf16 v[106:109], v[154:157], v[170:173], v[106:109]
	v_mfma_f32_16x16x32_bf16 v[106:109], v[158:161], v[174:177], v[106:109]
	v_mfma_f32_16x16x32_bf16 v[110:113], v[146:149], v[170:173], v[110:113]
	v_mfma_f32_16x16x32_bf16 v[110:113], v[150:153], v[174:177], v[110:113]
	v_mfma_f32_16x16x32_bf16 v[118:121], v[114:117], v[170:173], v[118:121]
	v_mfma_f32_16x16x32_bf16 v[118:121], v[134:137], v[174:177], v[118:121]
	v_mfma_f32_16x16x32_bf16 v[122:125], v[74:77], v[170:173], v[122:125]
	v_mfma_f32_16x16x32_bf16 v[122:125], v[94:97], v[174:177], v[122:125]
	v_mfma_f32_16x16x32_bf16 v[102:105], v[74:77], v[188:191], v[102:105]
	v_mfma_f32_16x16x32_bf16 v[102:105], v[94:97], v[202:205], v[102:105]
	v_mfma_f32_16x16x32_bf16 v[98:101], v[114:117], v[188:191], v[98:101]
	v_mfma_f32_16x16x32_bf16 v[98:101], v[134:137], v[202:205], v[98:101]
	v_mfma_f32_16x16x32_bf16 v[90:93], v[146:149], v[188:191], v[90:93]
	v_mfma_f32_16x16x32_bf16 v[90:93], v[150:153], v[202:205], v[90:93]
	v_mfma_f32_16x16x32_bf16 v[86:89], v[154:157], v[188:191], v[86:89]
	v_mfma_f32_16x16x32_bf16 v[86:89], v[158:161], v[202:205], v[86:89]
	v_mfma_f32_16x16x32_bf16 v[66:69], v[154:157], v[206:209], v[66:69]
	v_mfma_f32_16x16x32_bf16 v[66:69], v[158:161], v[210:213], v[66:69]
	v_mfma_f32_16x16x32_bf16 v[70:73], v[146:149], v[206:209], v[70:73]
	v_mfma_f32_16x16x32_bf16 v[70:73], v[150:153], v[210:213], v[70:73]
	v_mfma_f32_16x16x32_bf16 v[78:81], v[114:117], v[206:209], v[78:81]
	v_mfma_f32_16x16x32_bf16 v[78:81], v[134:137], v[210:213], v[78:81]
	v_mfma_f32_16x16x32_bf16 v[82:85], v[74:77], v[206:209], v[82:85]
	v_mfma_f32_16x16x32_bf16 v[82:85], v[94:97], v[210:213], v[82:85]
	s_setprio 0
	s_barrier
	ds_read_b128 v[162:165], v186 offset:16384
	ds_read_b128 v[166:169], v186 offset:17408
	ds_read_b128 v[170:173], v186 offset:18432
	ds_read_b128 v[174:177], v186 offset:19456
	ds_read_b128 v[188:191], v186 offset:20480
	ds_read_b128 v[202:205], v186 offset:21504
	ds_read_b128 v[206:209], v186 offset:22528
	ds_read_b128 v[210:213], v186 offset:23552
	s_mov_b32 m0, s29
	s_nop 0
	global_load_lds_dwordx4 v180, s[58:59]
	s_add_u32 s30, s58, 0x40000
	s_mov_b32 m0, s42
	s_nop 0
	global_load_lds_dwordx4 v182, s[58:59]
	s_addc_u32 s31, s59, 0
	s_mov_b32 m0, s43
	s_nop 0
	global_load_lds_dwordx4 v180, s[30:31]
	s_nop 0
	s_mov_b32 m0, s44
	s_nop 0
	global_load_lds_dwordx4 v182, s[30:31]
	s_nop 0
	s_mov_b32 m0, s15
	s_nop 0
	global_load_lds_dwordx4 v0, s[60:61]
	s_nop 0
	s_mov_b32 m0, s45
	s_nop 0
	global_load_lds_dwordx4 v181, s[60:61]
	s_waitcnt vmcnt(8)
	s_waitcnt lgkmcnt(0)
	s_barrier
	s_setprio 1
	s_waitcnt lgkmcnt(0)
	v_mfma_f32_16x16x32_bf16 v[62:65], v[74:77], v[162:165], v[62:65]
	v_mfma_f32_16x16x32_bf16 v[62:65], v[94:97], v[166:169], v[62:65]
	v_mfma_f32_16x16x32_bf16 v[58:61], v[114:117], v[162:165], v[58:61]
	v_mfma_f32_16x16x32_bf16 v[58:61], v[134:137], v[166:169], v[58:61]
	v_mfma_f32_16x16x32_bf16 v[54:57], v[146:149], v[162:165], v[54:57]
	v_mfma_f32_16x16x32_bf16 v[54:57], v[150:153], v[166:169], v[54:57]
	v_mfma_f32_16x16x32_bf16 v[50:53], v[154:157], v[162:165], v[50:53]
	v_mfma_f32_16x16x32_bf16 v[50:53], v[158:161], v[166:169], v[50:53]
	v_mfma_f32_16x16x32_bf16 v[34:37], v[154:157], v[170:173], v[34:37]
	v_mfma_f32_16x16x32_bf16 v[34:37], v[158:161], v[174:177], v[34:37]
	v_mfma_f32_16x16x32_bf16 v[38:41], v[146:149], v[170:173], v[38:41]
	v_mfma_f32_16x16x32_bf16 v[38:41], v[150:153], v[174:177], v[38:41]
	v_mfma_f32_16x16x32_bf16 v[42:45], v[114:117], v[170:173], v[42:45]
	v_mfma_f32_16x16x32_bf16 v[42:45], v[134:137], v[174:177], v[42:45]
	v_mfma_f32_16x16x32_bf16 v[46:49], v[74:77], v[170:173], v[46:49]
	v_mfma_f32_16x16x32_bf16 v[46:49], v[94:97], v[174:177], v[46:49]
	v_mfma_f32_16x16x32_bf16 v[30:33], v[74:77], v[188:191], v[30:33]
	v_mfma_f32_16x16x32_bf16 v[30:33], v[94:97], v[202:205], v[30:33]
	v_mfma_f32_16x16x32_bf16 v[26:29], v[114:117], v[188:191], v[26:29]
	v_mfma_f32_16x16x32_bf16 v[26:29], v[134:137], v[202:205], v[26:29]
	v_mfma_f32_16x16x32_bf16 v[22:25], v[146:149], v[188:191], v[22:25]
	v_mfma_f32_16x16x32_bf16 v[22:25], v[150:153], v[202:205], v[22:25]
	v_mfma_f32_16x16x32_bf16 v[18:21], v[154:157], v[188:191], v[18:21]
	v_mfma_f32_16x16x32_bf16 v[18:21], v[158:161], v[202:205], v[18:21]
	v_mfma_f32_16x16x32_bf16 v[2:5], v[154:157], v[206:209], v[2:5]
	v_mfma_f32_16x16x32_bf16 v[2:5], v[158:161], v[210:213], v[2:5]
	v_mfma_f32_16x16x32_bf16 v[6:9], v[146:149], v[206:209], v[6:9]
	v_mfma_f32_16x16x32_bf16 v[6:9], v[150:153], v[210:213], v[6:9]
	v_mfma_f32_16x16x32_bf16 v[10:13], v[114:117], v[206:209], v[10:13]
	v_mfma_f32_16x16x32_bf16 v[10:13], v[134:137], v[210:213], v[10:13]
	v_mfma_f32_16x16x32_bf16 v[14:17], v[74:77], v[206:209], v[14:17]
	v_mfma_f32_16x16x32_bf16 v[14:17], v[94:97], v[210:213], v[14:17]
	s_setprio 0
	s_barrier
; #define PG8_STAGE(bufoff, gbase, voff) do { _Pragma("unroll") for (int _i = 0; _i < 2; ++_i) { \
;         const unsigned _m0 = ldsb + (unsigned)((bufoff) + _i * 8192); const char* _gb = (const char*)(gbase); \
;         asm volatile("s_mov_b32 m0, %0\n\ts_nop 0\n\tglobal_load_lds_dwordx4 %1, %2" :: "s"(_m0), "v"((voff)[_i]), "s"(_gb) : "m0", "memory"); } } while (0)
; #define PG8_LDA(dst, b, h) do { _Pragma("unroll") for (int m = 0; m < 4; ++m) _Pragma("unroll") for (int k = 0; k < 2; ++k) dst[m][k] = *(const LAS bf16x8*)(lds + PG8_SA(b, h) + aoff + m * 2048 + k * 1024); } while (0)
; #define PG8_LDB(dst, b, h) do { _Pragma("unroll") for (int n = 0; n < 2; ++n) _Pragma("unroll") for (int k = 0; k < 2; ++k) dst[n][k] = *(const LAS bf16x8*)(lds + PG8_SB(b, h) + boff + n * 2048 + k * 1024); } while (0)
; #define PG8_MMA(ai, bj, At, Bt) do { __builtin_amdgcn_s_setprio(1); _Pragma("unroll") for (int m = 0; m < 4; ++m) _Pragma("unroll") for (int n = 0; n < 2; ++n) _Pragma("unroll") for (int k = 0; k < 2; ++k) \
;         acc[ai][bj][m][n] = __builtin_amdgcn_mfma_f32_16x16x32_bf16(Bt[n][k], At[m][k], acc[ai][bj][m][n], 0, 0, 0); __builtin_amdgcn_s_setprio(0); } while (0)
; #define PG8_WAIT_V(n) asm volatile("s_waitcnt vmcnt(" #n ")" ::: "memory")
; #define PG8_WAIT_L(n) asm volatile("s_waitcnt lgkmcnt(" #n ")" ::: "memory")
; #define PG8_BAR __builtin_amdgcn_s_barrier()
; #define PG8_SCHED __builtin_amdgcn_sched_barrier(0)
; template <class Epi, bool ALIGN_EPI>
; __device__ __forceinline__ void gemm_phase(LAS unsigned char* lds, const Gemm g, const StaticOrder& S, const Epi& E) {
;     ...
;             PG8_LDB(B0, 1, 0); PG8_LDB(B1, 1, 1); PG8_SCHED; PG8_LDA(At, 1, 0); PG8_STAGE(PG8_SA(0, 1), a2 + hstepA, voffA);
;             PG8_WAIT_V(8); PG8_WAIT_L(0); PG8_BAR; PG8_MMA(0, 0, At, B0); PG8_MMA(0, 1, At, B1); PG8_BAR; PG8_SCHED;
;             PG8_LDA(At, 1, 1); PG8_STAGE(PG8_SB(1, 0), b3, voffB); PG8_STAGE(PG8_SB(1, 1), b3 + hstepB, voffB); PG8_STAGE(PG8_SA(1, 0), a3, voffA);
;             PG8_WAIT_V(8); PG8_WAIT_L(0); PG8_BAR; PG8_MMA(1, 0, At, B0); PG8_MMA(1, 1, At, B1); PG8_BAR; PG8_SCHED;
;         }
;         if constexpr (ALIGN_EPI) { if (wr == 0) PG8_BAR; }
	v_add_u32_e32 v134, 0x18000, v185
	v_add_u32_e32 v158, 0x1c000, v185
	ds_read_b128 v[74:77], v134
	ds_read_b128 v[94:97], v134 offset:1024
	ds_read_b128 v[114:117], v134 offset:2048
	ds_read_b128 v[134:137], v134 offset:3072
	ds_read_b128 v[146:149], v158
	ds_read_b128 v[150:153], v158 offset:1024
	ds_read_b128 v[154:157], v158 offset:2048
	ds_read_b128 v[158:161], v158 offset:3072
	ds_read_b128 v[162:165], v186 offset:32768
	ds_read_b128 v[166:169], v186 offset:33792
	ds_read_b128 v[170:173], v186 offset:34816
	ds_read_b128 v[174:177], v186 offset:35840
	ds_read_b128 v[188:191], v186 offset:36864
	ds_read_b128 v[202:205], v186 offset:37888
	ds_read_b128 v[206:209], v186 offset:38912
	ds_read_b128 v[210:213], v186 offset:39936
	s_add_u32 s30, s60, 0x40000
	s_addc_u32 s31, s61, 0
	s_mov_b32 m0, s55
	s_nop 0
	global_load_lds_dwordx4 v0, s[30:31]
	s_nop 0
	s_mov_b32 m0, s88
	s_nop 0
	global_load_lds_dwordx4 v181, s[30:31]
	s_waitcnt vmcnt(8)
	s_waitcnt lgkmcnt(0)
	s_barrier
	s_setprio 1
	s_waitcnt lgkmcnt(0)
	v_mfma_f32_16x16x32_bf16 v[142:145], v[74:77], v[162:165], v[142:145]
	v_mfma_f32_16x16x32_bf16 v[142:145], v[94:97], v[166:169], v[142:145]
	v_mfma_f32_16x16x32_bf16 v[138:141], v[114:117], v[162:165], v[138:141]
	v_mfma_f32_16x16x32_bf16 v[138:141], v[134:137], v[166:169], v[138:141]
	v_mfma_f32_16x16x32_bf16 v[130:133], v[146:149], v[162:165], v[130:133]
	v_mfma_f32_16x16x32_bf16 v[130:133], v[150:153], v[166:169], v[130:133]
	v_mfma_f32_16x16x32_bf16 v[126:129], v[154:157], v[162:165], v[126:129]
	v_mfma_f32_16x16x32_bf16 v[126:129], v[158:161], v[166:169], v[126:129]
	v_mfma_f32_16x16x32_bf16 v[106:109], v[154:157], v[170:173], v[106:109]
	v_mfma_f32_16x16x32_bf16 v[106:109], v[158:161], v[174:177], v[106:109]
	v_mfma_f32_16x16x32_bf16 v[110:113], v[146:149], v[170:173], v[110:113]
	v_mfma_f32_16x16x32_bf16 v[110:113], v[150:153], v[174:177], v[110:113]
	v_mfma_f32_16x16x32_bf16 v[118:121], v[114:117], v[170:173], v[118:121]
	v_mfma_f32_16x16x32_bf16 v[118:121], v[134:137], v[174:177], v[118:121]
	v_mfma_f32_16x16x32_bf16 v[122:125], v[74:77], v[170:173], v[122:125]
	v_mfma_f32_16x16x32_bf16 v[122:125], v[94:97], v[174:177], v[122:125]
	v_mfma_f32_16x16x32_bf16 v[102:105], v[74:77], v[188:191], v[102:105]
	v_mfma_f32_16x16x32_bf16 v[102:105], v[94:97], v[202:205], v[102:105]
	v_mfma_f32_16x16x32_bf16 v[98:101], v[114:117], v[188:191], v[98:101]
	v_mfma_f32_16x16x32_bf16 v[98:101], v[134:137], v[202:205], v[98:101]
	v_mfma_f32_16x16x32_bf16 v[90:93], v[146:149], v[188:191], v[90:93]
	v_mfma_f32_16x16x32_bf16 v[90:93], v[150:153], v[202:205], v[90:93]
	v_mfma_f32_16x16x32_bf16 v[86:89], v[154:157], v[188:191], v[86:89]
	v_mfma_f32_16x16x32_bf16 v[86:89], v[158:161], v[202:205], v[86:89]
	v_mfma_f32_16x16x32_bf16 v[66:69], v[154:157], v[206:209], v[66:69]
	v_mfma_f32_16x16x32_bf16 v[66:69], v[158:161], v[210:213], v[66:69]
	v_mfma_f32_16x16x32_bf16 v[70:73], v[146:149], v[206:209], v[70:73]
	v_mfma_f32_16x16x32_bf16 v[70:73], v[150:153], v[210:213], v[70:73]
	v_mfma_f32_16x16x32_bf16 v[78:81], v[114:117], v[206:209], v[78:81]
	v_mfma_f32_16x16x32_bf16 v[78:81], v[134:137], v[210:213], v[78:81]
	v_mfma_f32_16x16x32_bf16 v[82:85], v[74:77], v[206:209], v[82:85]
	v_mfma_f32_16x16x32_bf16 v[82:85], v[94:97], v[210:213], v[82:85]
	s_setprio 0
	s_barrier
	ds_read_b128 v[162:165], v186 offset:49152
	ds_read_b128 v[166:169], v186 offset:50176
	ds_read_b128 v[170:173], v186 offset:51200
	ds_read_b128 v[174:177], v186 offset:52224
	ds_read_b128 v[188:191], v186 offset:53248
	ds_read_b128 v[202:205], v186 offset:54272
	ds_read_b128 v[206:209], v186 offset:55296
	ds_read_b128 v[210:213], v186 offset:56320
	s_add_u32 s30, s58, 0x80
	s_addc_u32 s31, s59, 0
	s_mov_b32 m0, s94
	s_nop 0
	global_load_lds_dwordx4 v180, s[30:31]
	s_nop 0
	s_mov_b32 m0, s95
	s_nop 0
	global_load_lds_dwordx4 v182, s[30:31]
	s_add_u32 s30, s58, 0x40080
	s_addc_u32 s31, s59, 0
	s_mov_b32 m0, s17
	s_nop 0
	global_load_lds_dwordx4 v180, s[30:31]
	s_nop 0
	s_mov_b32 m0, s53
	s_nop 0
	global_load_lds_dwordx4 v182, s[30:31]
	s_nop 0
	s_mov_b32 m0, s96
	s_nop 0
	global_load_lds_dwordx4 v0, s[56:57]
	s_nop 0
	s_mov_b32 m0, s97
	s_nop 0
	global_load_lds_dwordx4 v181, s[56:57]
	s_waitcnt vmcnt(8)
	s_waitcnt lgkmcnt(0)
	s_barrier
	s_setprio 1
	s_waitcnt lgkmcnt(0)
	v_mfma_f32_16x16x32_bf16 v[62:65], v[74:77], v[162:165], v[62:65]
	v_mfma_f32_16x16x32_bf16 v[62:65], v[94:97], v[166:169], v[62:65]
	v_mfma_f32_16x16x32_bf16 v[58:61], v[114:117], v[162:165], v[58:61]
	v_mfma_f32_16x16x32_bf16 v[58:61], v[134:137], v[166:169], v[58:61]
	v_mfma_f32_16x16x32_bf16 v[54:57], v[146:149], v[162:165], v[54:57]
	v_mfma_f32_16x16x32_bf16 v[54:57], v[150:153], v[166:169], v[54:57]
	v_mfma_f32_16x16x32_bf16 v[50:53], v[154:157], v[162:165], v[50:53]
	v_mfma_f32_16x16x32_bf16 v[50:53], v[158:161], v[166:169], v[50:53]
	v_mfma_f32_16x16x32_bf16 v[34:37], v[154:157], v[170:173], v[34:37]
	v_mfma_f32_16x16x32_bf16 v[34:37], v[158:161], v[174:177], v[34:37]
	v_mfma_f32_16x16x32_bf16 v[38:41], v[146:149], v[170:173], v[38:41]
	v_mfma_f32_16x16x32_bf16 v[38:41], v[150:153], v[174:177], v[38:41]
	v_mfma_f32_16x16x32_bf16 v[42:45], v[114:117], v[170:173], v[42:45]
	v_mfma_f32_16x16x32_bf16 v[42:45], v[134:137], v[174:177], v[42:45]
	v_mfma_f32_16x16x32_bf16 v[46:49], v[74:77], v[170:173], v[46:49]
	v_mfma_f32_16x16x32_bf16 v[46:49], v[94:97], v[174:177], v[46:49]
	v_mfma_f32_16x16x32_bf16 v[30:33], v[74:77], v[188:191], v[30:33]
	v_mfma_f32_16x16x32_bf16 v[30:33], v[94:97], v[202:205], v[30:33]
	v_mfma_f32_16x16x32_bf16 v[26:29], v[114:117], v[188:191], v[26:29]
	v_mfma_f32_16x16x32_bf16 v[26:29], v[134:137], v[202:205], v[26:29]
	v_mfma_f32_16x16x32_bf16 v[22:25], v[146:149], v[188:191], v[22:25]
	v_mfma_f32_16x16x32_bf16 v[22:25], v[150:153], v[202:205], v[22:25]
	v_mfma_f32_16x16x32_bf16 v[18:21], v[154:157], v[188:191], v[18:21]
	v_mfma_f32_16x16x32_bf16 v[18:21], v[158:161], v[202:205], v[18:21]
	v_mfma_f32_16x16x32_bf16 v[2:5], v[154:157], v[206:209], v[2:5]
	v_mfma_f32_16x16x32_bf16 v[2:5], v[158:161], v[210:213], v[2:5]
	v_mfma_f32_16x16x32_bf16 v[6:9], v[146:149], v[206:209], v[6:9]
	v_mfma_f32_16x16x32_bf16 v[6:9], v[150:153], v[210:213], v[6:9]
	v_mfma_f32_16x16x32_bf16 v[10:13], v[114:117], v[206:209], v[10:13]
	v_mfma_f32_16x16x32_bf16 v[10:13], v[134:137], v[210:213], v[10:13]
	v_mfma_f32_16x16x32_bf16 v[14:17], v[74:77], v[206:209], v[14:17]
	v_mfma_f32_16x16x32_bf16 v[14:17], v[94:97], v[210:213], v[14:17]
	s_setprio 0
	s_add_i32 s50, s50, 2
	s_add_u32 s41, s41, 0x100
	s_addc_u32 s49, s49, 0
	s_add_u32 s92, s92, 0x100
	s_addc_u32 s93, s93, 0
	s_cmp_gt_u32 s50, 13
	s_barrier
	s_cbranch_scc0 .LBB0_306
	v_readlane_b32 s4, v254, 46
	v_readlane_b32 s5, v254, 47
	s_and_b64 vcc, exec, s[4:5]
	s_cbranch_vccz .LBB0_309
	s_barrier

; #define PG8_STAGE(bufoff, gbase, voff) do { _Pragma("unroll") for (int _i = 0; _i < 2; ++_i) { \
;         const unsigned _m0 = ldsb + (unsigned)((bufoff) + _i * 8192); const char* _gb = (const char*)(gbase); \
;         asm volatile("s_mov_b32 m0, %0\n\ts_nop 0\n\tglobal_load_lds_dwordx4 %1, %2" :: "s"(_m0), "v"((voff)[_i]), "s"(_gb) : "m0", "memory"); } } while (0)
; #define PG8_LDA(dst, b, h) do { _Pragma("unroll") for (int m = 0; m < 4; ++m) _Pragma("unroll") for (int k = 0; k < 2; ++k) dst[m][k] = *(const LAS bf16x8*)(lds + PG8_SA(b, h) + aoff + m * 2048 + k * 1024); } while (0)
; #define PG8_LDB(dst, b, h) do { _Pragma("unroll") for (int n = 0; n < 2; ++n) _Pragma("unroll") for (int k = 0; k < 2; ++k) dst[n][k] = *(const LAS bf16x8*)(lds + PG8_SB(b, h) + boff + n * 2048 + k * 1024); } while (0)
; #define PG8_MMA(ai, bj, At, Bt) do { __builtin_amdgcn_s_setprio(1); _Pragma("unroll") for (int m = 0; m < 4; ++m) _Pragma("unroll") for (int n = 0; n < 2; ++n) _Pragma("unroll") for (int k = 0; k < 2; ++k) \
;         acc[ai][bj][m][n] = __builtin_amdgcn_mfma_f32_16x16x32_bf16(Bt[n][k], At[m][k], acc[ai][bj][m][n], 0, 0, 0); __builtin_amdgcn_s_setprio(0); } while (0)
; #define PG8_WAIT_V(n) asm volatile("s_waitcnt vmcnt(" #n ")" ::: "memory")
; #define PG8_WAIT_L(n) asm volatile("s_waitcnt lgkmcnt(" #n ")" ::: "memory")
; template <class Epi, bool ALIGN_EPI>
; __device__ __forceinline__ void gemm_phase(LAS unsigned char* lds, const Gemm g, const StaticOrder& S, const Epi& E) {
;     ...
;         for (int t = 0; t < nt; t += 2) {
;             const bool last = (t == nt - 2);
;             const char* a1 = cA + (size_t)(t + 1) * kstep;
;             const char* a2 = last ? nA : cA + (size_t)(t + 2) * kstep; const char* b2 = last ? nB : cB + (size_t)(t + 2) * kstep;
;             const char* a3 = a2 + kstep; const char* b3 = b2 + kstep;
;             PG8_LDB(B0, 0, 0); PG8_LDB(B1, 0, 1); PG8_SCHED; PG8_LDA(At, 0, 0); PG8_STAGE(PG8_SA(1, 1), a1 + hstepA, voffA);
;             PG8_WAIT_V(8); PG8_WAIT_L(0); PG8_BAR; PG8_MMA(0, 0, At, B0); PG8_MMA(0, 1, At, B1); PG8_BAR; PG8_SCHED;
;             PG8_LDA(At, 0, 1); PG8_STAGE(PG8_SB(0, 0), b2, voffB); PG8_STAGE(PG8_SB(0, 1), b2 + hstepB, voffB); PG8_STAGE(PG8_SA(0, 0), a2, voffA);
;             PG8_WAIT_V(8); PG8_WAIT_L(0); PG8_BAR; PG8_MMA(1, 0, At, B0); PG8_MMA(1, 1, At, B1); PG8_BAR; PG8_SCHED;
.LBB0_349:
	v_add_u32_e32 v0, 0x10000, v187
	ds_read_b128 v[34:37], v0
	ds_read_b128 v[54:57], v0 offset:1024
	ds_read_b128 v[74:77], v0 offset:2048
	ds_read_b128 v[94:97], v0 offset:3072
	v_add_u32_e32 v0, 0x14000, v187
	ds_read_b128 v[110:113], v0
	ds_read_b128 v[126:129], v0 offset:1024
	ds_read_b128 v[146:149], v0 offset:2048
	ds_read_b128 v[160:163], v0 offset:3072
	s_add_u32 s38, s36, 0xfffc0080
	s_addc_u32 s39, s37, -1
	s_cmp_eq_u32 s50, 12
	s_cselect_b32 s54, s5, s38
	s_cselect_b32 s55, s4, s39
	s_cselect_b32 s48, s27, s29
	s_cselect_b32 s49, s11, s41
	s_add_u32 s38, s54, 0x80
	s_addc_u32 s39, s55, 0
	ds_read_b128 v[164:167], v188
	ds_read_b128 v[168:171], v188 offset:1024
	ds_read_b128 v[172:175], v188 offset:2048
	ds_read_b128 v[176:179], v188 offset:3072
	ds_read_b128 v[190:193], v188 offset:4096
	ds_read_b128 v[202:205], v188 offset:5120
	ds_read_b128 v[206:209], v188 offset:6144
	ds_read_b128 v[210:213], v188 offset:7168
	s_mov_b32 m0, s91
	s_nop 0
	global_load_lds_dwordx4 v180, s[36:37]
	s_nop 0
	s_mov_b32 m0, s93
	s_nop 0
	global_load_lds_dwordx4 v182, s[36:37]
	s_waitcnt vmcnt(8)
	s_waitcnt lgkmcnt(0)
	s_barrier
	s_setprio 1
	s_waitcnt lgkmcnt(0)
	v_mfma_f32_16x16x32_bf16 v[154:157], v[34:37], v[164:167], v[154:157]
	v_mfma_f32_16x16x32_bf16 v[154:157], v[54:57], v[168:171], v[154:157]
	v_mfma_f32_16x16x32_bf16 v[150:153], v[74:77], v[164:167], v[150:153]
	v_mfma_f32_16x16x32_bf16 v[150:153], v[94:97], v[168:171], v[150:153]
	v_mfma_f32_16x16x32_bf16 v[142:145], v[110:113], v[164:167], v[142:145]
	v_mfma_f32_16x16x32_bf16 v[142:145], v[126:129], v[168:171], v[142:145]
	v_mfma_f32_16x16x32_bf16 v[138:141], v[146:149], v[164:167], v[138:141]
	v_mfma_f32_16x16x32_bf16 v[138:141], v[160:163], v[168:171], v[138:141]
	v_mfma_f32_16x16x32_bf16 v[118:121], v[146:149], v[172:175], v[118:121]
	v_mfma_f32_16x16x32_bf16 v[118:121], v[160:163], v[176:179], v[118:121]
	v_mfma_f32_16x16x32_bf16 v[122:125], v[110:113], v[172:175], v[122:125]
	v_mfma_f32_16x16x32_bf16 v[122:125], v[126:129], v[176:179], v[122:125]
	v_mfma_f32_16x16x32_bf16 v[130:133], v[74:77], v[172:175], v[130:133]
	v_mfma_f32_16x16x32_bf16 v[130:133], v[94:97], v[176:179], v[130:133]
	v_mfma_f32_16x16x32_bf16 v[134:137], v[34:37], v[172:175], v[134:137]
	v_mfma_f32_16x16x32_bf16 v[134:137], v[54:57], v[176:179], v[134:137]
	v_mfma_f32_16x16x32_bf16 v[114:117], v[34:37], v[190:193], v[114:117]
	v_mfma_f32_16x16x32_bf16 v[114:117], v[54:57], v[202:205], v[114:117]
	v_mfma_f32_16x16x32_bf16 v[106:109], v[74:77], v[190:193], v[106:109]
	v_mfma_f32_16x16x32_bf16 v[106:109], v[94:97], v[202:205], v[106:109]
	v_mfma_f32_16x16x32_bf16 v[102:105], v[110:113], v[190:193], v[102:105]
	v_mfma_f32_16x16x32_bf16 v[102:105], v[126:129], v[202:205], v[102:105]
	v_mfma_f32_16x16x32_bf16 v[98:101], v[146:149], v[190:193], v[98:101]
	v_mfma_f32_16x16x32_bf16 v[98:101], v[160:163], v[202:205], v[98:101]
	v_mfma_f32_16x16x32_bf16 v[78:81], v[146:149], v[206:209], v[78:81]
	v_mfma_f32_16x16x32_bf16 v[78:81], v[160:163], v[210:213], v[78:81]
	v_mfma_f32_16x16x32_bf16 v[82:85], v[110:113], v[206:209], v[82:85]
	v_mfma_f32_16x16x32_bf16 v[82:85], v[126:129], v[210:213], v[82:85]
	v_mfma_f32_16x16x32_bf16 v[86:89], v[74:77], v[206:209], v[86:89]
	v_mfma_f32_16x16x32_bf16 v[86:89], v[94:97], v[210:213], v[86:89]
	v_mfma_f32_16x16x32_bf16 v[90:93], v[34:37], v[206:209], v[90:93]
	v_mfma_f32_16x16x32_bf16 v[90:93], v[54:57], v[210:213], v[90:93]
	s_setprio 0
	s_barrier
	ds_read_b128 v[164:167], v188 offset:16384
	ds_read_b128 v[168:171], v188 offset:17408
	ds_read_b128 v[172:175], v188 offset:18432
	ds_read_b128 v[176:179], v188 offset:19456
	ds_read_b128 v[190:193], v188 offset:20480
	ds_read_b128 v[202:205], v188 offset:21504
	ds_read_b128 v[206:209], v188 offset:22528
	ds_read_b128 v[210:213], v188 offset:23552
	s_mov_b32 m0, s43
	s_nop 0
	global_load_lds_dwordx4 v181, s[48:49]
	s_add_u32 s96, s48, 0x40000
	s_mov_b32 m0, s44
	s_nop 0
	global_load_lds_dwordx4 v183, s[48:49]
	s_addc_u32 s97, s49, 0
	s_mov_b32 m0, s45
	s_nop 0
	global_load_lds_dwordx4 v181, s[96:97]
	s_nop 0
	s_mov_b32 m0, s56
	s_nop 0
	global_load_lds_dwordx4 v183, s[96:97]
	s_nop 0
	s_mov_b32 m0, s42
	s_nop 0
	global_load_lds_dwordx4 v180, s[54:55]
	s_nop 0
	s_mov_b32 m0, s57
	s_nop 0
	global_load_lds_dwordx4 v182, s[54:55]
	s_waitcnt vmcnt(8)
	s_waitcnt lgkmcnt(0)
	s_barrier
	s_setprio 1
	s_waitcnt lgkmcnt(0)
	v_mfma_f32_16x16x32_bf16 v[70:73], v[34:37], v[164:167], v[70:73]
	v_mfma_f32_16x16x32_bf16 v[66:69], v[74:77], v[164:167], v[66:69]
	v_mfma_f32_16x16x32_bf16 v[50:53], v[34:37], v[172:175], v[50:53]
	v_mfma_f32_16x16x32_bf16 v[46:49], v[74:77], v[172:175], v[46:49]
	v_mfma_f32_16x16x32_bf16 v[30:33], v[34:37], v[190:193], v[30:33]
	v_mfma_f32_16x16x32_bf16 v[26:29], v[74:77], v[190:193], v[26:29]
	v_mfma_f32_16x16x32_bf16 v[14:17], v[34:37], v[206:209], v[14:17]
	v_mfma_f32_16x16x32_bf16 v[10:13], v[74:77], v[206:209], v[10:13]
	v_mfma_f32_16x16x32_bf16 v[70:73], v[54:57], v[168:171], v[70:73]
	v_mfma_f32_16x16x32_bf16 v[66:69], v[94:97], v[168:171], v[66:69]
	v_mfma_f32_16x16x32_bf16 v[50:53], v[54:57], v[176:179], v[50:53]
	v_mfma_f32_16x16x32_bf16 v[46:49], v[94:97], v[176:179], v[46:49]
	v_mfma_f32_16x16x32_bf16 v[30:33], v[54:57], v[202:205], v[30:33]
	v_mfma_f32_16x16x32_bf16 v[26:29], v[94:97], v[202:205], v[26:29]
	v_mfma_f32_16x16x32_bf16 v[14:17], v[54:57], v[210:213], v[14:17]
	v_mfma_f32_16x16x32_bf16 v[10:13], v[94:97], v[210:213], v[10:13]
	s_setprio 0
	s_setprio 1
	v_mfma_f32_16x16x32_bf16 v[42:45], v[110:113], v[172:175], v[42:45]
	v_mfma_f32_16x16x32_bf16 v[38:41], v[146:149], v[172:175], v[38:41]
	v_mfma_f32_16x16x32_bf16 v[22:25], v[110:113], v[190:193], v[22:25]
	v_mfma_f32_16x16x32_bf16 v[18:21], v[146:149], v[190:193], v[18:21]
	v_mfma_f32_16x16x32_bf16 v[6:9], v[110:113], v[206:209], v[6:9]
	v_mfma_f32_16x16x32_bf16 v[2:5], v[146:149], v[206:209], v[2:5]
	v_mfma_f32_16x16x32_bf16 v[34:37], v[110:113], v[164:167], v[62:65]
	v_mfma_f32_16x16x32_bf16 v[54:57], v[146:149], v[164:167], v[58:61]
	v_mfma_f32_16x16x32_bf16 v[42:45], v[126:129], v[176:179], v[42:45]
	v_mfma_f32_16x16x32_bf16 v[38:41], v[160:163], v[176:179], v[38:41]
	v_mfma_f32_16x16x32_bf16 v[22:25], v[126:129], v[202:205], v[22:25]
	v_mfma_f32_16x16x32_bf16 v[18:21], v[160:163], v[202:205], v[18:21]
	v_mfma_f32_16x16x32_bf16 v[6:9], v[126:129], v[210:213], v[6:9]
	v_mfma_f32_16x16x32_bf16 v[2:5], v[160:163], v[210:213], v[2:5]
	v_mfma_f32_16x16x32_bf16 v[34:37], v[126:129], v[168:171], v[34:37]
	v_mfma_f32_16x16x32_bf16 v[54:57], v[160:163], v[168:171], v[54:57]
	s_setprio 0
	s_barrier
; #define PG8_STAGE(bufoff, gbase, voff) do { _Pragma("unroll") for (int _i = 0; _i < 2; ++_i) { \
;         const unsigned _m0 = ldsb + (unsigned)((bufoff) + _i * 8192); const char* _gb = (const char*)(gbase); \
;         asm volatile("s_mov_b32 m0, %0\n\ts_nop 0\n\tglobal_load_lds_dwordx4 %1, %2" :: "s"(_m0), "v"((voff)[_i]), "s"(_gb) : "m0", "memory"); } } while (0)
; #define PG8_LDA(dst, b, h) do { _Pragma("unroll") for (int m = 0; m < 4; ++m) _Pragma("unroll") for (int k = 0; k < 2; ++k) dst[m][k] = *(const LAS bf16x8*)(lds + PG8_SA(b, h) + aoff + m * 2048 + k * 1024); } while (0)
; #define PG8_LDB(dst, b, h) do { _Pragma("unroll") for (int n = 0; n < 2; ++n) _Pragma("unroll") for (int k = 0; k < 2; ++k) dst[n][k] = *(const LAS bf16x8*)(lds + PG8_SB(b, h) + boff + n * 2048 + k * 1024); } while (0)
; #define PG8_MMA(ai, bj, At, Bt) do { __builtin_amdgcn_s_setprio(1); _Pragma("unroll") for (int m = 0; m < 4; ++m) _Pragma("unroll") for (int n = 0; n < 2; ++n) _Pragma("unroll") for (int k = 0; k < 2; ++k) \
;         acc[ai][bj][m][n] = __builtin_amdgcn_mfma_f32_16x16x32_bf16(Bt[n][k], At[m][k], acc[ai][bj][m][n], 0, 0, 0); __builtin_amdgcn_s_setprio(0); } while (0)
; #define PG8_WAIT_V(n) asm volatile("s_waitcnt vmcnt(" #n ")" ::: "memory")
; #define PG8_WAIT_L(n) asm volatile("s_waitcnt lgkmcnt(" #n ")" ::: "memory")
; #define PG8_BAR __builtin_amdgcn_s_barrier()
; #define PG8_SCHED __builtin_amdgcn_sched_barrier(0)
; template <class Epi, bool ALIGN_EPI>
; __device__ __forceinline__ void gemm_phase(LAS unsigned char* lds, const Gemm g, const StaticOrder& S, const Epi& E) {
;     ...
;             PG8_LDB(B0, 1, 0); PG8_LDB(B1, 1, 1); PG8_SCHED; PG8_LDA(At, 1, 0); PG8_STAGE(PG8_SA(0, 1), a2 + hstepA, voffA);
;             PG8_WAIT_V(8); PG8_WAIT_L(0); PG8_BAR; PG8_MMA(0, 0, At, B0); PG8_MMA(0, 1, At, B1); PG8_BAR; PG8_SCHED;
;             PG8_LDA(At, 1, 1); PG8_STAGE(PG8_SB(1, 0), b3, voffB); PG8_STAGE(PG8_SB(1, 1), b3 + hstepB, voffB); PG8_STAGE(PG8_SA(1, 0), a3, voffA);
;             PG8_WAIT_V(8); PG8_WAIT_L(0); PG8_BAR; PG8_MMA(1, 0, At, B0); PG8_MMA(1, 1, At, B1); PG8_BAR; PG8_SCHED;
;         }
;         if constexpr (ALIGN_EPI) { if (wr == 0) PG8_BAR; }
	v_add_u32_e32 v0, 0x18000, v187
	ds_read_b128 v[58:61], v0
	ds_read_b128 v[62:65], v0 offset:1024
	ds_read_b128 v[74:77], v0 offset:2048
	ds_read_b128 v[94:97], v0 offset:3072
	v_add_u32_e32 v0, 0x1c000, v187
	ds_read_b128 v[110:113], v0
	ds_read_b128 v[126:129], v0 offset:1024
	ds_read_b128 v[146:149], v0 offset:2048
	ds_read_b128 v[160:163], v0 offset:3072
	ds_read_b128 v[164:167], v188 offset:32768
	ds_read_b128 v[168:171], v188 offset:33792
	ds_read_b128 v[172:175], v188 offset:34816
	ds_read_b128 v[176:179], v188 offset:35840
	ds_read_b128 v[190:193], v188 offset:36864
	ds_read_b128 v[202:205], v188 offset:37888
	ds_read_b128 v[206:209], v188 offset:38912
	ds_read_b128 v[210:213], v188 offset:39936
	s_add_u32 s54, s54, 0x40000
	s_addc_u32 s55, s55, 0
	s_mov_b32 m0, s58
	s_nop 0
	global_load_lds_dwordx4 v180, s[54:55]
	s_nop 0
	s_mov_b32 m0, s59
	s_nop 0
	global_load_lds_dwordx4 v182, s[54:55]
	s_waitcnt vmcnt(8)
	s_waitcnt lgkmcnt(0)
	s_barrier
	s_setprio 1
	s_waitcnt lgkmcnt(0)
	v_mfma_f32_16x16x32_bf16 v[154:157], v[58:61], v[164:167], v[154:157]
	v_mfma_f32_16x16x32_bf16 v[154:157], v[62:65], v[168:171], v[154:157]
	v_mfma_f32_16x16x32_bf16 v[150:153], v[74:77], v[164:167], v[150:153]
	v_mfma_f32_16x16x32_bf16 v[150:153], v[94:97], v[168:171], v[150:153]
	v_mfma_f32_16x16x32_bf16 v[142:145], v[110:113], v[164:167], v[142:145]
	v_mfma_f32_16x16x32_bf16 v[142:145], v[126:129], v[168:171], v[142:145]
	v_mfma_f32_16x16x32_bf16 v[138:141], v[146:149], v[164:167], v[138:141]
	v_mfma_f32_16x16x32_bf16 v[138:141], v[160:163], v[168:171], v[138:141]
	v_mfma_f32_16x16x32_bf16 v[118:121], v[146:149], v[172:175], v[118:121]
	v_mfma_f32_16x16x32_bf16 v[118:121], v[160:163], v[176:179], v[118:121]
	v_mfma_f32_16x16x32_bf16 v[122:125], v[110:113], v[172:175], v[122:125]
	v_mfma_f32_16x16x32_bf16 v[122:125], v[126:129], v[176:179], v[122:125]
	v_mfma_f32_16x16x32_bf16 v[130:133], v[74:77], v[172:175], v[130:133]
	v_mfma_f32_16x16x32_bf16 v[130:133], v[94:97], v[176:179], v[130:133]
	v_mfma_f32_16x16x32_bf16 v[134:137], v[58:61], v[172:175], v[134:137]
	v_mfma_f32_16x16x32_bf16 v[134:137], v[62:65], v[176:179], v[134:137]
	v_mfma_f32_16x16x32_bf16 v[114:117], v[58:61], v[190:193], v[114:117]
	v_mfma_f32_16x16x32_bf16 v[114:117], v[62:65], v[202:205], v[114:117]
	v_mfma_f32_16x16x32_bf16 v[106:109], v[74:77], v[190:193], v[106:109]
	v_mfma_f32_16x16x32_bf16 v[106:109], v[94:97], v[202:205], v[106:109]
	v_mfma_f32_16x16x32_bf16 v[102:105], v[110:113], v[190:193], v[102:105]
	v_mfma_f32_16x16x32_bf16 v[102:105], v[126:129], v[202:205], v[102:105]
	v_mfma_f32_16x16x32_bf16 v[98:101], v[146:149], v[190:193], v[98:101]
	v_mfma_f32_16x16x32_bf16 v[98:101], v[160:163], v[202:205], v[98:101]
	v_mfma_f32_16x16x32_bf16 v[78:81], v[146:149], v[206:209], v[78:81]
	v_mfma_f32_16x16x32_bf16 v[78:81], v[160:163], v[210:213], v[78:81]
	v_mfma_f32_16x16x32_bf16 v[82:85], v[110:113], v[206:209], v[82:85]
	v_mfma_f32_16x16x32_bf16 v[82:85], v[126:129], v[210:213], v[82:85]
	v_mfma_f32_16x16x32_bf16 v[86:89], v[74:77], v[206:209], v[86:89]
	v_mfma_f32_16x16x32_bf16 v[86:89], v[94:97], v[210:213], v[86:89]
	v_mfma_f32_16x16x32_bf16 v[90:93], v[58:61], v[206:209], v[90:93]
	v_mfma_f32_16x16x32_bf16 v[90:93], v[62:65], v[210:213], v[90:93]
	s_setprio 0
	s_barrier
	ds_read_b128 v[164:167], v188 offset:49152
	ds_read_b128 v[168:171], v188 offset:50176
	ds_read_b128 v[172:175], v188 offset:51200
	ds_read_b128 v[176:179], v188 offset:52224
	ds_read_b128 v[190:193], v188 offset:53248
	ds_read_b128 v[202:205], v188 offset:54272
	ds_read_b128 v[206:209], v188 offset:55296
	ds_read_b128 v[210:213], v188 offset:56320
	s_add_u32 s54, s48, 0x80
	s_addc_u32 s55, s49, 0
	s_mov_b32 m0, s17
	s_nop 0
	global_load_lds_dwordx4 v181, s[54:55]
	s_add_u32 s48, s48, 0x40080
	s_mov_b32 m0, s60
	s_nop 0
	global_load_lds_dwordx4 v183, s[54:55]
	s_addc_u32 s49, s49, 0
	s_mov_b32 m0, s89
	s_nop 0
	global_load_lds_dwordx4 v181, s[48:49]
	s_nop 0
	s_mov_b32 m0, s90
	s_nop 0
	global_load_lds_dwordx4 v183, s[48:49]
	s_nop 0
	s_mov_b32 m0, s61
	s_nop 0
	global_load_lds_dwordx4 v180, s[38:39]
	s_nop 0
	s_mov_b32 m0, s88
	s_nop 0
	global_load_lds_dwordx4 v182, s[38:39]
	s_waitcnt vmcnt(8)
	s_waitcnt lgkmcnt(0)
	s_barrier
	s_setprio 1
	s_waitcnt lgkmcnt(0)
	v_mfma_f32_16x16x32_bf16 v[70:73], v[58:61], v[164:167], v[70:73]
	v_mfma_f32_16x16x32_bf16 v[66:69], v[74:77], v[164:167], v[66:69]
	v_mfma_f32_16x16x32_bf16 v[50:53], v[58:61], v[172:175], v[50:53]
	v_mfma_f32_16x16x32_bf16 v[46:49], v[74:77], v[172:175], v[46:49]
	v_mfma_f32_16x16x32_bf16 v[30:33], v[58:61], v[190:193], v[30:33]
	v_mfma_f32_16x16x32_bf16 v[26:29], v[74:77], v[190:193], v[26:29]
	v_mfma_f32_16x16x32_bf16 v[14:17], v[58:61], v[206:209], v[14:17]
	v_mfma_f32_16x16x32_bf16 v[10:13], v[74:77], v[206:209], v[10:13]
	v_mfma_f32_16x16x32_bf16 v[70:73], v[62:65], v[168:171], v[70:73]
	v_mfma_f32_16x16x32_bf16 v[66:69], v[94:97], v[168:171], v[66:69]
	v_mfma_f32_16x16x32_bf16 v[50:53], v[62:65], v[176:179], v[50:53]
	v_mfma_f32_16x16x32_bf16 v[46:49], v[94:97], v[176:179], v[46:49]
	v_mfma_f32_16x16x32_bf16 v[30:33], v[62:65], v[202:205], v[30:33]
	v_mfma_f32_16x16x32_bf16 v[26:29], v[94:97], v[202:205], v[26:29]
	v_mfma_f32_16x16x32_bf16 v[14:17], v[62:65], v[210:213], v[14:17]
	v_mfma_f32_16x16x32_bf16 v[10:13], v[94:97], v[210:213], v[10:13]
	s_setprio 0
	s_setprio 1
	v_mfma_f32_16x16x32_bf16 v[34:37], v[110:113], v[164:167], v[34:37]
	v_mfma_f32_16x16x32_bf16 v[62:65], v[126:129], v[168:171], v[34:37]
	v_mfma_f32_16x16x32_bf16 v[34:37], v[146:149], v[164:167], v[54:57]
	v_mfma_f32_16x16x32_bf16 v[58:61], v[160:163], v[168:171], v[34:37]
	v_mfma_f32_16x16x32_bf16 v[34:37], v[110:113], v[172:175], v[42:45]
	v_mfma_f32_16x16x32_bf16 v[42:45], v[126:129], v[176:179], v[34:37]
	v_mfma_f32_16x16x32_bf16 v[34:37], v[146:149], v[172:175], v[38:41]
	v_mfma_f32_16x16x32_bf16 v[22:25], v[110:113], v[190:193], v[22:25]
	v_mfma_f32_16x16x32_bf16 v[18:21], v[146:149], v[190:193], v[18:21]
	v_mfma_f32_16x16x32_bf16 v[6:9], v[110:113], v[206:209], v[6:9]
	v_mfma_f32_16x16x32_bf16 v[2:5], v[146:149], v[206:209], v[2:5]
	v_mfma_f32_16x16x32_bf16 v[38:41], v[160:163], v[176:179], v[34:37]
	v_mfma_f32_16x16x32_bf16 v[22:25], v[126:129], v[202:205], v[22:25]
	v_mfma_f32_16x16x32_bf16 v[18:21], v[160:163], v[202:205], v[18:21]
	v_mfma_f32_16x16x32_bf16 v[6:9], v[126:129], v[210:213], v[6:9]
	v_mfma_f32_16x16x32_bf16 v[2:5], v[160:163], v[210:213], v[2:5]
	s_setprio 0
	s_add_i32 s50, s50, 2
	s_add_u32 s29, s29, 0x100
	s_addc_u32 s41, s41, 0
	s_add_u32 s36, s36, 0x100
	s_addc_u32 s37, s37, 0
	s_cmp_gt_u32 s50, 13
	s_barrier
	s_cbranch_scc0 .LBB0_349
	s_and_b64 vcc, exec, s[24:25]
	s_cbranch_vccz .LBB0_352
	s_barrier
